# GEMM K-loops: duplicate s_waitcnt lgkmcnt(0) behind the segment barriers removed (44 sites)
# baseline (speedup 1.0000x reference)
; #define PG8_STAGE(bufoff, gbase, voff) do { _Pragma("unroll") for (int _i = 0; _i < 2; ++_i) \
;         __builtin_amdgcn_global_load_lds((const unsigned*)((const char*)(gbase) + (voff)[_i]), (PG8_LAS unsigned*)(lds + (bufoff) + ldsw + _i * 8192), 16, 0, 0); } while (0)
; #define PG8_LDA(dst, b, h) do { _Pragma("unroll") for (int m = 0; m < 4; ++m) _Pragma("unroll") for (int k = 0; k < 2; ++k) dst[m][k] = *(const PG8_LAS bf16x8*)(lds + PG8_SA(b, h) + aoff + m * 2048 + k * 1024); } while (0)
; #define PG8_LDB(dst, b, h) do { _Pragma("unroll") for (int n = 0; n < 2; ++n) _Pragma("unroll") for (int k = 0; k < 2; ++k) dst[n][k] = *(const PG8_LAS bf16x8*)(lds + PG8_SB(b, h) + boff + n * 2048 + k * 1024); } while (0)
; #define PG8_MMA(ai, bj, At, Bt) do { __builtin_amdgcn_s_setprio(1); _Pragma("unroll") for (int m = 0; m < 4; ++m) _Pragma("unroll") for (int n = 0; n < 2; ++n) _Pragma("unroll") for (int k = 0; k < 2; ++k) \
;         acc[ai][bj][m][n] = __builtin_amdgcn_mfma_f32_16x16x32_bf16(Bt[n][k], At[m][k], acc[ai][bj][m][n], 0, 0, 0); __builtin_amdgcn_s_setprio(0); } while (0)
; #define PG8_WAIT_V(n) asm volatile("s_waitcnt vmcnt(" #n ")" ::: "memory")
; #define PG8_WAIT_L(n) asm volatile("s_waitcnt lgkmcnt(" #n ")" ::: "memory")
; template <class Epi, class Sched, bool ALIGN_EPI = false, bool SP2 = false>
; __device__ __forceinline__ void gemm_phase(PG8_LAS unsigned char* lds, const Gemm g, const Sched& S, const Epi& E) {
;     ...
;             const bool last = (t == nt - 2);
;             const char* a1 = cA + (size_t)(t + 1) * kstep;
;             const char* a2 = last ? nA : cA + (size_t)(t + 2) * kstep; const char* b2 = last ? nB : cB + (size_t)(t + 2) * kstep;
;             const char* a3 = a2 + kstep; const char* b3 = b2 + kstep;
;             if (last && has_next) S.a_ready(nxt);
;             if constexpr (SP2) {
;             PG8_LDB(B0, 0, 0); PG8_LDB(B1, 0, 1); PG8_SCHED; PG8_LDA(At, 0, 0); PG8_STAGE(PG8_SA(1, 1), a1 + hstepA, voffA);
;             PG8_WAIT_V(8); PG8_WAIT_L(0); PG8_BAR; PG8_MMA(0, 0, At, B0); PG8_MMA(0, 1, At, B1); PG8_BAR; PG8_SCHED;
;             PG8_LDA(At, 0, 1); PG8_STAGE(PG8_SB(0, 0), b2, voffB); PG8_STAGE(PG8_SB(0, 1), b2 + hstepB, voffB); PG8_STAGE(PG8_SA(0, 0), a2, voffA);
;             PG8_WAIT_V(8); PG8_WAIT_L(0); PG8_BAR; PG8_MMA(1, 0, At, B0); PG8_MMA(1, 1, At, B1); PG8_BAR; PG8_SCHED;
.LBB0_318:
	ds_read_b128 v[156:159], v153
	ds_read_b128 v[160:163], v153 offset:1024
	ds_read_b128 v[164:167], v153 offset:2048
	ds_read_b128 v[168:171], v153 offset:3072
	ds_read_b128 v[172:175], v154
	ds_read_b128 v[176:179], v154 offset:1024
	ds_read_b128 v[180:183], v154 offset:2048
	ds_read_b128 v[184:187], v154 offset:3072
	s_add_u32 s8, s6, 0xfffc0080
	s_addc_u32 s9, s7, -1
	s_cmp_eq_u32 s36, 12
	s_cselect_b32 s31, s1, s9
	s_cselect_b32 s30, s5, s8
	s_cselect_b32 s9, s23, s35
	s_cselect_b32 s8, s25, s34
	s_add_i32 m0, s42, 0xc000
	ds_read_b128 v[188:191], v155
	ds_read_b128 v[192:195], v155 offset:1024
	ds_read_b128 v[196:199], v155 offset:2048
	ds_read_b128 v[200:203], v155 offset:3072
	ds_read_b128 v[204:207], v155 offset:4096
	ds_read_b128 v[208:211], v155 offset:5120
	ds_read_b128 v[212:215], v155 offset:6144
	ds_read_b128 v[216:219], v155 offset:7168
	global_load_lds_dwordx4 v140, s[6:7]
	s_add_i32 m0, s42, 0xe000
	s_nop 0
	global_load_lds_dwordx4 v142, s[6:7]
	s_waitcnt vmcnt(8)
	s_waitcnt lgkmcnt(0)
	s_barrier
	v_mfma_f32_16x16x32_bf16 v[126:129], v[156:159], v[188:191], v[126:129]
	v_mfma_f32_16x16x32_bf16 v[122:125], v[164:167], v[188:191], v[122:125]
	v_mfma_f32_16x16x32_bf16 v[110:113], v[156:159], v[196:199], v[110:113]
	v_mfma_f32_16x16x32_bf16 v[106:109], v[164:167], v[196:199], v[106:109]
	v_mfma_f32_16x16x32_bf16 v[94:97], v[156:159], v[204:207], v[94:97]
	v_mfma_f32_16x16x32_bf16 v[90:93], v[164:167], v[204:207], v[90:93]
	v_mfma_f32_16x16x32_bf16 v[78:81], v[156:159], v[212:215], v[78:81]
	v_mfma_f32_16x16x32_bf16 v[74:77], v[164:167], v[212:215], v[74:77]
	v_mfma_f32_16x16x32_bf16 v[126:129], v[160:163], v[192:195], v[126:129]
	v_mfma_f32_16x16x32_bf16 v[122:125], v[168:171], v[192:195], v[122:125]
	v_mfma_f32_16x16x32_bf16 v[110:113], v[160:163], v[200:203], v[110:113]
	v_mfma_f32_16x16x32_bf16 v[106:109], v[168:171], v[200:203], v[106:109]
	v_mfma_f32_16x16x32_bf16 v[94:97], v[160:163], v[208:211], v[94:97]
	v_mfma_f32_16x16x32_bf16 v[90:93], v[168:171], v[208:211], v[90:93]
	v_mfma_f32_16x16x32_bf16 v[78:81], v[160:163], v[216:219], v[78:81]
	v_mfma_f32_16x16x32_bf16 v[74:77], v[168:171], v[216:219], v[74:77]
	v_mfma_f32_16x16x32_bf16 v[118:121], v[172:175], v[188:191], v[118:121]
	v_mfma_f32_16x16x32_bf16 v[114:117], v[180:183], v[188:191], v[114:117]
	v_mfma_f32_16x16x32_bf16 v[102:105], v[172:175], v[196:199], v[102:105]
	v_mfma_f32_16x16x32_bf16 v[98:101], v[180:183], v[196:199], v[98:101]
	v_mfma_f32_16x16x32_bf16 v[86:89], v[172:175], v[204:207], v[86:89]
	v_mfma_f32_16x16x32_bf16 v[82:85], v[180:183], v[204:207], v[82:85]
	v_mfma_f32_16x16x32_bf16 v[70:73], v[172:175], v[212:215], v[70:73]
	v_mfma_f32_16x16x32_bf16 v[66:69], v[180:183], v[212:215], v[66:69]
	v_mfma_f32_16x16x32_bf16 v[118:121], v[176:179], v[192:195], v[118:121]
	v_mfma_f32_16x16x32_bf16 v[114:117], v[184:187], v[192:195], v[114:117]
	v_mfma_f32_16x16x32_bf16 v[102:105], v[176:179], v[200:203], v[102:105]
	v_mfma_f32_16x16x32_bf16 v[98:101], v[184:187], v[200:203], v[98:101]
	v_mfma_f32_16x16x32_bf16 v[86:89], v[176:179], v[208:211], v[86:89]
	v_mfma_f32_16x16x32_bf16 v[82:85], v[184:187], v[208:211], v[82:85]
	v_mfma_f32_16x16x32_bf16 v[70:73], v[176:179], v[216:219], v[70:73]
	v_mfma_f32_16x16x32_bf16 v[66:69], v[184:187], v[216:219], v[66:69]
	s_barrier
	s_add_i32 s37, s59, s41
	s_add_u32 s98, s8, 0x80
	s_addc_u32 s99, s9, 0
	s_mov_b32 m0, s37
	ds_read_b128 v[188:191], v155 offset:16384
	ds_read_b128 v[192:195], v155 offset:17408
	ds_read_b128 v[196:199], v155 offset:18432
	ds_read_b128 v[200:203], v155 offset:19456
	ds_read_b128 v[204:207], v155 offset:20480
	ds_read_b128 v[208:211], v155 offset:21504
	ds_read_b128 v[212:215], v155 offset:22528
	ds_read_b128 v[216:219], v155 offset:23552
	global_load_lds_dwordx4 v132, s[8:9]
	s_add_i32 m0, s37, 0x2000
	s_add_u32 s72, s8, 0x40000
	s_addc_u32 s73, s9, 0
	s_add_i32 s37, s60, s41
	global_load_lds_dwordx4 v136, s[8:9]
	s_mov_b32 m0, s37
	s_nop 0
	global_load_lds_dwordx4 v132, s[72:73]
	s_add_i32 m0, s37, 0x2000
	s_nop 0
	global_load_lds_dwordx4 v136, s[72:73]
	s_add_u32 s100, s30, 0x80
	s_addc_u32 s101, s31, 0
	s_mov_b32 m0, s42
	s_nop 0
	global_load_lds_dwordx4 v130, s[30:31]
	s_mov_b32 m0, s43
	s_nop 0
	global_load_lds_dwordx4 v134, s[30:31]
	s_waitcnt vmcnt(8)
	s_waitcnt lgkmcnt(0)
	s_barrier
	v_mfma_f32_16x16x32_bf16 v[62:65], v[156:159], v[188:191], v[62:65]
	v_mfma_f32_16x16x32_bf16 v[58:61], v[164:167], v[188:191], v[58:61]
	v_mfma_f32_16x16x32_bf16 v[46:49], v[156:159], v[196:199], v[46:49]
	v_mfma_f32_16x16x32_bf16 v[42:45], v[164:167], v[196:199], v[42:45]
	v_mfma_f32_16x16x32_bf16 v[30:33], v[156:159], v[204:207], v[30:33]
	v_mfma_f32_16x16x32_bf16 v[26:29], v[164:167], v[204:207], v[26:29]
	v_mfma_f32_16x16x32_bf16 v[14:17], v[156:159], v[212:215], v[14:17]
	v_mfma_f32_16x16x32_bf16 v[10:13], v[164:167], v[212:215], v[10:13]
	v_mfma_f32_16x16x32_bf16 v[62:65], v[160:163], v[192:195], v[62:65]
	v_mfma_f32_16x16x32_bf16 v[58:61], v[168:171], v[192:195], v[58:61]
	v_mfma_f32_16x16x32_bf16 v[46:49], v[160:163], v[200:203], v[46:49]
	v_mfma_f32_16x16x32_bf16 v[42:45], v[168:171], v[200:203], v[42:45]
	v_mfma_f32_16x16x32_bf16 v[30:33], v[160:163], v[208:211], v[30:33]
	v_mfma_f32_16x16x32_bf16 v[26:29], v[168:171], v[208:211], v[26:29]
	v_mfma_f32_16x16x32_bf16 v[14:17], v[160:163], v[216:219], v[14:17]
	v_mfma_f32_16x16x32_bf16 v[10:13], v[168:171], v[216:219], v[10:13]
	v_mfma_f32_16x16x32_bf16 v[54:57], v[172:175], v[188:191], v[54:57]
	v_mfma_f32_16x16x32_bf16 v[50:53], v[180:183], v[188:191], v[50:53]
	v_mfma_f32_16x16x32_bf16 v[38:41], v[172:175], v[196:199], v[38:41]
	v_mfma_f32_16x16x32_bf16 v[34:37], v[180:183], v[196:199], v[34:37]
	v_mfma_f32_16x16x32_bf16 v[22:25], v[172:175], v[204:207], v[22:25]
	v_mfma_f32_16x16x32_bf16 v[18:21], v[180:183], v[204:207], v[18:21]
	v_mfma_f32_16x16x32_bf16 v[6:9], v[172:175], v[212:215], v[6:9]
	v_mfma_f32_16x16x32_bf16 v[2:5], v[180:183], v[212:215], v[2:5]
	v_mfma_f32_16x16x32_bf16 v[54:57], v[176:179], v[192:195], v[54:57]
	v_mfma_f32_16x16x32_bf16 v[50:53], v[184:187], v[192:195], v[50:53]
	v_mfma_f32_16x16x32_bf16 v[38:41], v[176:179], v[200:203], v[38:41]
	v_mfma_f32_16x16x32_bf16 v[34:37], v[184:187], v[200:203], v[34:37]
	v_mfma_f32_16x16x32_bf16 v[22:25], v[176:179], v[208:211], v[22:25]
	v_mfma_f32_16x16x32_bf16 v[18:21], v[184:187], v[208:211], v[18:21]
	v_mfma_f32_16x16x32_bf16 v[6:9], v[176:179], v[216:219], v[6:9]
	v_mfma_f32_16x16x32_bf16 v[2:5], v[184:187], v[216:219], v[2:5]
	s_barrier
; #define PG8_STAGE(bufoff, gbase, voff) do { _Pragma("unroll") for (int _i = 0; _i < 2; ++_i) \
;         __builtin_amdgcn_global_load_lds((const unsigned*)((const char*)(gbase) + (voff)[_i]), (PG8_LAS unsigned*)(lds + (bufoff) + ldsw + _i * 8192), 16, 0, 0); } while (0)
; #define PG8_LDA(dst, b, h) do { _Pragma("unroll") for (int m = 0; m < 4; ++m) _Pragma("unroll") for (int k = 0; k < 2; ++k) dst[m][k] = *(const PG8_LAS bf16x8*)(lds + PG8_SA(b, h) + aoff + m * 2048 + k * 1024); } while (0)
; #define PG8_LDB(dst, b, h) do { _Pragma("unroll") for (int n = 0; n < 2; ++n) _Pragma("unroll") for (int k = 0; k < 2; ++k) dst[n][k] = *(const PG8_LAS bf16x8*)(lds + PG8_SB(b, h) + boff + n * 2048 + k * 1024); } while (0)
; #define PG8_MMA(ai, bj, At, Bt) do { __builtin_amdgcn_s_setprio(1); _Pragma("unroll") for (int m = 0; m < 4; ++m) _Pragma("unroll") for (int n = 0; n < 2; ++n) _Pragma("unroll") for (int k = 0; k < 2; ++k) \
;         acc[ai][bj][m][n] = __builtin_amdgcn_mfma_f32_16x16x32_bf16(Bt[n][k], At[m][k], acc[ai][bj][m][n], 0, 0, 0); __builtin_amdgcn_s_setprio(0); } while (0)
; #define PG8_WAIT_V(n) asm volatile("s_waitcnt vmcnt(" #n ")" ::: "memory")
; #define PG8_WAIT_L(n) asm volatile("s_waitcnt lgkmcnt(" #n ")" ::: "memory")
; #define PG8_BAR __builtin_amdgcn_s_barrier()
; #define PG8_SCHED __builtin_amdgcn_sched_barrier(0)
; template <class Epi, class Sched, bool ALIGN_EPI = false, bool SP2 = false>
; __device__ __forceinline__ void gemm_phase(PG8_LAS unsigned char* lds, const Gemm g, const Sched& S, const Epi& E) {
;     ...
;             PG8_LDB(B0, 1, 0); PG8_LDB(B1, 1, 1); PG8_SCHED; PG8_LDA(At, 1, 0); PG8_STAGE(PG8_SA(0, 1), a2 + hstepA, voffA);
;             PG8_WAIT_V(8); PG8_WAIT_L(0); PG8_BAR; PG8_MMA(0, 0, At, B0); PG8_MMA(0, 1, At, B1); PG8_BAR; PG8_SCHED;
;             PG8_LDA(At, 1, 1); PG8_STAGE(PG8_SB(1, 0), b3, voffB); PG8_STAGE(PG8_SB(1, 1), b3 + hstepB, voffB); PG8_STAGE(PG8_SA(1, 0), a3, voffA);
;             PG8_WAIT_V(8); PG8_WAIT_L(0); PG8_BAR; PG8_MMA(1, 0, At, B0); PG8_MMA(1, 1, At, B1); PG8_BAR; PG8_SCHED;
	s_add_i32 s37, 0, 0x18000
	v_add_u32_e32 v138, s37, v152
	s_add_i32 s71, 0, 0x1c000
	ds_read_b128 v[156:159], v138
	ds_read_b128 v[160:163], v138 offset:1024
	ds_read_b128 v[164:167], v138 offset:2048
	ds_read_b128 v[168:171], v138 offset:3072
	v_add_u32_e32 v138, s71, v152
	ds_read_b128 v[172:175], v138
	ds_read_b128 v[176:179], v138 offset:1024
	ds_read_b128 v[180:183], v138 offset:2048
	ds_read_b128 v[184:187], v138 offset:3072
	s_add_u32 s30, s30, 0x40000
	s_addc_u32 s31, s31, 0
	s_mov_b32 m0, s44
	ds_read_b128 v[188:191], v155 offset:32768
	ds_read_b128 v[192:195], v155 offset:33792
	ds_read_b128 v[196:199], v155 offset:34816
	ds_read_b128 v[200:203], v155 offset:35840
	ds_read_b128 v[204:207], v155 offset:36864
	ds_read_b128 v[208:211], v155 offset:37888
	ds_read_b128 v[212:215], v155 offset:38912
	ds_read_b128 v[216:219], v155 offset:39936
	global_load_lds_dwordx4 v130, s[30:31]
	s_mov_b32 m0, s45
	s_nop 0
	global_load_lds_dwordx4 v134, s[30:31]
	s_waitcnt vmcnt(8)
	s_waitcnt lgkmcnt(0)
	s_barrier
	v_mfma_f32_16x16x32_bf16 v[126:129], v[156:159], v[188:191], v[126:129]
	v_mfma_f32_16x16x32_bf16 v[122:125], v[164:167], v[188:191], v[122:125]
	v_mfma_f32_16x16x32_bf16 v[110:113], v[156:159], v[196:199], v[110:113]
	v_mfma_f32_16x16x32_bf16 v[106:109], v[164:167], v[196:199], v[106:109]
	v_mfma_f32_16x16x32_bf16 v[94:97], v[156:159], v[204:207], v[94:97]
	v_mfma_f32_16x16x32_bf16 v[90:93], v[164:167], v[204:207], v[90:93]
	v_mfma_f32_16x16x32_bf16 v[78:81], v[156:159], v[212:215], v[78:81]
	v_mfma_f32_16x16x32_bf16 v[74:77], v[164:167], v[212:215], v[74:77]
	v_mfma_f32_16x16x32_bf16 v[126:129], v[160:163], v[192:195], v[126:129]
	v_mfma_f32_16x16x32_bf16 v[122:125], v[168:171], v[192:195], v[122:125]
	v_mfma_f32_16x16x32_bf16 v[110:113], v[160:163], v[200:203], v[110:113]
	v_mfma_f32_16x16x32_bf16 v[106:109], v[168:171], v[200:203], v[106:109]
	v_mfma_f32_16x16x32_bf16 v[94:97], v[160:163], v[208:211], v[94:97]
	v_mfma_f32_16x16x32_bf16 v[90:93], v[168:171], v[208:211], v[90:93]
	v_mfma_f32_16x16x32_bf16 v[78:81], v[160:163], v[216:219], v[78:81]
	v_mfma_f32_16x16x32_bf16 v[74:77], v[168:171], v[216:219], v[74:77]
	v_mfma_f32_16x16x32_bf16 v[118:121], v[172:175], v[188:191], v[118:121]
	v_mfma_f32_16x16x32_bf16 v[114:117], v[180:183], v[188:191], v[114:117]
	v_mfma_f32_16x16x32_bf16 v[102:105], v[172:175], v[196:199], v[102:105]
	v_mfma_f32_16x16x32_bf16 v[98:101], v[180:183], v[196:199], v[98:101]
	v_mfma_f32_16x16x32_bf16 v[86:89], v[172:175], v[204:207], v[86:89]
	v_mfma_f32_16x16x32_bf16 v[82:85], v[180:183], v[204:207], v[82:85]
	v_mfma_f32_16x16x32_bf16 v[70:73], v[172:175], v[212:215], v[70:73]
	v_mfma_f32_16x16x32_bf16 v[66:69], v[180:183], v[212:215], v[66:69]
	v_mfma_f32_16x16x32_bf16 v[118:121], v[176:179], v[192:195], v[118:121]
	v_mfma_f32_16x16x32_bf16 v[114:117], v[184:187], v[192:195], v[114:117]
	v_mfma_f32_16x16x32_bf16 v[102:105], v[176:179], v[200:203], v[102:105]
	v_mfma_f32_16x16x32_bf16 v[98:101], v[184:187], v[200:203], v[98:101]
	v_mfma_f32_16x16x32_bf16 v[86:89], v[176:179], v[208:211], v[86:89]
	v_mfma_f32_16x16x32_bf16 v[82:85], v[184:187], v[208:211], v[82:85]
	v_mfma_f32_16x16x32_bf16 v[70:73], v[176:179], v[216:219], v[70:73]
	v_mfma_f32_16x16x32_bf16 v[66:69], v[184:187], v[216:219], v[66:69]
	s_barrier
	s_add_i32 s30, s37, s41
	s_mov_b32 m0, s30
	ds_read_b128 v[188:191], v155 offset:49152
	ds_read_b128 v[192:195], v155 offset:50176
	ds_read_b128 v[196:199], v155 offset:51200
	ds_read_b128 v[200:203], v155 offset:52224
	ds_read_b128 v[204:207], v155 offset:53248
	ds_read_b128 v[208:211], v155 offset:54272
	ds_read_b128 v[212:215], v155 offset:55296
	ds_read_b128 v[216:219], v155 offset:56320
	global_load_lds_dwordx4 v132, s[98:99]
	s_add_i32 m0, s30, 0x2000
	s_add_u32 s8, s8, 0x40080
	s_addc_u32 s9, s9, 0
	s_add_i32 s30, s71, s41
	global_load_lds_dwordx4 v136, s[98:99]
	s_mov_b32 m0, s30
	s_nop 0
	global_load_lds_dwordx4 v132, s[8:9]
	s_add_i32 m0, s30, 0x2000
	s_nop 0
	global_load_lds_dwordx4 v136, s[8:9]
	s_mov_b32 m0, s54
	s_nop 0
	global_load_lds_dwordx4 v130, s[100:101]
	s_mov_b32 m0, s55
	s_nop 0
	global_load_lds_dwordx4 v134, s[100:101]
	s_waitcnt vmcnt(8)
	s_waitcnt lgkmcnt(0)
	s_barrier
	v_mfma_f32_16x16x32_bf16 v[62:65], v[156:159], v[188:191], v[62:65]
	v_mfma_f32_16x16x32_bf16 v[58:61], v[164:167], v[188:191], v[58:61]
	v_mfma_f32_16x16x32_bf16 v[46:49], v[156:159], v[196:199], v[46:49]
	v_mfma_f32_16x16x32_bf16 v[42:45], v[164:167], v[196:199], v[42:45]
	v_mfma_f32_16x16x32_bf16 v[30:33], v[156:159], v[204:207], v[30:33]
	v_mfma_f32_16x16x32_bf16 v[26:29], v[164:167], v[204:207], v[26:29]
	v_mfma_f32_16x16x32_bf16 v[14:17], v[156:159], v[212:215], v[14:17]
	v_mfma_f32_16x16x32_bf16 v[10:13], v[164:167], v[212:215], v[10:13]
	v_mfma_f32_16x16x32_bf16 v[62:65], v[160:163], v[192:195], v[62:65]
	v_mfma_f32_16x16x32_bf16 v[58:61], v[168:171], v[192:195], v[58:61]
	v_mfma_f32_16x16x32_bf16 v[46:49], v[160:163], v[200:203], v[46:49]
	v_mfma_f32_16x16x32_bf16 v[42:45], v[168:171], v[200:203], v[42:45]
	v_mfma_f32_16x16x32_bf16 v[30:33], v[160:163], v[208:211], v[30:33]
	v_mfma_f32_16x16x32_bf16 v[26:29], v[168:171], v[208:211], v[26:29]
	v_mfma_f32_16x16x32_bf16 v[14:17], v[160:163], v[216:219], v[14:17]
	v_mfma_f32_16x16x32_bf16 v[10:13], v[168:171], v[216:219], v[10:13]
	v_mfma_f32_16x16x32_bf16 v[54:57], v[172:175], v[188:191], v[54:57]
	v_mfma_f32_16x16x32_bf16 v[50:53], v[180:183], v[188:191], v[50:53]
	v_mfma_f32_16x16x32_bf16 v[38:41], v[172:175], v[196:199], v[38:41]
	v_mfma_f32_16x16x32_bf16 v[34:37], v[180:183], v[196:199], v[34:37]
	v_mfma_f32_16x16x32_bf16 v[22:25], v[172:175], v[204:207], v[22:25]
	v_mfma_f32_16x16x32_bf16 v[18:21], v[180:183], v[204:207], v[18:21]
	v_mfma_f32_16x16x32_bf16 v[6:9], v[172:175], v[212:215], v[6:9]
	v_mfma_f32_16x16x32_bf16 v[2:5], v[180:183], v[212:215], v[2:5]
	v_mfma_f32_16x16x32_bf16 v[54:57], v[176:179], v[192:195], v[54:57]
	v_mfma_f32_16x16x32_bf16 v[50:53], v[184:187], v[192:195], v[50:53]
	v_mfma_f32_16x16x32_bf16 v[38:41], v[176:179], v[200:203], v[38:41]
	v_mfma_f32_16x16x32_bf16 v[34:37], v[184:187], v[200:203], v[34:37]
	v_mfma_f32_16x16x32_bf16 v[22:25], v[176:179], v[208:211], v[22:25]
	v_mfma_f32_16x16x32_bf16 v[18:21], v[184:187], v[208:211], v[18:21]
	v_mfma_f32_16x16x32_bf16 v[6:9], v[176:179], v[216:219], v[6:9]
	v_mfma_f32_16x16x32_bf16 v[2:5], v[184:187], v[216:219], v[2:5]
	s_barrier
	s_add_i32 s36, s36, 2
	s_add_u32 s6, s6, 0x100
	s_addc_u32 s7, s7, 0
	s_add_u32 s34, s34, 0x100
	s_addc_u32 s35, s35, 0
	s_cmp_gt_u32 s36, 13
	s_cbranch_scc0 .LBB0_318
	s_and_b64 vcc, exec, s[18:19]
	s_cbranch_vccz .LBB0_321
	s_barrier

; #define PG8_STAGE(bufoff, gbase, voff) do { _Pragma("unroll") for (int _i = 0; _i < 2; ++_i) \
;         __builtin_amdgcn_global_load_lds((const unsigned*)((const char*)(gbase) + (voff)[_i]), (PG8_LAS unsigned*)(lds + (bufoff) + ldsw + _i * 8192), 16, 0, 0); } while (0)
; #define PG8_LDA(dst, b, h) do { _Pragma("unroll") for (int m = 0; m < 4; ++m) _Pragma("unroll") for (int k = 0; k < 2; ++k) dst[m][k] = *(const PG8_LAS bf16x8*)(lds + PG8_SA(b, h) + aoff + m * 2048 + k * 1024); } while (0)
; #define PG8_LDB(dst, b, h) do { _Pragma("unroll") for (int n = 0; n < 2; ++n) _Pragma("unroll") for (int k = 0; k < 2; ++k) dst[n][k] = *(const PG8_LAS bf16x8*)(lds + PG8_SB(b, h) + boff + n * 2048 + k * 1024); } while (0)
; #define PG8_MMA(ai, bj, At, Bt) do { __builtin_amdgcn_s_setprio(1); _Pragma("unroll") for (int m = 0; m < 4; ++m) _Pragma("unroll") for (int n = 0; n < 2; ++n) _Pragma("unroll") for (int k = 0; k < 2; ++k) \
;         acc[ai][bj][m][n] = __builtin_amdgcn_mfma_f32_16x16x32_bf16(Bt[n][k], At[m][k], acc[ai][bj][m][n], 0, 0, 0); __builtin_amdgcn_s_setprio(0); } while (0)
; #define PG8_WAIT_V(n) asm volatile("s_waitcnt vmcnt(" #n ")" ::: "memory")
; #define PG8_WAIT_L(n) asm volatile("s_waitcnt lgkmcnt(" #n ")" ::: "memory")
; template <class Epi, class Sched, bool ALIGN_EPI = false, bool SP2 = false>
; __device__ __forceinline__ void gemm_phase(PG8_LAS unsigned char* lds, const Gemm g, const Sched& S, const Epi& E) {
;     ...
;             const bool last = (t == nt - 2);
;             const char* a1 = cA + (size_t)(t + 1) * kstep;
;             const char* a2 = last ? nA : cA + (size_t)(t + 2) * kstep; const char* b2 = last ? nB : cB + (size_t)(t + 2) * kstep;
;             const char* a3 = a2 + kstep; const char* b3 = b2 + kstep;
;             if (last && has_next) S.a_ready(nxt);
;             if constexpr (SP2) {
;             PG8_LDB(B0, 0, 0); PG8_LDB(B1, 0, 1); PG8_SCHED; PG8_LDA(At, 0, 0); PG8_STAGE(PG8_SA(1, 1), a1 + hstepA, voffA);
;             PG8_WAIT_V(8); PG8_WAIT_L(0); PG8_BAR; PG8_MMA(0, 0, At, B0); PG8_MMA(0, 1, At, B1); PG8_BAR; PG8_SCHED;
;             PG8_LDA(At, 0, 1); PG8_STAGE(PG8_SB(0, 0), b2, voffB); PG8_STAGE(PG8_SB(0, 1), b2 + hstepB, voffB); PG8_STAGE(PG8_SA(0, 0), a2, voffA);
;             PG8_WAIT_V(8); PG8_WAIT_L(0); PG8_BAR; PG8_MMA(1, 0, At, B0); PG8_MMA(1, 1, At, B1); PG8_BAR; PG8_SCHED;
.LBB0_780:
	ds_read_b128 v[148:151], v165
	ds_read_b128 v[152:155], v165 offset:1024
	ds_read_b128 v[156:159], v165 offset:2048
	ds_read_b128 v[170:173], v165 offset:3072
	ds_read_b128 v[174:177], v166
	ds_read_b128 v[178:181], v166 offset:1024
	ds_read_b128 v[182:185], v166 offset:2048
	ds_read_b128 v[186:189], v166 offset:3072
	s_add_u32 s0, s6, 0x100
	s_addc_u32 s1, s7, 0
	s_cmp_eq_u32 s66, 2
	s_cselect_b32 s29, s25, s1
	s_cselect_b32 s28, s24, s0
	s_cselect_b32 s9, s27, s65
	s_cselect_b32 s8, s26, s64
	v_lshl_add_u64 v[222:223], s[6:7], 0, v[140:141]
	s_add_i32 m0, s36, 0xc000
	ds_read_b128 v[190:193], v167
	ds_read_b128 v[194:197], v167 offset:1024
	ds_read_b128 v[198:201], v167 offset:2048
	ds_read_b128 v[202:205], v167 offset:3072
	ds_read_b128 v[206:209], v167 offset:4096
	ds_read_b128 v[210:213], v167 offset:5120
	ds_read_b128 v[214:217], v167 offset:6144
	ds_read_b128 v[218:221], v167 offset:7168
	global_load_lds_dwordx4 v[222:223], off
	v_lshl_add_u64 v[222:223], s[6:7], 0, v[142:143]
	s_add_i32 m0, s36, 0xe000
	s_nop 0
	global_load_lds_dwordx4 v[222:223], off
	s_waitcnt vmcnt(8)
	s_waitcnt lgkmcnt(0)
	s_barrier
	v_mfma_f32_16x16x32_bf16 v[126:129], v[148:151], v[190:193], v[126:129]
	v_mfma_f32_16x16x32_bf16 v[122:125], v[156:159], v[190:193], v[122:125]
	v_mfma_f32_16x16x32_bf16 v[110:113], v[148:151], v[198:201], v[110:113]
	v_mfma_f32_16x16x32_bf16 v[106:109], v[156:159], v[198:201], v[106:109]
	v_mfma_f32_16x16x32_bf16 v[94:97], v[148:151], v[206:209], v[94:97]
	v_mfma_f32_16x16x32_bf16 v[90:93], v[156:159], v[206:209], v[90:93]
	v_mfma_f32_16x16x32_bf16 v[78:81], v[148:151], v[214:217], v[78:81]
	v_mfma_f32_16x16x32_bf16 v[74:77], v[156:159], v[214:217], v[74:77]
	v_mfma_f32_16x16x32_bf16 v[126:129], v[152:155], v[194:197], v[126:129]
	v_mfma_f32_16x16x32_bf16 v[122:125], v[170:173], v[194:197], v[122:125]
	v_mfma_f32_16x16x32_bf16 v[110:113], v[152:155], v[202:205], v[110:113]
	v_mfma_f32_16x16x32_bf16 v[106:109], v[170:173], v[202:205], v[106:109]
	v_mfma_f32_16x16x32_bf16 v[94:97], v[152:155], v[210:213], v[94:97]
	v_mfma_f32_16x16x32_bf16 v[90:93], v[170:173], v[210:213], v[90:93]
	v_mfma_f32_16x16x32_bf16 v[78:81], v[152:155], v[218:221], v[78:81]
	v_mfma_f32_16x16x32_bf16 v[74:77], v[170:173], v[218:221], v[74:77]
	v_mfma_f32_16x16x32_bf16 v[118:121], v[174:177], v[190:193], v[118:121]
	v_mfma_f32_16x16x32_bf16 v[114:117], v[182:185], v[190:193], v[114:117]
	v_mfma_f32_16x16x32_bf16 v[102:105], v[174:177], v[198:201], v[102:105]
	v_mfma_f32_16x16x32_bf16 v[98:101], v[182:185], v[198:201], v[98:101]
	v_mfma_f32_16x16x32_bf16 v[86:89], v[174:177], v[206:209], v[86:89]
	v_mfma_f32_16x16x32_bf16 v[82:85], v[182:185], v[206:209], v[82:85]
	v_mfma_f32_16x16x32_bf16 v[70:73], v[174:177], v[214:217], v[70:73]
	v_mfma_f32_16x16x32_bf16 v[66:69], v[182:185], v[214:217], v[66:69]
	v_mfma_f32_16x16x32_bf16 v[118:121], v[178:181], v[194:197], v[118:121]
	v_mfma_f32_16x16x32_bf16 v[114:117], v[186:189], v[194:197], v[114:117]
	v_mfma_f32_16x16x32_bf16 v[102:105], v[178:181], v[202:205], v[102:105]
	v_mfma_f32_16x16x32_bf16 v[98:101], v[186:189], v[202:205], v[98:101]
	v_mfma_f32_16x16x32_bf16 v[86:89], v[178:181], v[210:213], v[86:89]
	v_mfma_f32_16x16x32_bf16 v[82:85], v[186:189], v[210:213], v[82:85]
	v_mfma_f32_16x16x32_bf16 v[70:73], v[178:181], v[218:221], v[70:73]
	v_mfma_f32_16x16x32_bf16 v[66:69], v[186:189], v[218:221], v[66:69]
	s_barrier
	s_add_i32 s6, s48, s35
	s_add_u32 s98, s8, 0x80
	s_addc_u32 s99, s9, 0
	s_mov_b32 m0, s6
	ds_read_b128 v[190:193], v167 offset:16384
	ds_read_b128 v[194:197], v167 offset:17408
	ds_read_b128 v[198:201], v167 offset:18432
	ds_read_b128 v[202:205], v167 offset:19456
	ds_read_b128 v[206:209], v167 offset:20480
	ds_read_b128 v[210:213], v167 offset:21504
	ds_read_b128 v[214:217], v167 offset:22528
	ds_read_b128 v[218:221], v167 offset:23552
	global_load_lds_dwordx4 v132, s[8:9]
	s_add_i32 m0, s6, 0x2000
	s_add_u32 s6, s8, 0x18000
	s_addc_u32 s7, s9, 0
	s_add_i32 s67, s49, s35
	global_load_lds_dwordx4 v136, s[8:9]
	s_mov_b32 m0, s67
	s_nop 0
	global_load_lds_dwordx4 v132, s[6:7]
	s_add_i32 m0, s67, 0x2000
	s_nop 0
	global_load_lds_dwordx4 v136, s[6:7]
	s_add_u32 s100, s28, 0x80
	s_addc_u32 s101, s29, 0
	s_mov_b32 m0, s36
	s_nop 0
	global_load_lds_dwordx4 v130, s[28:29]
	s_mov_b32 m0, s37
	s_nop 0
	global_load_lds_dwordx4 v134, s[28:29]
	s_waitcnt vmcnt(8)
	s_waitcnt lgkmcnt(0)
	s_barrier
	v_mfma_f32_16x16x32_bf16 v[62:65], v[148:151], v[190:193], v[62:65]
	v_mfma_f32_16x16x32_bf16 v[58:61], v[156:159], v[190:193], v[58:61]
	v_mfma_f32_16x16x32_bf16 v[46:49], v[148:151], v[198:201], v[46:49]
	v_mfma_f32_16x16x32_bf16 v[42:45], v[156:159], v[198:201], v[42:45]
	v_mfma_f32_16x16x32_bf16 v[30:33], v[148:151], v[206:209], v[30:33]
	v_mfma_f32_16x16x32_bf16 v[26:29], v[156:159], v[206:209], v[26:29]
	v_mfma_f32_16x16x32_bf16 v[14:17], v[148:151], v[214:217], v[14:17]
	v_mfma_f32_16x16x32_bf16 v[10:13], v[156:159], v[214:217], v[10:13]
	v_mfma_f32_16x16x32_bf16 v[62:65], v[152:155], v[194:197], v[62:65]
	v_mfma_f32_16x16x32_bf16 v[58:61], v[170:173], v[194:197], v[58:61]
	v_mfma_f32_16x16x32_bf16 v[46:49], v[152:155], v[202:205], v[46:49]
	v_mfma_f32_16x16x32_bf16 v[42:45], v[170:173], v[202:205], v[42:45]
	v_mfma_f32_16x16x32_bf16 v[30:33], v[152:155], v[210:213], v[30:33]
	v_mfma_f32_16x16x32_bf16 v[26:29], v[170:173], v[210:213], v[26:29]
	v_mfma_f32_16x16x32_bf16 v[14:17], v[152:155], v[218:221], v[14:17]
	v_mfma_f32_16x16x32_bf16 v[10:13], v[170:173], v[218:221], v[10:13]
	v_mfma_f32_16x16x32_bf16 v[54:57], v[174:177], v[190:193], v[54:57]
	v_mfma_f32_16x16x32_bf16 v[50:53], v[182:185], v[190:193], v[50:53]
	v_mfma_f32_16x16x32_bf16 v[38:41], v[174:177], v[198:201], v[38:41]
	v_mfma_f32_16x16x32_bf16 v[34:37], v[182:185], v[198:201], v[34:37]
	v_mfma_f32_16x16x32_bf16 v[22:25], v[174:177], v[206:209], v[22:25]
	v_mfma_f32_16x16x32_bf16 v[18:21], v[182:185], v[206:209], v[18:21]
	v_mfma_f32_16x16x32_bf16 v[6:9], v[174:177], v[214:217], v[6:9]
	v_mfma_f32_16x16x32_bf16 v[2:5], v[182:185], v[214:217], v[2:5]
	v_mfma_f32_16x16x32_bf16 v[54:57], v[178:181], v[194:197], v[54:57]
	v_mfma_f32_16x16x32_bf16 v[50:53], v[186:189], v[194:197], v[50:53]
	v_mfma_f32_16x16x32_bf16 v[38:41], v[178:181], v[202:205], v[38:41]
	v_mfma_f32_16x16x32_bf16 v[34:37], v[186:189], v[202:205], v[34:37]
	v_mfma_f32_16x16x32_bf16 v[22:25], v[178:181], v[210:213], v[22:25]
	v_mfma_f32_16x16x32_bf16 v[18:21], v[186:189], v[210:213], v[18:21]
	v_mfma_f32_16x16x32_bf16 v[6:9], v[178:181], v[218:221], v[6:9]
	v_mfma_f32_16x16x32_bf16 v[2:5], v[186:189], v[218:221], v[2:5]
	s_barrier
; #define PG8_STAGE(bufoff, gbase, voff) do { _Pragma("unroll") for (int _i = 0; _i < 2; ++_i) \
;         __builtin_amdgcn_global_load_lds((const unsigned*)((const char*)(gbase) + (voff)[_i]), (PG8_LAS unsigned*)(lds + (bufoff) + ldsw + _i * 8192), 16, 0, 0); } while (0)
; #define PG8_LDA(dst, b, h) do { _Pragma("unroll") for (int m = 0; m < 4; ++m) _Pragma("unroll") for (int k = 0; k < 2; ++k) dst[m][k] = *(const PG8_LAS bf16x8*)(lds + PG8_SA(b, h) + aoff + m * 2048 + k * 1024); } while (0)
; #define PG8_LDB(dst, b, h) do { _Pragma("unroll") for (int n = 0; n < 2; ++n) _Pragma("unroll") for (int k = 0; k < 2; ++k) dst[n][k] = *(const PG8_LAS bf16x8*)(lds + PG8_SB(b, h) + boff + n * 2048 + k * 1024); } while (0)
; #define PG8_MMA(ai, bj, At, Bt) do { __builtin_amdgcn_s_setprio(1); _Pragma("unroll") for (int m = 0; m < 4; ++m) _Pragma("unroll") for (int n = 0; n < 2; ++n) _Pragma("unroll") for (int k = 0; k < 2; ++k) \
;         acc[ai][bj][m][n] = __builtin_amdgcn_mfma_f32_16x16x32_bf16(Bt[n][k], At[m][k], acc[ai][bj][m][n], 0, 0, 0); __builtin_amdgcn_s_setprio(0); } while (0)
; #define PG8_WAIT_V(n) asm volatile("s_waitcnt vmcnt(" #n ")" ::: "memory")
; #define PG8_WAIT_L(n) asm volatile("s_waitcnt lgkmcnt(" #n ")" ::: "memory")
; #define PG8_BAR __builtin_amdgcn_s_barrier()
; #define PG8_SCHED __builtin_amdgcn_sched_barrier(0)
; template <class Epi, class Sched, bool ALIGN_EPI = false, bool SP2 = false>
; __device__ __forceinline__ void gemm_phase(PG8_LAS unsigned char* lds, const Gemm g, const Sched& S, const Epi& E) {
;     ...
;             PG8_LDB(B0, 1, 0); PG8_LDB(B1, 1, 1); PG8_SCHED; PG8_LDA(At, 1, 0); PG8_STAGE(PG8_SA(0, 1), a2 + hstepA, voffA);
;             PG8_WAIT_V(8); PG8_WAIT_L(0); PG8_BAR; PG8_MMA(0, 0, At, B0); PG8_MMA(0, 1, At, B1); PG8_BAR; PG8_SCHED;
;             PG8_LDA(At, 1, 1); PG8_STAGE(PG8_SB(1, 0), b3, voffB); PG8_STAGE(PG8_SB(1, 1), b3 + hstepB, voffB); PG8_STAGE(PG8_SA(1, 0), a3, voffA);
;             PG8_WAIT_V(8); PG8_WAIT_L(0); PG8_BAR; PG8_MMA(1, 0, At, B0); PG8_MMA(1, 1, At, B1); PG8_BAR; PG8_SCHED;
	s_add_i32 s67, 0, 0x18000
	v_add_u32_e32 v138, s67, v160
	s_add_i32 s68, 0, 0x1c000
	ds_read_b128 v[148:151], v138
	ds_read_b128 v[152:155], v138 offset:1024
	ds_read_b128 v[156:159], v138 offset:2048
	ds_read_b128 v[170:173], v138 offset:3072
	v_add_u32_e32 v138, s68, v160
	ds_read_b128 v[174:177], v138
	ds_read_b128 v[178:181], v138 offset:1024
	ds_read_b128 v[182:185], v138 offset:2048
	ds_read_b128 v[186:189], v138 offset:3072
	s_add_u32 s6, s28, 0x2a000
	s_addc_u32 s7, s29, 0
	s_mov_b32 m0, s38
	ds_read_b128 v[190:193], v167 offset:32768
	ds_read_b128 v[194:197], v167 offset:33792
	ds_read_b128 v[198:201], v167 offset:34816
	ds_read_b128 v[202:205], v167 offset:35840
	ds_read_b128 v[206:209], v167 offset:36864
	ds_read_b128 v[210:213], v167 offset:37888
	ds_read_b128 v[214:217], v167 offset:38912
	ds_read_b128 v[218:221], v167 offset:39936
	global_load_lds_dwordx4 v130, s[6:7]
	s_mov_b32 m0, s39
	s_nop 0
	global_load_lds_dwordx4 v134, s[6:7]
	s_waitcnt vmcnt(8)
	s_waitcnt lgkmcnt(0)
	s_barrier
	v_mfma_f32_16x16x32_bf16 v[126:129], v[148:151], v[190:193], v[126:129]
	v_mfma_f32_16x16x32_bf16 v[122:125], v[156:159], v[190:193], v[122:125]
	v_mfma_f32_16x16x32_bf16 v[110:113], v[148:151], v[198:201], v[110:113]
	v_mfma_f32_16x16x32_bf16 v[106:109], v[156:159], v[198:201], v[106:109]
	v_mfma_f32_16x16x32_bf16 v[94:97], v[148:151], v[206:209], v[94:97]
	v_mfma_f32_16x16x32_bf16 v[90:93], v[156:159], v[206:209], v[90:93]
	v_mfma_f32_16x16x32_bf16 v[78:81], v[148:151], v[214:217], v[78:81]
	v_mfma_f32_16x16x32_bf16 v[74:77], v[156:159], v[214:217], v[74:77]
	v_mfma_f32_16x16x32_bf16 v[126:129], v[152:155], v[194:197], v[126:129]
	v_mfma_f32_16x16x32_bf16 v[122:125], v[170:173], v[194:197], v[122:125]
	v_mfma_f32_16x16x32_bf16 v[110:113], v[152:155], v[202:205], v[110:113]
	v_mfma_f32_16x16x32_bf16 v[106:109], v[170:173], v[202:205], v[106:109]
	v_mfma_f32_16x16x32_bf16 v[94:97], v[152:155], v[210:213], v[94:97]
	v_mfma_f32_16x16x32_bf16 v[90:93], v[170:173], v[210:213], v[90:93]
	v_mfma_f32_16x16x32_bf16 v[78:81], v[152:155], v[218:221], v[78:81]
	v_mfma_f32_16x16x32_bf16 v[74:77], v[170:173], v[218:221], v[74:77]
	v_mfma_f32_16x16x32_bf16 v[118:121], v[174:177], v[190:193], v[118:121]
	v_mfma_f32_16x16x32_bf16 v[114:117], v[182:185], v[190:193], v[114:117]
	v_mfma_f32_16x16x32_bf16 v[102:105], v[174:177], v[198:201], v[102:105]
	v_mfma_f32_16x16x32_bf16 v[98:101], v[182:185], v[198:201], v[98:101]
	v_mfma_f32_16x16x32_bf16 v[86:89], v[174:177], v[206:209], v[86:89]
	v_mfma_f32_16x16x32_bf16 v[82:85], v[182:185], v[206:209], v[82:85]
	v_mfma_f32_16x16x32_bf16 v[70:73], v[174:177], v[214:217], v[70:73]
	v_mfma_f32_16x16x32_bf16 v[66:69], v[182:185], v[214:217], v[66:69]
	v_mfma_f32_16x16x32_bf16 v[118:121], v[178:181], v[194:197], v[118:121]
	v_mfma_f32_16x16x32_bf16 v[114:117], v[186:189], v[194:197], v[114:117]
	v_mfma_f32_16x16x32_bf16 v[102:105], v[178:181], v[202:205], v[102:105]
	v_mfma_f32_16x16x32_bf16 v[98:101], v[186:189], v[202:205], v[98:101]
	v_mfma_f32_16x16x32_bf16 v[86:89], v[178:181], v[210:213], v[86:89]
	v_mfma_f32_16x16x32_bf16 v[82:85], v[186:189], v[210:213], v[82:85]
	v_mfma_f32_16x16x32_bf16 v[70:73], v[178:181], v[218:221], v[70:73]
	v_mfma_f32_16x16x32_bf16 v[66:69], v[186:189], v[218:221], v[66:69]
	s_barrier
	s_add_i32 s6, s67, s35
	s_mov_b32 m0, s6
	ds_read_b128 v[190:193], v167 offset:49152
	ds_read_b128 v[194:197], v167 offset:50176
	ds_read_b128 v[198:201], v167 offset:51200
	ds_read_b128 v[202:205], v167 offset:52224
	ds_read_b128 v[206:209], v167 offset:53248
	ds_read_b128 v[210:213], v167 offset:54272
	ds_read_b128 v[214:217], v167 offset:55296
	ds_read_b128 v[218:221], v167 offset:56320
	global_load_lds_dwordx4 v132, s[98:99]
	s_add_i32 m0, s6, 0x2000
	s_add_u32 s6, s8, 0x18080
	s_addc_u32 s7, s9, 0
	s_add_i32 s8, s68, s35
	global_load_lds_dwordx4 v136, s[98:99]
	s_mov_b32 m0, s8
	s_nop 0
	global_load_lds_dwordx4 v132, s[6:7]
	s_add_i32 m0, s8, 0x2000
	s_nop 0
	global_load_lds_dwordx4 v136, s[6:7]
	s_mov_b32 m0, s45
	s_nop 0
	global_load_lds_dwordx4 v130, s[100:101]
	s_mov_b32 m0, s46
	s_nop 0
	global_load_lds_dwordx4 v134, s[100:101]
	s_waitcnt vmcnt(8)
	s_waitcnt lgkmcnt(0)
	s_barrier
	v_mfma_f32_16x16x32_bf16 v[62:65], v[148:151], v[190:193], v[62:65]
	v_mfma_f32_16x16x32_bf16 v[58:61], v[156:159], v[190:193], v[58:61]
	v_mfma_f32_16x16x32_bf16 v[46:49], v[148:151], v[198:201], v[46:49]
	v_mfma_f32_16x16x32_bf16 v[42:45], v[156:159], v[198:201], v[42:45]
	v_mfma_f32_16x16x32_bf16 v[30:33], v[148:151], v[206:209], v[30:33]
	v_mfma_f32_16x16x32_bf16 v[26:29], v[156:159], v[206:209], v[26:29]
	v_mfma_f32_16x16x32_bf16 v[14:17], v[148:151], v[214:217], v[14:17]
	v_mfma_f32_16x16x32_bf16 v[10:13], v[156:159], v[214:217], v[10:13]
	v_mfma_f32_16x16x32_bf16 v[62:65], v[152:155], v[194:197], v[62:65]
	v_mfma_f32_16x16x32_bf16 v[58:61], v[170:173], v[194:197], v[58:61]
	v_mfma_f32_16x16x32_bf16 v[46:49], v[152:155], v[202:205], v[46:49]
	v_mfma_f32_16x16x32_bf16 v[42:45], v[170:173], v[202:205], v[42:45]
	v_mfma_f32_16x16x32_bf16 v[30:33], v[152:155], v[210:213], v[30:33]
	v_mfma_f32_16x16x32_bf16 v[26:29], v[170:173], v[210:213], v[26:29]
	v_mfma_f32_16x16x32_bf16 v[14:17], v[152:155], v[218:221], v[14:17]
	v_mfma_f32_16x16x32_bf16 v[10:13], v[170:173], v[218:221], v[10:13]
	v_mfma_f32_16x16x32_bf16 v[54:57], v[174:177], v[190:193], v[54:57]
	v_mfma_f32_16x16x32_bf16 v[50:53], v[182:185], v[190:193], v[50:53]
	v_mfma_f32_16x16x32_bf16 v[38:41], v[174:177], v[198:201], v[38:41]
	v_mfma_f32_16x16x32_bf16 v[34:37], v[182:185], v[198:201], v[34:37]
	v_mfma_f32_16x16x32_bf16 v[22:25], v[174:177], v[206:209], v[22:25]
	v_mfma_f32_16x16x32_bf16 v[18:21], v[182:185], v[206:209], v[18:21]
	v_mfma_f32_16x16x32_bf16 v[6:9], v[174:177], v[214:217], v[6:9]
	v_mfma_f32_16x16x32_bf16 v[2:5], v[182:185], v[214:217], v[2:5]
	v_mfma_f32_16x16x32_bf16 v[54:57], v[178:181], v[194:197], v[54:57]
	v_mfma_f32_16x16x32_bf16 v[50:53], v[186:189], v[194:197], v[50:53]
	v_mfma_f32_16x16x32_bf16 v[38:41], v[178:181], v[202:205], v[38:41]
	v_mfma_f32_16x16x32_bf16 v[34:37], v[186:189], v[202:205], v[34:37]
	v_mfma_f32_16x16x32_bf16 v[22:25], v[178:181], v[210:213], v[22:25]
	v_mfma_f32_16x16x32_bf16 v[18:21], v[186:189], v[210:213], v[18:21]
	v_mfma_f32_16x16x32_bf16 v[6:9], v[178:181], v[218:221], v[6:9]
	v_mfma_f32_16x16x32_bf16 v[2:5], v[186:189], v[218:221], v[2:5]
	s_barrier
	s_add_i32 s66, s66, 2
	s_add_u32 s64, s64, 0x100
	s_addc_u32 s65, s65, 0
	s_cmp_gt_u32 s66, 3
	s_mov_b64 s[6:7], s[0:1]
	s_cbranch_scc0 .LBB0_780
	s_and_b64 vcc, exec, s[20:21]
	s_cbranch_vccz .LBB0_783
	s_barrier

; #define PG8_STAGE(bufoff, gbase, voff) do { _Pragma("unroll") for (int _i = 0; _i < 2; ++_i) \
;         __builtin_amdgcn_global_load_lds((const unsigned*)((const char*)(gbase) + (voff)[_i]), (PG8_LAS unsigned*)(lds + (bufoff) + ldsw + _i * 8192), 16, 0, 0); } while (0)
; #define PG8_LDA(dst, b, h) do { _Pragma("unroll") for (int m = 0; m < 4; ++m) _Pragma("unroll") for (int k = 0; k < 2; ++k) dst[m][k] = *(const PG8_LAS bf16x8*)(lds + PG8_SA(b, h) + aoff + m * 2048 + k * 1024); } while (0)
; #define PG8_LDB(dst, b, h) do { _Pragma("unroll") for (int n = 0; n < 2; ++n) _Pragma("unroll") for (int k = 0; k < 2; ++k) dst[n][k] = *(const PG8_LAS bf16x8*)(lds + PG8_SB(b, h) + boff + n * 2048 + k * 1024); } while (0)
; #define PG8_MMA(ai, bj, At, Bt) do { __builtin_amdgcn_s_setprio(1); _Pragma("unroll") for (int m = 0; m < 4; ++m) _Pragma("unroll") for (int n = 0; n < 2; ++n) _Pragma("unroll") for (int k = 0; k < 2; ++k) \
;         acc[ai][bj][m][n] = __builtin_amdgcn_mfma_f32_16x16x32_bf16(Bt[n][k], At[m][k], acc[ai][bj][m][n], 0, 0, 0); __builtin_amdgcn_s_setprio(0); } while (0)
; #define PG8_WAIT_V(n) asm volatile("s_waitcnt vmcnt(" #n ")" ::: "memory")
; #define PG8_WAIT_L(n) asm volatile("s_waitcnt lgkmcnt(" #n ")" ::: "memory")
; template <class Epi, class Sched, bool ALIGN_EPI = false, bool SP2 = false>
; __device__ __forceinline__ void gemm_phase(PG8_LAS unsigned char* lds, const Gemm g, const Sched& S, const Epi& E) {
;     ...
;             const bool last = (t == nt - 2);
;             const char* a1 = cA + (size_t)(t + 1) * kstep;
;             const char* a2 = last ? nA : cA + (size_t)(t + 2) * kstep; const char* b2 = last ? nB : cB + (size_t)(t + 2) * kstep;
;             const char* a3 = a2 + kstep; const char* b3 = b2 + kstep;
;             if (last && has_next) S.a_ready(nxt);
;             if constexpr (SP2) {
;             PG8_LDB(B0, 0, 0); PG8_LDB(B1, 0, 1); PG8_SCHED; PG8_LDA(At, 0, 0); PG8_STAGE(PG8_SA(1, 1), a1 + hstepA, voffA);
;             PG8_WAIT_V(8); PG8_WAIT_L(0); PG8_BAR; PG8_MMA(0, 0, At, B0); PG8_MMA(0, 1, At, B1); PG8_BAR; PG8_SCHED;
;             PG8_LDA(At, 0, 1); PG8_STAGE(PG8_SB(0, 0), b2, voffB); PG8_STAGE(PG8_SB(0, 1), b2 + hstepB, voffB); PG8_STAGE(PG8_SA(0, 0), a2, voffA);
;             PG8_WAIT_V(8); PG8_WAIT_L(0); PG8_BAR; PG8_MMA(1, 0, At, B0); PG8_MMA(1, 1, At, B1); PG8_BAR; PG8_SCHED;
.LBB0_1086:
	ds_read_b128 v[130:133], v168
	ds_read_b128 v[134:137], v168 offset:1024
	ds_read_b128 v[138:141], v168 offset:2048
	ds_read_b128 v[158:161], v168 offset:3072
	ds_read_b128 v[162:165], v169
	ds_read_b128 v[172:175], v169 offset:1024
	ds_read_b128 v[176:179], v169 offset:2048
	ds_read_b128 v[180:183], v169 offset:3072
	s_add_u32 s26, s24, 0xfffe0080
	s_addc_u32 s27, s25, -1
	s_cmp_eq_u32 s49, 4
	s_cselect_b32 s29, s17, s27
	s_cselect_b32 s28, s45, s26
	s_cselect_b32 s27, s15, s48
	s_cselect_b32 s26, s46, s47
	s_add_i32 m0, s23, 0xc000
	ds_read_b128 v[184:187], v170
	ds_read_b128 v[188:191], v170 offset:1024
	ds_read_b128 v[192:195], v170 offset:2048
	ds_read_b128 v[196:199], v170 offset:3072
	ds_read_b128 v[200:203], v170 offset:4096
	ds_read_b128 v[204:207], v170 offset:5120
	ds_read_b128 v[208:211], v170 offset:6144
	ds_read_b128 v[212:215], v170 offset:7168
	global_load_lds_dwordx4 v150, s[24:25]
	s_add_i32 m0, s23, 0xe000
	s_nop 0
	global_load_lds_dwordx4 v152, s[24:25]
	s_waitcnt vmcnt(8)
	s_waitcnt lgkmcnt(0)
	s_barrier
	v_mfma_f32_16x16x32_bf16 v[126:129], v[130:133], v[184:187], v[126:129]
	v_mfma_f32_16x16x32_bf16 v[122:125], v[138:141], v[184:187], v[122:125]
	v_mfma_f32_16x16x32_bf16 v[110:113], v[130:133], v[192:195], v[110:113]
	v_mfma_f32_16x16x32_bf16 v[106:109], v[138:141], v[192:195], v[106:109]
	v_mfma_f32_16x16x32_bf16 v[94:97], v[130:133], v[200:203], v[94:97]
	v_mfma_f32_16x16x32_bf16 v[90:93], v[138:141], v[200:203], v[90:93]
	v_mfma_f32_16x16x32_bf16 v[78:81], v[130:133], v[208:211], v[78:81]
	v_mfma_f32_16x16x32_bf16 v[74:77], v[138:141], v[208:211], v[74:77]
	v_mfma_f32_16x16x32_bf16 v[126:129], v[134:137], v[188:191], v[126:129]
	v_mfma_f32_16x16x32_bf16 v[122:125], v[158:161], v[188:191], v[122:125]
	v_mfma_f32_16x16x32_bf16 v[110:113], v[134:137], v[196:199], v[110:113]
	v_mfma_f32_16x16x32_bf16 v[106:109], v[158:161], v[196:199], v[106:109]
	v_mfma_f32_16x16x32_bf16 v[94:97], v[134:137], v[204:207], v[94:97]
	v_mfma_f32_16x16x32_bf16 v[90:93], v[158:161], v[204:207], v[90:93]
	v_mfma_f32_16x16x32_bf16 v[78:81], v[134:137], v[212:215], v[78:81]
	v_mfma_f32_16x16x32_bf16 v[74:77], v[158:161], v[212:215], v[74:77]
	v_mfma_f32_16x16x32_bf16 v[118:121], v[162:165], v[184:187], v[118:121]
	v_mfma_f32_16x16x32_bf16 v[114:117], v[176:179], v[184:187], v[114:117]
	v_mfma_f32_16x16x32_bf16 v[102:105], v[162:165], v[192:195], v[102:105]
	v_mfma_f32_16x16x32_bf16 v[98:101], v[176:179], v[192:195], v[98:101]
	v_mfma_f32_16x16x32_bf16 v[86:89], v[162:165], v[200:203], v[86:89]
	v_mfma_f32_16x16x32_bf16 v[82:85], v[176:179], v[200:203], v[82:85]
	v_mfma_f32_16x16x32_bf16 v[70:73], v[162:165], v[208:211], v[70:73]
	v_mfma_f32_16x16x32_bf16 v[66:69], v[176:179], v[208:211], v[66:69]
	v_mfma_f32_16x16x32_bf16 v[118:121], v[172:175], v[188:191], v[118:121]
	v_mfma_f32_16x16x32_bf16 v[114:117], v[180:183], v[188:191], v[114:117]
	v_mfma_f32_16x16x32_bf16 v[102:105], v[172:175], v[196:199], v[102:105]
	v_mfma_f32_16x16x32_bf16 v[98:101], v[180:183], v[196:199], v[98:101]
	v_mfma_f32_16x16x32_bf16 v[86:89], v[172:175], v[204:207], v[86:89]
	v_mfma_f32_16x16x32_bf16 v[82:85], v[180:183], v[204:207], v[82:85]
	v_mfma_f32_16x16x32_bf16 v[70:73], v[172:175], v[212:215], v[70:73]
	v_mfma_f32_16x16x32_bf16 v[66:69], v[180:183], v[212:215], v[66:69]
	s_barrier
	s_add_i32 s50, s42, s34
	s_add_u32 s98, s26, 0x80
	s_addc_u32 s99, s27, 0
	s_mov_b32 m0, s50
	ds_read_b128 v[184:187], v170 offset:16384
	ds_read_b128 v[188:191], v170 offset:17408
	ds_read_b128 v[192:195], v170 offset:18432
	ds_read_b128 v[196:199], v170 offset:19456
	ds_read_b128 v[200:203], v170 offset:20480
	ds_read_b128 v[204:207], v170 offset:21504
	ds_read_b128 v[208:211], v170 offset:22528
	ds_read_b128 v[212:215], v170 offset:23552
	global_load_lds_dwordx4 v144, s[26:27]
	s_add_i32 m0, s50, 0x2000
	s_add_u32 s50, s26, 0x20000
	s_addc_u32 s51, s27, 0
	s_add_i32 s52, s43, s34
	global_load_lds_dwordx4 v148, s[26:27]
	s_mov_b32 m0, s52
	s_nop 0
	global_load_lds_dwordx4 v144, s[50:51]
	s_add_i32 m0, s52, 0x2000
	s_nop 0
	global_load_lds_dwordx4 v148, s[50:51]
	s_add_u32 s100, s28, 0x80
	s_addc_u32 s101, s29, 0
	s_mov_b32 m0, s23
	s_nop 0
	global_load_lds_dwordx4 v142, s[28:29]
	s_mov_b32 m0, s35
	s_nop 0
	global_load_lds_dwordx4 v146, s[28:29]
	s_waitcnt vmcnt(8)
	s_waitcnt lgkmcnt(0)
	s_barrier
	v_mfma_f32_16x16x32_bf16 v[62:65], v[130:133], v[184:187], v[62:65]
	v_mfma_f32_16x16x32_bf16 v[58:61], v[138:141], v[184:187], v[58:61]
	v_mfma_f32_16x16x32_bf16 v[46:49], v[130:133], v[192:195], v[46:49]
	v_mfma_f32_16x16x32_bf16 v[42:45], v[138:141], v[192:195], v[42:45]
	v_mfma_f32_16x16x32_bf16 v[30:33], v[130:133], v[200:203], v[30:33]
	v_mfma_f32_16x16x32_bf16 v[26:29], v[138:141], v[200:203], v[26:29]
	v_mfma_f32_16x16x32_bf16 v[14:17], v[130:133], v[208:211], v[14:17]
	v_mfma_f32_16x16x32_bf16 v[10:13], v[138:141], v[208:211], v[10:13]
	v_mfma_f32_16x16x32_bf16 v[62:65], v[134:137], v[188:191], v[62:65]
	v_mfma_f32_16x16x32_bf16 v[58:61], v[158:161], v[188:191], v[58:61]
	v_mfma_f32_16x16x32_bf16 v[46:49], v[134:137], v[196:199], v[46:49]
	v_mfma_f32_16x16x32_bf16 v[42:45], v[158:161], v[196:199], v[42:45]
	v_mfma_f32_16x16x32_bf16 v[30:33], v[134:137], v[204:207], v[30:33]
	v_mfma_f32_16x16x32_bf16 v[26:29], v[158:161], v[204:207], v[26:29]
	v_mfma_f32_16x16x32_bf16 v[14:17], v[134:137], v[212:215], v[14:17]
	v_mfma_f32_16x16x32_bf16 v[10:13], v[158:161], v[212:215], v[10:13]
	v_mfma_f32_16x16x32_bf16 v[54:57], v[162:165], v[184:187], v[54:57]
	v_mfma_f32_16x16x32_bf16 v[50:53], v[176:179], v[184:187], v[50:53]
	v_mfma_f32_16x16x32_bf16 v[38:41], v[162:165], v[192:195], v[38:41]
	v_mfma_f32_16x16x32_bf16 v[34:37], v[176:179], v[192:195], v[34:37]
	v_mfma_f32_16x16x32_bf16 v[22:25], v[162:165], v[200:203], v[22:25]
	v_mfma_f32_16x16x32_bf16 v[18:21], v[176:179], v[200:203], v[18:21]
	v_mfma_f32_16x16x32_bf16 v[6:9], v[162:165], v[208:211], v[6:9]
	v_mfma_f32_16x16x32_bf16 v[2:5], v[176:179], v[208:211], v[2:5]
	v_mfma_f32_16x16x32_bf16 v[54:57], v[172:175], v[188:191], v[54:57]
	v_mfma_f32_16x16x32_bf16 v[50:53], v[180:183], v[188:191], v[50:53]
	v_mfma_f32_16x16x32_bf16 v[38:41], v[172:175], v[196:199], v[38:41]
	v_mfma_f32_16x16x32_bf16 v[34:37], v[180:183], v[196:199], v[34:37]
	v_mfma_f32_16x16x32_bf16 v[22:25], v[172:175], v[204:207], v[22:25]
	v_mfma_f32_16x16x32_bf16 v[18:21], v[180:183], v[204:207], v[18:21]
	v_mfma_f32_16x16x32_bf16 v[6:9], v[172:175], v[212:215], v[6:9]
	v_mfma_f32_16x16x32_bf16 v[2:5], v[180:183], v[212:215], v[2:5]
	s_barrier
; #define PG8_STAGE(bufoff, gbase, voff) do { _Pragma("unroll") for (int _i = 0; _i < 2; ++_i) \
;         __builtin_amdgcn_global_load_lds((const unsigned*)((const char*)(gbase) + (voff)[_i]), (PG8_LAS unsigned*)(lds + (bufoff) + ldsw + _i * 8192), 16, 0, 0); } while (0)
; #define PG8_LDA(dst, b, h) do { _Pragma("unroll") for (int m = 0; m < 4; ++m) _Pragma("unroll") for (int k = 0; k < 2; ++k) dst[m][k] = *(const PG8_LAS bf16x8*)(lds + PG8_SA(b, h) + aoff + m * 2048 + k * 1024); } while (0)
; #define PG8_LDB(dst, b, h) do { _Pragma("unroll") for (int n = 0; n < 2; ++n) _Pragma("unroll") for (int k = 0; k < 2; ++k) dst[n][k] = *(const PG8_LAS bf16x8*)(lds + PG8_SB(b, h) + boff + n * 2048 + k * 1024); } while (0)
; #define PG8_MMA(ai, bj, At, Bt) do { __builtin_amdgcn_s_setprio(1); _Pragma("unroll") for (int m = 0; m < 4; ++m) _Pragma("unroll") for (int n = 0; n < 2; ++n) _Pragma("unroll") for (int k = 0; k < 2; ++k) \
;         acc[ai][bj][m][n] = __builtin_amdgcn_mfma_f32_16x16x32_bf16(Bt[n][k], At[m][k], acc[ai][bj][m][n], 0, 0, 0); __builtin_amdgcn_s_setprio(0); } while (0)
; #define PG8_WAIT_V(n) asm volatile("s_waitcnt vmcnt(" #n ")" ::: "memory")
; #define PG8_WAIT_L(n) asm volatile("s_waitcnt lgkmcnt(" #n ")" ::: "memory")
; #define PG8_BAR __builtin_amdgcn_s_barrier()
; #define PG8_SCHED __builtin_amdgcn_sched_barrier(0)
; template <class Epi, class Sched, bool ALIGN_EPI = false, bool SP2 = false>
; __device__ __forceinline__ void gemm_phase(PG8_LAS unsigned char* lds, const Gemm g, const Sched& S, const Epi& E) {
;     ...
;             PG8_LDB(B0, 1, 0); PG8_LDB(B1, 1, 1); PG8_SCHED; PG8_LDA(At, 1, 0); PG8_STAGE(PG8_SA(0, 1), a2 + hstepA, voffA);
;             PG8_WAIT_V(8); PG8_WAIT_L(0); PG8_BAR; PG8_MMA(0, 0, At, B0); PG8_MMA(0, 1, At, B1); PG8_BAR; PG8_SCHED;
;             PG8_LDA(At, 1, 1); PG8_STAGE(PG8_SB(1, 0), b3, voffB); PG8_STAGE(PG8_SB(1, 1), b3 + hstepB, voffB); PG8_STAGE(PG8_SA(1, 0), a3, voffA);
;             PG8_WAIT_V(8); PG8_WAIT_L(0); PG8_BAR; PG8_MMA(1, 0, At, B0); PG8_MMA(1, 1, At, B1); PG8_BAR; PG8_SCHED;
	s_add_i32 s50, 0, 0x18000
	s_add_i32 s51, 0, 0x1c000
	v_add_u32_e32 v158, s50, v166
	v_add_u32_e32 v171, s51, v166
	ds_read_b128 v[130:133], v158
	ds_read_b128 v[134:137], v158 offset:1024
	ds_read_b128 v[138:141], v158 offset:2048
	ds_read_b128 v[158:161], v158 offset:3072
	ds_read_b128 v[162:165], v171
	ds_read_b128 v[172:175], v171 offset:1024
	ds_read_b128 v[176:179], v171 offset:2048
	ds_read_b128 v[180:183], v171 offset:3072
	s_add_u32 s28, s28, 0x20000
	s_addc_u32 s29, s29, 0
	s_mov_b32 m0, s36
	ds_read_b128 v[184:187], v170 offset:32768
	ds_read_b128 v[188:191], v170 offset:33792
	ds_read_b128 v[192:195], v170 offset:34816
	ds_read_b128 v[196:199], v170 offset:35840
	ds_read_b128 v[200:203], v170 offset:36864
	ds_read_b128 v[204:207], v170 offset:37888
	ds_read_b128 v[208:211], v170 offset:38912
	ds_read_b128 v[212:215], v170 offset:39936
	global_load_lds_dwordx4 v142, s[28:29]
	s_mov_b32 m0, s37
	s_nop 0
	global_load_lds_dwordx4 v146, s[28:29]
	s_waitcnt vmcnt(8)
	s_waitcnt lgkmcnt(0)
	s_barrier
	v_mfma_f32_16x16x32_bf16 v[126:129], v[130:133], v[184:187], v[126:129]
	v_mfma_f32_16x16x32_bf16 v[122:125], v[138:141], v[184:187], v[122:125]
	v_mfma_f32_16x16x32_bf16 v[110:113], v[130:133], v[192:195], v[110:113]
	v_mfma_f32_16x16x32_bf16 v[106:109], v[138:141], v[192:195], v[106:109]
	v_mfma_f32_16x16x32_bf16 v[94:97], v[130:133], v[200:203], v[94:97]
	v_mfma_f32_16x16x32_bf16 v[90:93], v[138:141], v[200:203], v[90:93]
	v_mfma_f32_16x16x32_bf16 v[78:81], v[130:133], v[208:211], v[78:81]
	v_mfma_f32_16x16x32_bf16 v[74:77], v[138:141], v[208:211], v[74:77]
	v_mfma_f32_16x16x32_bf16 v[126:129], v[134:137], v[188:191], v[126:129]
	v_mfma_f32_16x16x32_bf16 v[122:125], v[158:161], v[188:191], v[122:125]
	v_mfma_f32_16x16x32_bf16 v[110:113], v[134:137], v[196:199], v[110:113]
	v_mfma_f32_16x16x32_bf16 v[106:109], v[158:161], v[196:199], v[106:109]
	v_mfma_f32_16x16x32_bf16 v[94:97], v[134:137], v[204:207], v[94:97]
	v_mfma_f32_16x16x32_bf16 v[90:93], v[158:161], v[204:207], v[90:93]
	v_mfma_f32_16x16x32_bf16 v[78:81], v[134:137], v[212:215], v[78:81]
	v_mfma_f32_16x16x32_bf16 v[74:77], v[158:161], v[212:215], v[74:77]
	v_mfma_f32_16x16x32_bf16 v[118:121], v[162:165], v[184:187], v[118:121]
	v_mfma_f32_16x16x32_bf16 v[114:117], v[176:179], v[184:187], v[114:117]
	v_mfma_f32_16x16x32_bf16 v[102:105], v[162:165], v[192:195], v[102:105]
	v_mfma_f32_16x16x32_bf16 v[98:101], v[176:179], v[192:195], v[98:101]
	v_mfma_f32_16x16x32_bf16 v[86:89], v[162:165], v[200:203], v[86:89]
	v_mfma_f32_16x16x32_bf16 v[82:85], v[176:179], v[200:203], v[82:85]
	v_mfma_f32_16x16x32_bf16 v[70:73], v[162:165], v[208:211], v[70:73]
	v_mfma_f32_16x16x32_bf16 v[66:69], v[176:179], v[208:211], v[66:69]
	v_mfma_f32_16x16x32_bf16 v[118:121], v[172:175], v[188:191], v[118:121]
	v_mfma_f32_16x16x32_bf16 v[114:117], v[180:183], v[188:191], v[114:117]
	v_mfma_f32_16x16x32_bf16 v[102:105], v[172:175], v[196:199], v[102:105]
	v_mfma_f32_16x16x32_bf16 v[98:101], v[180:183], v[196:199], v[98:101]
	v_mfma_f32_16x16x32_bf16 v[86:89], v[172:175], v[204:207], v[86:89]
	v_mfma_f32_16x16x32_bf16 v[82:85], v[180:183], v[204:207], v[82:85]
	v_mfma_f32_16x16x32_bf16 v[70:73], v[172:175], v[212:215], v[70:73]
	v_mfma_f32_16x16x32_bf16 v[66:69], v[180:183], v[212:215], v[66:69]
	s_barrier
	s_add_i32 s28, s50, s34
	s_mov_b32 m0, s28
	ds_read_b128 v[184:187], v170 offset:49152
	ds_read_b128 v[188:191], v170 offset:50176
	ds_read_b128 v[192:195], v170 offset:51200
	ds_read_b128 v[196:199], v170 offset:52224
	ds_read_b128 v[200:203], v170 offset:53248
	ds_read_b128 v[204:207], v170 offset:54272
	ds_read_b128 v[208:211], v170 offset:55296
	ds_read_b128 v[212:215], v170 offset:56320
	global_load_lds_dwordx4 v144, s[98:99]
	s_add_i32 m0, s28, 0x2000
	s_add_u32 s26, s26, 0x20080
	s_addc_u32 s27, s27, 0
	s_add_i32 s28, s51, s34
	global_load_lds_dwordx4 v148, s[98:99]
	s_mov_b32 m0, s28
	s_nop 0
	global_load_lds_dwordx4 v144, s[26:27]
	s_add_i32 m0, s28, 0x2000
	s_nop 0
	global_load_lds_dwordx4 v148, s[26:27]
	s_mov_b32 m0, s39
	s_nop 0
	global_load_lds_dwordx4 v142, s[100:101]
	s_mov_b32 m0, s40
	s_nop 0
	global_load_lds_dwordx4 v146, s[100:101]
	s_waitcnt vmcnt(8)
	s_waitcnt lgkmcnt(0)
	s_barrier
	v_mfma_f32_16x16x32_bf16 v[62:65], v[130:133], v[184:187], v[62:65]
	v_mfma_f32_16x16x32_bf16 v[58:61], v[138:141], v[184:187], v[58:61]
	v_mfma_f32_16x16x32_bf16 v[46:49], v[130:133], v[192:195], v[46:49]
	v_mfma_f32_16x16x32_bf16 v[42:45], v[138:141], v[192:195], v[42:45]
	v_mfma_f32_16x16x32_bf16 v[30:33], v[130:133], v[200:203], v[30:33]
	v_mfma_f32_16x16x32_bf16 v[26:29], v[138:141], v[200:203], v[26:29]
	v_mfma_f32_16x16x32_bf16 v[14:17], v[130:133], v[208:211], v[14:17]
	v_mfma_f32_16x16x32_bf16 v[10:13], v[138:141], v[208:211], v[10:13]
	v_mfma_f32_16x16x32_bf16 v[62:65], v[134:137], v[188:191], v[62:65]
	v_mfma_f32_16x16x32_bf16 v[58:61], v[158:161], v[188:191], v[58:61]
	v_mfma_f32_16x16x32_bf16 v[46:49], v[134:137], v[196:199], v[46:49]
	v_mfma_f32_16x16x32_bf16 v[42:45], v[158:161], v[196:199], v[42:45]
	v_mfma_f32_16x16x32_bf16 v[30:33], v[134:137], v[204:207], v[30:33]
	v_mfma_f32_16x16x32_bf16 v[26:29], v[158:161], v[204:207], v[26:29]
	v_mfma_f32_16x16x32_bf16 v[14:17], v[134:137], v[212:215], v[14:17]
	v_mfma_f32_16x16x32_bf16 v[10:13], v[158:161], v[212:215], v[10:13]
	v_mfma_f32_16x16x32_bf16 v[54:57], v[162:165], v[184:187], v[54:57]
	v_mfma_f32_16x16x32_bf16 v[50:53], v[176:179], v[184:187], v[50:53]
	v_mfma_f32_16x16x32_bf16 v[38:41], v[162:165], v[192:195], v[38:41]
	v_mfma_f32_16x16x32_bf16 v[34:37], v[176:179], v[192:195], v[34:37]
	v_mfma_f32_16x16x32_bf16 v[22:25], v[162:165], v[200:203], v[22:25]
	v_mfma_f32_16x16x32_bf16 v[18:21], v[176:179], v[200:203], v[18:21]
	v_mfma_f32_16x16x32_bf16 v[6:9], v[162:165], v[208:211], v[6:9]
	v_mfma_f32_16x16x32_bf16 v[2:5], v[176:179], v[208:211], v[2:5]
	v_mfma_f32_16x16x32_bf16 v[54:57], v[172:175], v[188:191], v[54:57]
	v_mfma_f32_16x16x32_bf16 v[50:53], v[180:183], v[188:191], v[50:53]
	v_mfma_f32_16x16x32_bf16 v[38:41], v[172:175], v[196:199], v[38:41]
	v_mfma_f32_16x16x32_bf16 v[34:37], v[180:183], v[196:199], v[34:37]
	v_mfma_f32_16x16x32_bf16 v[22:25], v[172:175], v[204:207], v[22:25]
	v_mfma_f32_16x16x32_bf16 v[18:21], v[180:183], v[204:207], v[18:21]
	v_mfma_f32_16x16x32_bf16 v[6:9], v[172:175], v[212:215], v[6:9]
	v_mfma_f32_16x16x32_bf16 v[2:5], v[180:183], v[212:215], v[2:5]
	s_barrier
	s_add_i32 s49, s49, 2
	s_add_u32 s24, s24, 0x100
	s_addc_u32 s25, s25, 0
	s_add_u32 s47, s47, 0x100
	s_addc_u32 s48, s48, 0
	s_cmp_gt_u32 s49, 5
	s_cbranch_scc0 .LBB0_1086
	s_and_b64 vcc, exec, s[12:13]
	s_cbranch_vccz .LBB0_1089
	s_barrier

; #define PG8_STAGE(bufoff, gbase, voff) do { _Pragma("unroll") for (int _i = 0; _i < 2; ++_i) \
;         __builtin_amdgcn_global_load_lds((const unsigned*)((const char*)(gbase) + (voff)[_i]), (PG8_LAS unsigned*)(lds + (bufoff) + ldsw + _i * 8192), 16, 0, 0); } while (0)
; #define PG8_LDA(dst, b, h) do { _Pragma("unroll") for (int m = 0; m < 4; ++m) _Pragma("unroll") for (int k = 0; k < 2; ++k) dst[m][k] = *(const PG8_LAS bf16x8*)(lds + PG8_SA(b, h) + aoff + m * 2048 + k * 1024); } while (0)
; #define PG8_LDB(dst, b, h) do { _Pragma("unroll") for (int n = 0; n < 2; ++n) _Pragma("unroll") for (int k = 0; k < 2; ++k) dst[n][k] = *(const PG8_LAS bf16x8*)(lds + PG8_SB(b, h) + boff + n * 2048 + k * 1024); } while (0)
; #define PG8_MMA(ai, bj, At, Bt) do { __builtin_amdgcn_s_setprio(1); _Pragma("unroll") for (int m = 0; m < 4; ++m) _Pragma("unroll") for (int n = 0; n < 2; ++n) _Pragma("unroll") for (int k = 0; k < 2; ++k) \
;         acc[ai][bj][m][n] = __builtin_amdgcn_mfma_f32_16x16x32_bf16(Bt[n][k], At[m][k], acc[ai][bj][m][n], 0, 0, 0); __builtin_amdgcn_s_setprio(0); } while (0)
; #define PG8_WAIT_V(n) asm volatile("s_waitcnt vmcnt(" #n ")" ::: "memory")
; #define PG8_WAIT_L(n) asm volatile("s_waitcnt lgkmcnt(" #n ")" ::: "memory")
; template <class Epi, class Sched, bool ALIGN_EPI = false, bool SP2 = false>
; __device__ __forceinline__ void gemm_phase(PG8_LAS unsigned char* lds, const Gemm g, const Sched& S, const Epi& E) {
;     ...
;             const bool last = (t == nt - 2);
;             const char* a1 = cA + (size_t)(t + 1) * kstep;
;             const char* a2 = last ? nA : cA + (size_t)(t + 2) * kstep; const char* b2 = last ? nB : cB + (size_t)(t + 2) * kstep;
;             const char* a3 = a2 + kstep; const char* b3 = b2 + kstep;
;             if (last && has_next) S.a_ready(nxt);
;             if constexpr (SP2) {
;             PG8_LDB(B0, 0, 0); PG8_LDB(B1, 0, 1); PG8_SCHED; PG8_LDA(At, 0, 0); PG8_STAGE(PG8_SA(1, 1), a1 + hstepA, voffA);
;             PG8_WAIT_V(8); PG8_WAIT_L(0); PG8_BAR; PG8_MMA(0, 0, At, B0); PG8_MMA(0, 1, At, B1); PG8_BAR; PG8_SCHED;
;             PG8_LDA(At, 0, 1); PG8_STAGE(PG8_SB(0, 0), b2, voffB); PG8_STAGE(PG8_SB(0, 1), b2 + hstepB, voffB); PG8_STAGE(PG8_SA(0, 0), a2, voffA);
;             PG8_WAIT_V(8); PG8_WAIT_L(0); PG8_BAR; PG8_MMA(1, 0, At, B0); PG8_MMA(1, 1, At, B1); PG8_BAR; PG8_SCHED;
.LBB0_1269:
	v_add_u32_e32 v24, s56, v22
	ds_read_b128 v[50:53], v24
	ds_read_b128 v[54:57], v24 offset:1024
	ds_read_b128 v[70:73], v24 offset:2048
	ds_read_b128 v[74:77], v24 offset:3072
	v_add_u32_e32 v24, s57, v22
	s_add_u32 s36, s20, s34
	ds_read_b128 v[78:81], v24
	ds_read_b128 v[90:93], v24 offset:1024
	ds_read_b128 v[94:97], v24 offset:2048
	ds_read_b128 v[154:157], v24 offset:3072
	s_addc_u32 s37, s21, s35
	s_add_u32 s36, s36, 0x100
	s_addc_u32 s37, s37, 0
	s_add_u32 s64, s59, s34
	s_addc_u32 s65, s60, s35
	s_cmpk_eq_i32 s34, 0x700
	s_cselect_b32 s39, s27, s37
	s_cselect_b32 s38, s61, s36
	s_cselect_b32 s37, s25, s65
	s_cselect_b32 s36, s62, s64
	v_lshl_add_u64 v[24:25], v[18:19], 0, s[34:35]
	s_add_i32 m0, s48, 0xc000
	ds_read_b128 v[158:161], v23
	ds_read_b128 v[178:181], v23 offset:1024
	ds_read_b128 v[194:197], v23 offset:2048
	ds_read_b128 v[198:201], v23 offset:3072
	ds_read_b128 v[202:205], v23 offset:4096
	ds_read_b128 v[206:209], v23 offset:5120
	ds_read_b128 v[210:213], v23 offset:6144
	ds_read_b128 v[214:217], v23 offset:7168
	global_load_lds_dwordx4 v[24:25], off
	v_lshl_add_u64 v[24:25], v[20:21], 0, s[34:35]
	s_add_i32 m0, s48, 0xe000
	s_nop 0
	global_load_lds_dwordx4 v[24:25], off
	s_waitcnt vmcnt(8)
	s_waitcnt lgkmcnt(0)
	s_barrier
	v_mfma_f32_16x16x32_bf16 v[62:65], v[50:53], v[158:161], v[62:65]
	v_mfma_f32_16x16x32_bf16 v[170:173], v[70:73], v[158:161], v[170:173]
	v_mfma_f32_16x16x32_bf16 v[166:169], v[50:53], v[194:197], v[166:169]
	v_mfma_f32_16x16x32_bf16 v[162:165], v[70:73], v[194:197], v[162:165]
	v_mfma_f32_16x16x32_bf16 v[174:177], v[50:53], v[202:205], v[174:177]
	v_mfma_f32_16x16x32_bf16 v[190:193], v[70:73], v[202:205], v[190:193]
	v_mfma_f32_16x16x32_bf16 v[186:189], v[50:53], v[210:213], v[186:189]
	v_mfma_f32_16x16x32_bf16 v[182:185], v[70:73], v[210:213], v[182:185]
	v_mfma_f32_16x16x32_bf16 v[62:65], v[54:57], v[178:181], v[62:65]
	v_mfma_f32_16x16x32_bf16 v[170:173], v[74:77], v[178:181], v[170:173]
	v_mfma_f32_16x16x32_bf16 v[166:169], v[54:57], v[198:201], v[166:169]
	v_mfma_f32_16x16x32_bf16 v[162:165], v[74:77], v[198:201], v[162:165]
	v_mfma_f32_16x16x32_bf16 v[174:177], v[54:57], v[206:209], v[174:177]
	v_mfma_f32_16x16x32_bf16 v[190:193], v[74:77], v[206:209], v[190:193]
	v_mfma_f32_16x16x32_bf16 v[186:189], v[54:57], v[214:217], v[186:189]
	v_mfma_f32_16x16x32_bf16 v[182:185], v[74:77], v[214:217], v[182:185]
	v_mfma_f32_16x16x32_bf16 v[86:89], v[78:81], v[158:161], v[86:89]
	v_mfma_f32_16x16x32_bf16 v[82:85], v[94:97], v[158:161], v[82:85]
	v_mfma_f32_16x16x32_bf16 v[66:69], v[78:81], v[194:197], v[66:69]
	v_mfma_f32_16x16x32_bf16 v[58:61], v[94:97], v[194:197], v[58:61]
	v_mfma_f32_16x16x32_bf16 v[114:117], v[78:81], v[202:205], v[114:117]
	v_mfma_f32_16x16x32_bf16 v[110:113], v[94:97], v[202:205], v[110:113]
	v_mfma_f32_16x16x32_bf16 v[106:109], v[78:81], v[210:213], v[106:109]
	v_mfma_f32_16x16x32_bf16 v[102:105], v[94:97], v[210:213], v[102:105]
	v_mfma_f32_16x16x32_bf16 v[86:89], v[90:93], v[178:181], v[86:89]
	v_mfma_f32_16x16x32_bf16 v[82:85], v[154:157], v[178:181], v[82:85]
	v_mfma_f32_16x16x32_bf16 v[66:69], v[90:93], v[198:201], v[66:69]
	v_mfma_f32_16x16x32_bf16 v[58:61], v[154:157], v[198:201], v[58:61]
	v_mfma_f32_16x16x32_bf16 v[114:117], v[90:93], v[206:209], v[114:117]
	v_mfma_f32_16x16x32_bf16 v[110:113], v[154:157], v[206:209], v[110:113]
	v_mfma_f32_16x16x32_bf16 v[106:109], v[90:93], v[214:217], v[106:109]
	v_mfma_f32_16x16x32_bf16 v[102:105], v[154:157], v[214:217], v[102:105]
	s_barrier
	s_add_i32 s64, s56, s47
	s_add_u32 s98, s36, 0x80
	s_addc_u32 s99, s37, 0
	s_mov_b32 m0, s64
	ds_read_b128 v[158:161], v23 offset:16384
	ds_read_b128 v[178:181], v23 offset:17408
	ds_read_b128 v[194:197], v23 offset:18432
	ds_read_b128 v[198:201], v23 offset:19456
	ds_read_b128 v[202:205], v23 offset:20480
	ds_read_b128 v[206:209], v23 offset:21504
	ds_read_b128 v[210:213], v23 offset:22528
	ds_read_b128 v[214:217], v23 offset:23552
	global_load_lds_dwordx4 v4, s[36:37]
	s_add_i32 m0, s64, 0x2000
	s_add_u32 s64, s36, 0x40000
	s_addc_u32 s65, s37, 0
	s_add_i32 s66, s57, s47
	global_load_lds_dwordx4 v8, s[36:37]
	s_mov_b32 m0, s66
	s_add_u32 s100, s38, 0x80
	s_addc_u32 s101, s39, 0
	global_load_lds_dwordx4 v4, s[64:65]
	s_add_i32 m0, s66, 0x2000
	s_nop 0
	global_load_lds_dwordx4 v8, s[64:65]
	s_mov_b32 m0, s48
	s_nop 0
	global_load_lds_dwordx4 v2, s[38:39]
	s_mov_b32 m0, s49
	s_nop 0
	global_load_lds_dwordx4 v6, s[38:39]
	s_waitcnt vmcnt(8)
	s_waitcnt lgkmcnt(0)
	s_barrier
	v_mfma_f32_16x16x32_bf16 v[150:153], v[50:53], v[158:161], v[150:153]
	v_mfma_f32_16x16x32_bf16 v[146:149], v[70:73], v[158:161], v[146:149]
	v_mfma_f32_16x16x32_bf16 v[142:145], v[50:53], v[194:197], v[142:145]
	v_mfma_f32_16x16x32_bf16 v[138:141], v[70:73], v[194:197], v[138:141]
	v_mfma_f32_16x16x32_bf16 v[126:129], v[50:53], v[202:205], v[126:129]
	v_mfma_f32_16x16x32_bf16 v[98:101], v[70:73], v[202:205], v[98:101]
	v_mfma_f32_16x16x32_bf16 v[46:49], v[50:53], v[210:213], v[46:49]
	v_mfma_f32_16x16x32_bf16 v[42:45], v[70:73], v[210:213], v[42:45]
	v_mfma_f32_16x16x32_bf16 v[150:153], v[54:57], v[178:181], v[150:153]
	v_mfma_f32_16x16x32_bf16 v[146:149], v[74:77], v[178:181], v[146:149]
	v_mfma_f32_16x16x32_bf16 v[142:145], v[54:57], v[198:201], v[142:145]
	v_mfma_f32_16x16x32_bf16 v[138:141], v[74:77], v[198:201], v[138:141]
	v_mfma_f32_16x16x32_bf16 v[126:129], v[54:57], v[206:209], v[126:129]
	v_mfma_f32_16x16x32_bf16 v[98:101], v[74:77], v[206:209], v[98:101]
	v_mfma_f32_16x16x32_bf16 v[46:49], v[54:57], v[214:217], v[46:49]
	v_mfma_f32_16x16x32_bf16 v[42:45], v[74:77], v[214:217], v[42:45]
	v_mfma_f32_16x16x32_bf16 v[38:41], v[78:81], v[202:205], v[38:41]
	v_mfma_f32_16x16x32_bf16 v[34:37], v[94:97], v[202:205], v[34:37]
	v_mfma_f32_16x16x32_bf16 v[30:33], v[78:81], v[210:213], v[30:33]
	v_mfma_f32_16x16x32_bf16 v[24:27], v[94:97], v[210:213], v[26:29]
	v_mfma_f32_16x16x32_bf16 v[50:53], v[78:81], v[158:161], v[134:137]
	v_mfma_f32_16x16x32_bf16 v[54:57], v[94:97], v[158:161], v[130:133]
	v_mfma_f32_16x16x32_bf16 v[70:73], v[78:81], v[194:197], v[122:125]
	v_mfma_f32_16x16x32_bf16 v[74:77], v[94:97], v[194:197], v[118:121]
	v_mfma_f32_16x16x32_bf16 v[38:41], v[90:93], v[206:209], v[38:41]
	v_mfma_f32_16x16x32_bf16 v[34:37], v[154:157], v[206:209], v[34:37]
	v_mfma_f32_16x16x32_bf16 v[30:33], v[90:93], v[214:217], v[30:33]
	v_mfma_f32_16x16x32_bf16 v[24:27], v[154:157], v[214:217], v[24:27]
	v_mfma_f32_16x16x32_bf16 v[50:53], v[90:93], v[178:181], v[50:53]
	v_mfma_f32_16x16x32_bf16 v[54:57], v[154:157], v[178:181], v[54:57]
	v_mfma_f32_16x16x32_bf16 v[70:73], v[90:93], v[198:201], v[70:73]
	v_mfma_f32_16x16x32_bf16 v[74:77], v[154:157], v[198:201], v[74:77]
	s_barrier
; #define PG8_STAGE(bufoff, gbase, voff) do { _Pragma("unroll") for (int _i = 0; _i < 2; ++_i) \
;         __builtin_amdgcn_global_load_lds((const unsigned*)((const char*)(gbase) + (voff)[_i]), (PG8_LAS unsigned*)(lds + (bufoff) + ldsw + _i * 8192), 16, 0, 0); } while (0)
; #define PG8_LDA(dst, b, h) do { _Pragma("unroll") for (int m = 0; m < 4; ++m) _Pragma("unroll") for (int k = 0; k < 2; ++k) dst[m][k] = *(const PG8_LAS bf16x8*)(lds + PG8_SA(b, h) + aoff + m * 2048 + k * 1024); } while (0)
; #define PG8_LDB(dst, b, h) do { _Pragma("unroll") for (int n = 0; n < 2; ++n) _Pragma("unroll") for (int k = 0; k < 2; ++k) dst[n][k] = *(const PG8_LAS bf16x8*)(lds + PG8_SB(b, h) + boff + n * 2048 + k * 1024); } while (0)
; #define PG8_MMA(ai, bj, At, Bt) do { __builtin_amdgcn_s_setprio(1); _Pragma("unroll") for (int m = 0; m < 4; ++m) _Pragma("unroll") for (int n = 0; n < 2; ++n) _Pragma("unroll") for (int k = 0; k < 2; ++k) \
;         acc[ai][bj][m][n] = __builtin_amdgcn_mfma_f32_16x16x32_bf16(Bt[n][k], At[m][k], acc[ai][bj][m][n], 0, 0, 0); __builtin_amdgcn_s_setprio(0); } while (0)
; #define PG8_WAIT_V(n) asm volatile("s_waitcnt vmcnt(" #n ")" ::: "memory")
; #define PG8_WAIT_L(n) asm volatile("s_waitcnt lgkmcnt(" #n ")" ::: "memory")
; #define PG8_BAR __builtin_amdgcn_s_barrier()
; #define PG8_SCHED __builtin_amdgcn_sched_barrier(0)
; template <class Epi, class Sched, bool ALIGN_EPI = false, bool SP2 = false>
; __device__ __forceinline__ void gemm_phase(PG8_LAS unsigned char* lds, const Gemm g, const Sched& S, const Epi& E) {
;     ...
;             PG8_WAIT_V(8); PG8_WAIT_L(0); PG8_BAR; PG8_MMA(1, 0, At, B0); PG8_MMA(1, 1, At, B1); PG8_BAR; PG8_SCHED;
;             PG8_LDB(B0, 1, 0); PG8_LDB(B1, 1, 1); PG8_SCHED; PG8_LDA(At, 1, 0); PG8_STAGE(PG8_SA(0, 1), a2 + hstepA, voffA);
;             PG8_WAIT_V(8); PG8_WAIT_L(0); PG8_BAR; PG8_MMA(0, 0, At, B0); PG8_MMA(0, 1, At, B1); PG8_BAR; PG8_SCHED;
;             PG8_LDA(At, 1, 1); PG8_STAGE(PG8_SB(1, 0), b3, voffB); PG8_STAGE(PG8_SB(1, 1), b3 + hstepB, voffB); PG8_STAGE(PG8_SA(1, 0), a3, voffA);
	s_add_i32 s64, 0, 0x18000
	v_add_u32_e32 v28, s64, v22
	s_add_i32 s65, 0, 0x1c000
	ds_read_b128 v[78:81], v28
	ds_read_b128 v[90:93], v28 offset:1024
	ds_read_b128 v[94:97], v28 offset:2048
	ds_read_b128 v[118:121], v28 offset:3072
	v_add_u32_e32 v28, s65, v22
	ds_read_b128 v[154:157], v28
	ds_read_b128 v[158:161], v28 offset:1024
	ds_read_b128 v[178:181], v28 offset:2048
	ds_read_b128 v[194:197], v28 offset:3072
	s_add_u32 s38, s38, 0x40000
	s_addc_u32 s39, s39, 0
	s_mov_b32 m0, s51
	ds_read_b128 v[122:125], v23 offset:32768
	ds_read_b128 v[130:133], v23 offset:33792
	ds_read_b128 v[134:137], v23 offset:34816
	ds_read_b128 v[198:201], v23 offset:35840
	ds_read_b128 v[202:205], v23 offset:36864
	ds_read_b128 v[206:209], v23 offset:37888
	ds_read_b128 v[210:213], v23 offset:38912
	ds_read_b128 v[214:217], v23 offset:39936
	global_load_lds_dwordx4 v2, s[38:39]
	s_mov_b32 m0, s52
	s_nop 0
	global_load_lds_dwordx4 v6, s[38:39]
	s_waitcnt vmcnt(8)
	s_waitcnt lgkmcnt(0)
	s_barrier
	v_mfma_f32_16x16x32_bf16 v[62:65], v[78:81], v[122:125], v[62:65]
	v_mfma_f32_16x16x32_bf16 v[170:173], v[94:97], v[122:125], v[170:173]
	v_mfma_f32_16x16x32_bf16 v[166:169], v[78:81], v[134:137], v[166:169]
	v_mfma_f32_16x16x32_bf16 v[162:165], v[94:97], v[134:137], v[162:165]
	v_mfma_f32_16x16x32_bf16 v[174:177], v[78:81], v[202:205], v[174:177]
	v_mfma_f32_16x16x32_bf16 v[190:193], v[94:97], v[202:205], v[190:193]
	v_mfma_f32_16x16x32_bf16 v[186:189], v[78:81], v[210:213], v[186:189]
	v_mfma_f32_16x16x32_bf16 v[182:185], v[94:97], v[210:213], v[182:185]
	v_mfma_f32_16x16x32_bf16 v[62:65], v[90:93], v[130:133], v[62:65]
	v_mfma_f32_16x16x32_bf16 v[170:173], v[118:121], v[130:133], v[170:173]
	v_mfma_f32_16x16x32_bf16 v[166:169], v[90:93], v[198:201], v[166:169]
	v_mfma_f32_16x16x32_bf16 v[162:165], v[118:121], v[198:201], v[162:165]
	v_mfma_f32_16x16x32_bf16 v[174:177], v[90:93], v[206:209], v[174:177]
	v_mfma_f32_16x16x32_bf16 v[190:193], v[118:121], v[206:209], v[190:193]
	v_mfma_f32_16x16x32_bf16 v[186:189], v[90:93], v[214:217], v[186:189]
	v_mfma_f32_16x16x32_bf16 v[182:185], v[118:121], v[214:217], v[182:185]
	v_mfma_f32_16x16x32_bf16 v[86:89], v[154:157], v[122:125], v[86:89]
	v_mfma_f32_16x16x32_bf16 v[82:85], v[178:181], v[122:125], v[82:85]
	v_mfma_f32_16x16x32_bf16 v[66:69], v[154:157], v[134:137], v[66:69]
	v_mfma_f32_16x16x32_bf16 v[58:61], v[178:181], v[134:137], v[58:61]
	v_mfma_f32_16x16x32_bf16 v[114:117], v[154:157], v[202:205], v[114:117]
	v_mfma_f32_16x16x32_bf16 v[110:113], v[178:181], v[202:205], v[110:113]
	v_mfma_f32_16x16x32_bf16 v[106:109], v[154:157], v[210:213], v[106:109]
	v_mfma_f32_16x16x32_bf16 v[102:105], v[178:181], v[210:213], v[102:105]
	v_mfma_f32_16x16x32_bf16 v[86:89], v[158:161], v[130:133], v[86:89]
	v_mfma_f32_16x16x32_bf16 v[82:85], v[194:197], v[130:133], v[82:85]
	v_mfma_f32_16x16x32_bf16 v[66:69], v[158:161], v[198:201], v[66:69]
	v_mfma_f32_16x16x32_bf16 v[58:61], v[194:197], v[198:201], v[58:61]
	v_mfma_f32_16x16x32_bf16 v[114:117], v[158:161], v[206:209], v[114:117]
	v_mfma_f32_16x16x32_bf16 v[110:113], v[194:197], v[206:209], v[110:113]
	v_mfma_f32_16x16x32_bf16 v[106:109], v[158:161], v[214:217], v[106:109]
	v_mfma_f32_16x16x32_bf16 v[102:105], v[194:197], v[214:217], v[102:105]
	s_barrier
	s_add_i32 s38, s64, s47
	s_mov_b32 m0, s38
	ds_read_b128 v[122:125], v23 offset:49152
	ds_read_b128 v[130:133], v23 offset:50176
	ds_read_b128 v[198:201], v23 offset:51200
	ds_read_b128 v[202:205], v23 offset:52224
	ds_read_b128 v[206:209], v23 offset:53248
	ds_read_b128 v[210:213], v23 offset:54272
	ds_read_b128 v[214:217], v23 offset:55296
	ds_read_b128 v[218:221], v23 offset:56320
	global_load_lds_dwordx4 v4, s[98:99]
	s_add_i32 m0, s38, 0x2000
	s_add_u32 s36, s36, 0x40080
	s_addc_u32 s37, s37, 0
	s_add_i32 s38, s65, s47
	global_load_lds_dwordx4 v8, s[98:99]
	s_mov_b32 m0, s38
	s_nop 0
	global_load_lds_dwordx4 v4, s[36:37]
	s_add_i32 m0, s38, 0x2000
	s_nop 0
	global_load_lds_dwordx4 v8, s[36:37]
	s_mov_b32 m0, s54
	s_nop 0
	global_load_lds_dwordx4 v2, s[100:101]
	s_mov_b32 m0, s55
	s_nop 0
	global_load_lds_dwordx4 v6, s[100:101]
	s_waitcnt vmcnt(8)
	s_waitcnt lgkmcnt(0)
	s_barrier
; #define PG8_MMA(ai, bj, At, Bt) do { __builtin_amdgcn_s_setprio(1); _Pragma("unroll") for (int m = 0; m < 4; ++m) _Pragma("unroll") for (int n = 0; n < 2; ++n) _Pragma("unroll") for (int k = 0; k < 2; ++k) \
;         acc[ai][bj][m][n] = __builtin_amdgcn_mfma_f32_16x16x32_bf16(Bt[n][k], At[m][k], acc[ai][bj][m][n], 0, 0, 0); __builtin_amdgcn_s_setprio(0); } while (0)
; #define PG8_WAIT_V(n) asm volatile("s_waitcnt vmcnt(" #n ")" ::: "memory")
; #define PG8_WAIT_L(n) asm volatile("s_waitcnt lgkmcnt(" #n ")" ::: "memory")
; #define PG8_BAR __builtin_amdgcn_s_barrier()
; #define PG8_SCHED __builtin_amdgcn_sched_barrier(0)
; template <class Epi, class Sched, bool ALIGN_EPI = false, bool SP2 = false>
; __device__ __forceinline__ void gemm_phase(PG8_LAS unsigned char* lds, const Gemm g, const Sched& S, const Epi& E) {
;     ...
;             PG8_WAIT_V(8); PG8_WAIT_L(0); PG8_BAR; PG8_MMA(1, 0, At, B0); PG8_MMA(1, 1, At, B1); PG8_BAR; PG8_SCHED;
;     ...
;         }
;         if constexpr (ALIGN_EPI) { if (wr == 0) PG8_BAR; }
;         if constexpr (!Epi::AFTER_DRAIN) { E(acc, cur, wr, wc, fr, fq); S.done(cur); }
;         if (!has_next) break;
; #pragma unroll
;         for (int a = 0; a < 2; ++a)
; #pragma unroll
;             for (int b = 0; b < 2; ++b)
; #pragma unroll
;                 for (int m = 0; m < 4; ++m)
; #pragma unroll
;                     for (int n = 0; n < 2; ++n) acc[a][b][m][n] = (f32x4){0.f, 0.f, 0.f, 0.f};
	v_mfma_f32_16x16x32_bf16 v[134:137], v[78:81], v[122:125], v[150:153]
	v_mfma_f32_16x16x32_bf16 v[150:153], v[90:93], v[130:133], v[134:137]
	v_mfma_f32_16x16x32_bf16 v[134:137], v[94:97], v[122:125], v[146:149]
	v_mfma_f32_16x16x32_bf16 v[146:149], v[118:121], v[130:133], v[134:137]
	v_mfma_f32_16x16x32_bf16 v[134:137], v[78:81], v[198:201], v[142:145]
	v_mfma_f32_16x16x32_bf16 v[142:145], v[90:93], v[202:205], v[134:137]
	v_mfma_f32_16x16x32_bf16 v[134:137], v[94:97], v[198:201], v[138:141]
	v_mfma_f32_16x16x32_bf16 v[126:129], v[78:81], v[206:209], v[126:129]
	v_mfma_f32_16x16x32_bf16 v[98:101], v[94:97], v[206:209], v[98:101]
	v_mfma_f32_16x16x32_bf16 v[46:49], v[78:81], v[214:217], v[46:49]
	v_mfma_f32_16x16x32_bf16 v[42:45], v[94:97], v[214:217], v[42:45]
	v_mfma_f32_16x16x32_bf16 v[138:141], v[118:121], v[202:205], v[134:137]
	v_mfma_f32_16x16x32_bf16 v[126:129], v[90:93], v[210:213], v[126:129]
	v_mfma_f32_16x16x32_bf16 v[98:101], v[118:121], v[210:213], v[98:101]
	v_mfma_f32_16x16x32_bf16 v[46:49], v[90:93], v[218:221], v[46:49]
	v_mfma_f32_16x16x32_bf16 v[42:45], v[118:121], v[218:221], v[42:45]
	v_mfma_f32_16x16x32_bf16 v[50:53], v[154:157], v[122:125], v[50:53]
	v_mfma_f32_16x16x32_bf16 v[134:137], v[158:161], v[130:133], v[50:53]
	v_mfma_f32_16x16x32_bf16 v[50:53], v[178:181], v[122:125], v[54:57]
	v_mfma_f32_16x16x32_bf16 v[130:133], v[194:197], v[130:133], v[50:53]
	v_mfma_f32_16x16x32_bf16 v[50:53], v[154:157], v[198:201], v[70:73]
	v_mfma_f32_16x16x32_bf16 v[122:125], v[158:161], v[202:205], v[50:53]
	v_mfma_f32_16x16x32_bf16 v[50:53], v[178:181], v[198:201], v[74:77]
	v_mfma_f32_16x16x32_bf16 v[38:41], v[154:157], v[206:209], v[38:41]
	v_mfma_f32_16x16x32_bf16 v[34:37], v[178:181], v[206:209], v[34:37]
	v_mfma_f32_16x16x32_bf16 v[28:31], v[154:157], v[214:217], v[30:33]
	v_mfma_f32_16x16x32_bf16 v[24:27], v[178:181], v[214:217], v[24:27]
	v_mfma_f32_16x16x32_bf16 v[118:121], v[194:197], v[202:205], v[50:53]
	v_mfma_f32_16x16x32_bf16 v[38:41], v[158:161], v[210:213], v[38:41]
	v_mfma_f32_16x16x32_bf16 v[34:37], v[194:197], v[210:213], v[34:37]
	v_mfma_f32_16x16x32_bf16 v[30:33], v[158:161], v[218:221], v[28:31]
	v_mfma_f32_16x16x32_bf16 v[26:29], v[194:197], v[218:221], v[24:27]
	s_barrier
	s_add_i32 s63, s63, 2
	s_add_u32 s34, s34, 0x100
	s_addc_u32 s35, s35, 0
	s_cmp_gt_u32 s63, 13
	s_cbranch_scc0 .LBB0_1269
	s_add_u32 s34, s59, 0xffffff00
	s_addc_u32 s35, s60, -1
	s_andn2_b64 vcc, exec, s[4:5]
	s_cbranch_vccnz .LBB0_1260
	v_mov_b32_e32 v26, 0
	s_mov_b32 s14, s24
	s_mov_b32 s12, s26
	s_mov_b64 s[20:21], s[30:31]
	s_mov_b32 s53, s58
	v_mov_b32_e32 v27, v26
	v_mov_b32_e32 v28, v26
	v_mov_b32_e32 v29, v26
	v_mov_b32_e32 v30, v26
	v_mov_b32_e32 v31, v26
	v_mov_b32_e32 v32, v26
	v_mov_b32_e32 v33, v26
	v_mov_b32_e32 v34, v26
	v_mov_b32_e32 v35, v26
	v_mov_b32_e32 v36, v26
	v_mov_b32_e32 v37, v26
	v_mov_b32_e32 v38, v26
	v_mov_b32_e32 v39, v26
	v_mov_b32_e32 v40, v26
	v_mov_b32_e32 v41, v26
	v_mov_b32_e32 v118, v26
	v_mov_b32_e32 v119, v26
	v_mov_b32_e32 v120, v26
	v_mov_b32_e32 v121, v26
	v_mov_b32_e32 v122, v26
	v_mov_b32_e32 v123, v26
	v_mov_b32_e32 v124, v26
	v_mov_b32_e32 v125, v26
	v_mov_b32_e32 v130, v26
	v_mov_b32_e32 v131, v26
	v_mov_b32_e32 v132, v26
	v_mov_b32_e32 v133, v26
	v_mov_b32_e32 v134, v26
	v_mov_b32_e32 v135, v26
	v_mov_b32_e32 v136, v26
	v_mov_b32_e32 v137, v26
	v_mov_b32_e32 v42, v26
	v_mov_b32_e32 v43, v26
	v_mov_b32_e32 v44, v26
	v_mov_b32_e32 v45, v26
	v_mov_b32_e32 v46, v26
	v_mov_b32_e32 v47, v26
	v_mov_b32_e32 v48, v26
	v_mov_b32_e32 v49, v26
	v_mov_b32_e32 v98, v26
	v_mov_b32_e32 v99, v26
	v_mov_b32_e32 v100, v26
	v_mov_b32_e32 v101, v26
	v_mov_b32_e32 v126, v26
	v_mov_b32_e32 v127, v26
	v_mov_b32_e32 v128, v26
	v_mov_b32_e32 v129, v26
	v_mov_b32_e32 v138, v26
	v_mov_b32_e32 v139, v26
	v_mov_b32_e32 v140, v26
	v_mov_b32_e32 v141, v26
	v_mov_b32_e32 v142, v26
	v_mov_b32_e32 v143, v26
	v_mov_b32_e32 v144, v26
	v_mov_b32_e32 v145, v26
	v_mov_b32_e32 v146, v26
	v_mov_b32_e32 v147, v26
	v_mov_b32_e32 v148, v26
	v_mov_b32_e32 v149, v26
	v_mov_b32_e32 v150, v26
	v_mov_b32_e32 v151, v26
	v_mov_b32_e32 v152, v26
	v_mov_b32_e32 v153, v26
	v_mov_b32_e32 v102, v26
	v_mov_b32_e32 v103, v26
	v_mov_b32_e32 v104, v26
	v_mov_b32_e32 v105, v26
	v_mov_b32_e32 v106, v26
	v_mov_b32_e32 v107, v26
	v_mov_b32_e32 v108, v26
	v_mov_b32_e32 v109, v26
	v_mov_b32_e32 v110, v26
	v_mov_b32_e32 v111, v26
	v_mov_b32_e32 v112, v26
	v_mov_b32_e32 v113, v26
	v_mov_b32_e32 v114, v26
	v_mov_b32_e32 v115, v26
	v_mov_b32_e32 v116, v26
	v_mov_b32_e32 v117, v26
	v_mov_b32_e32 v58, v26
	v_mov_b32_e32 v59, v26
	v_mov_b32_e32 v60, v26
	v_mov_b32_e32 v61, v26
	v_mov_b32_e32 v66, v26
	v_mov_b32_e32 v67, v26
	v_mov_b32_e32 v68, v26
	v_mov_b32_e32 v69, v26
	v_mov_b32_e32 v82, v26
	v_mov_b32_e32 v83, v26
	v_mov_b32_e32 v84, v26
	v_mov_b32_e32 v85, v26
	v_mov_b32_e32 v86, v26
	v_mov_b32_e32 v87, v26
	v_mov_b32_e32 v88, v26
	v_mov_b32_e32 v89, v26
	v_mov_b32_e32 v182, v26
	v_mov_b32_e32 v183, v26
	v_mov_b32_e32 v184, v26
	v_mov_b32_e32 v185, v26
	v_mov_b32_e32 v186, v26
	v_mov_b32_e32 v187, v26
	v_mov_b32_e32 v188, v26
	v_mov_b32_e32 v189, v26
	v_mov_b32_e32 v190, v26
	v_mov_b32_e32 v191, v26
	v_mov_b32_e32 v192, v26
	v_mov_b32_e32 v193, v26
	v_mov_b32_e32 v174, v26
	v_mov_b32_e32 v175, v26
	v_mov_b32_e32 v176, v26
	v_mov_b32_e32 v177, v26
	v_mov_b32_e32 v162, v26
	v_mov_b32_e32 v163, v26
	v_mov_b32_e32 v164, v26
	v_mov_b32_e32 v165, v26
	v_mov_b32_e32 v166, v26
	v_mov_b32_e32 v167, v26
	v_mov_b32_e32 v168, v26
	v_mov_b32_e32 v169, v26
	v_mov_b32_e32 v170, v26
	v_mov_b32_e32 v171, v26
	v_mov_b32_e32 v172, v26
	v_mov_b32_e32 v173, v26
	v_mov_b32_e32 v62, v26
	v_mov_b32_e32 v63, v26
	v_mov_b32_e32 v64, v26
	v_mov_b32_e32 v65, v26
	s_andn2_b64 vcc, exec, s[2:3]
	s_cbranch_vccnz .LBB0_1261

; #define PG8_STAGE(bufoff, gbase, voff) do { _Pragma("unroll") for (int _i = 0; _i < 2; ++_i) \
;         __builtin_amdgcn_global_load_lds((const unsigned*)((const char*)(gbase) + (voff)[_i]), (PG8_LAS unsigned*)(lds + (bufoff) + ldsw + _i * 8192), 16, 0, 0); } while (0)
; #define PG8_LDA(dst, b, h) do { _Pragma("unroll") for (int m = 0; m < 4; ++m) _Pragma("unroll") for (int k = 0; k < 2; ++k) dst[m][k] = *(const PG8_LAS bf16x8*)(lds + PG8_SA(b, h) + aoff + m * 2048 + k * 1024); } while (0)
; #define PG8_LDB(dst, b, h) do { _Pragma("unroll") for (int n = 0; n < 2; ++n) _Pragma("unroll") for (int k = 0; k < 2; ++k) dst[n][k] = *(const PG8_LAS bf16x8*)(lds + PG8_SB(b, h) + boff + n * 2048 + k * 1024); } while (0)
; #define PG8_MMA(ai, bj, At, Bt) do { __builtin_amdgcn_s_setprio(1); _Pragma("unroll") for (int m = 0; m < 4; ++m) _Pragma("unroll") for (int n = 0; n < 2; ++n) _Pragma("unroll") for (int k = 0; k < 2; ++k) \
;         acc[ai][bj][m][n] = __builtin_amdgcn_mfma_f32_16x16x32_bf16(Bt[n][k], At[m][k], acc[ai][bj][m][n], 0, 0, 0); __builtin_amdgcn_s_setprio(0); } while (0)
; #define PG8_WAIT_V(n) asm volatile("s_waitcnt vmcnt(" #n ")" ::: "memory")
; #define PG8_WAIT_L(n) asm volatile("s_waitcnt lgkmcnt(" #n ")" ::: "memory")
; #define PG8_BAR __builtin_amdgcn_s_barrier()
; #define PG8_SCHED __builtin_amdgcn_sched_barrier(0)
; template <class Epi, class Sched, bool ALIGN_EPI = false, bool SP2 = false>
; __device__ __forceinline__ void gemm_phase(PG8_LAS unsigned char* lds, const Gemm g, const Sched& S, const Epi& E) {
;     ...
;             PG8_LDB(B0, 0, 0); PG8_LDB(B1, 0, 1); PG8_SCHED; PG8_LDA(At, 0, 0); PG8_STAGE(PG8_SA(1, 1), a1 + hstepA, voffA);
;             PG8_WAIT_V(8); PG8_WAIT_L(0); PG8_BAR; PG8_MMA(0, 0, At, B0); PG8_MMA(0, 1, At, B1); PG8_BAR; PG8_SCHED;
;             PG8_LDA(At, 0, 1); PG8_STAGE(PG8_SB(0, 0), b2, voffB); PG8_STAGE(PG8_SB(0, 1), b2 + hstepB, voffB); PG8_STAGE(PG8_SA(0, 0), a2, voffA);
;             PG8_WAIT_V(8); PG8_WAIT_L(0); PG8_BAR; PG8_MMA(1, 0, At, B0); PG8_MMA(1, 1, At, B1); PG8_BAR; PG8_SCHED;
.LBB0_1528:
	ds_read_b128 v[130:133], v182
	ds_read_b128 v[134:137], v182 offset:1024
	ds_read_b128 v[154:157], v182 offset:2048
	ds_read_b128 v[158:161], v182 offset:3072
	ds_read_b128 v[162:165], v183
	ds_read_b128 v[166:169], v183 offset:1024
	ds_read_b128 v[170:173], v183 offset:2048
	ds_read_b128 v[186:189], v183 offset:3072
	s_add_u32 s44, s42, 0xfffc0080
	s_addc_u32 s45, s43, -1
	s_cmp_eq_u32 s69, 12
	s_cselect_b32 s47, s31, s45
	s_cselect_b32 s46, s39, s44
	s_cselect_b32 s45, s29, s68
	s_cselect_b32 s44, s66, s67
	s_add_i32 m0, s41, 0xc000
	ds_read_b128 v[190:193], v184
	ds_read_b128 v[194:197], v184 offset:1024
	ds_read_b128 v[198:201], v184 offset:2048
	ds_read_b128 v[202:205], v184 offset:3072
	ds_read_b128 v[206:209], v184 offset:4096
	ds_read_b128 v[210:213], v184 offset:5120
	ds_read_b128 v[214:217], v184 offset:6144
	ds_read_b128 v[218:221], v184 offset:7168
	global_load_lds_dwordx4 v146, s[42:43]
	s_add_i32 m0, s41, 0xe000
	s_nop 0
	global_load_lds_dwordx4 v148, s[42:43]
	s_waitcnt vmcnt(8)
	s_waitcnt lgkmcnt(0)
	s_barrier
	v_mfma_f32_16x16x32_bf16 v[126:129], v[130:133], v[190:193], v[126:129]
	v_mfma_f32_16x16x32_bf16 v[94:97], v[154:157], v[190:193], v[94:97]
	v_mfma_f32_16x16x32_bf16 v[118:121], v[130:133], v[198:201], v[118:121]
	v_mfma_f32_16x16x32_bf16 v[86:89], v[154:157], v[198:201], v[86:89]
	v_mfma_f32_16x16x32_bf16 v[114:117], v[130:133], v[206:209], v[114:117]
	v_mfma_f32_16x16x32_bf16 v[82:85], v[154:157], v[206:209], v[82:85]
	v_mfma_f32_16x16x32_bf16 v[102:105], v[130:133], v[214:217], v[102:105]
	v_mfma_f32_16x16x32_bf16 v[70:73], v[154:157], v[214:217], v[70:73]
	v_mfma_f32_16x16x32_bf16 v[126:129], v[134:137], v[194:197], v[126:129]
	v_mfma_f32_16x16x32_bf16 v[94:97], v[158:161], v[194:197], v[94:97]
	v_mfma_f32_16x16x32_bf16 v[118:121], v[134:137], v[202:205], v[118:121]
	v_mfma_f32_16x16x32_bf16 v[86:89], v[158:161], v[202:205], v[86:89]
	v_mfma_f32_16x16x32_bf16 v[114:117], v[134:137], v[210:213], v[114:117]
	v_mfma_f32_16x16x32_bf16 v[82:85], v[158:161], v[210:213], v[82:85]
	v_mfma_f32_16x16x32_bf16 v[102:105], v[134:137], v[218:221], v[102:105]
	v_mfma_f32_16x16x32_bf16 v[70:73], v[158:161], v[218:221], v[70:73]
	v_mfma_f32_16x16x32_bf16 v[122:125], v[162:165], v[190:193], v[122:125]
	v_mfma_f32_16x16x32_bf16 v[90:93], v[170:173], v[190:193], v[90:93]
	v_mfma_f32_16x16x32_bf16 v[110:113], v[162:165], v[198:201], v[110:113]
	v_mfma_f32_16x16x32_bf16 v[78:81], v[170:173], v[198:201], v[78:81]
	v_mfma_f32_16x16x32_bf16 v[106:109], v[162:165], v[206:209], v[106:109]
	v_mfma_f32_16x16x32_bf16 v[74:77], v[170:173], v[206:209], v[74:77]
	v_mfma_f32_16x16x32_bf16 v[98:101], v[162:165], v[214:217], v[98:101]
	v_mfma_f32_16x16x32_bf16 v[66:69], v[170:173], v[214:217], v[66:69]
	v_mfma_f32_16x16x32_bf16 v[122:125], v[166:169], v[194:197], v[122:125]
	v_mfma_f32_16x16x32_bf16 v[90:93], v[186:189], v[194:197], v[90:93]
	v_mfma_f32_16x16x32_bf16 v[110:113], v[166:169], v[202:205], v[110:113]
	v_mfma_f32_16x16x32_bf16 v[78:81], v[186:189], v[202:205], v[78:81]
	v_mfma_f32_16x16x32_bf16 v[106:109], v[166:169], v[210:213], v[106:109]
	v_mfma_f32_16x16x32_bf16 v[74:77], v[186:189], v[210:213], v[74:77]
	v_mfma_f32_16x16x32_bf16 v[98:101], v[166:169], v[218:221], v[98:101]
	v_mfma_f32_16x16x32_bf16 v[66:69], v[186:189], v[218:221], v[66:69]
	s_barrier
	s_add_i32 s70, s63, s51
	s_add_u32 s98, s44, 0x80
	s_addc_u32 s99, s45, 0
	s_mov_b32 m0, s70
	ds_read_b128 v[190:193], v184 offset:16384
	ds_read_b128 v[194:197], v184 offset:17408
	ds_read_b128 v[198:201], v184 offset:18432
	ds_read_b128 v[202:205], v184 offset:19456
	ds_read_b128 v[206:209], v184 offset:20480
	ds_read_b128 v[210:213], v184 offset:21504
	ds_read_b128 v[214:217], v184 offset:22528
	ds_read_b128 v[218:221], v184 offset:23552
	global_load_lds_dwordx4 v140, s[44:45]
	s_add_i32 m0, s70, 0x2000
	s_add_u32 s70, s44, 0x40000
	s_addc_u32 s71, s45, 0
	s_add_i32 s72, s64, s51
	global_load_lds_dwordx4 v144, s[44:45]
	s_mov_b32 m0, s72
	v_lshl_add_u64 v[226:227], s[46:47], 0, v[142:143]
	global_load_lds_dwordx4 v140, s[70:71]
	s_add_i32 m0, s72, 0x2000
	s_nop 0
	global_load_lds_dwordx4 v144, s[70:71]
	s_add_u32 s100, s46, 0x80
	s_addc_u32 s101, s47, 0
	s_mov_b32 m0, s41
	s_nop 0
	global_load_lds_dwordx4 v138, s[46:47]
	s_mov_b32 m0, s52
	s_nop 0
	global_load_lds_dwordx4 v142, s[46:47]
	s_waitcnt vmcnt(8)
	s_waitcnt lgkmcnt(0)
	s_barrier
	v_mfma_f32_16x16x32_bf16 v[62:65], v[130:133], v[190:193], v[62:65]
	v_mfma_f32_16x16x32_bf16 v[30:33], v[154:157], v[190:193], v[30:33]
	v_mfma_f32_16x16x32_bf16 v[54:57], v[130:133], v[198:201], v[54:57]
	v_mfma_f32_16x16x32_bf16 v[22:25], v[154:157], v[198:201], v[22:25]
	v_mfma_f32_16x16x32_bf16 v[50:53], v[130:133], v[206:209], v[50:53]
	v_mfma_f32_16x16x32_bf16 v[18:21], v[154:157], v[206:209], v[18:21]
	v_mfma_f32_16x16x32_bf16 v[38:41], v[130:133], v[214:217], v[38:41]
	v_mfma_f32_16x16x32_bf16 v[6:9], v[154:157], v[214:217], v[6:9]
	v_mfma_f32_16x16x32_bf16 v[62:65], v[134:137], v[194:197], v[62:65]
	v_mfma_f32_16x16x32_bf16 v[30:33], v[158:161], v[194:197], v[30:33]
	v_mfma_f32_16x16x32_bf16 v[54:57], v[134:137], v[202:205], v[54:57]
	v_mfma_f32_16x16x32_bf16 v[22:25], v[158:161], v[202:205], v[22:25]
	v_mfma_f32_16x16x32_bf16 v[50:53], v[134:137], v[210:213], v[50:53]
	v_mfma_f32_16x16x32_bf16 v[18:21], v[158:161], v[210:213], v[18:21]
	v_mfma_f32_16x16x32_bf16 v[38:41], v[134:137], v[218:221], v[38:41]
	v_mfma_f32_16x16x32_bf16 v[6:9], v[158:161], v[218:221], v[6:9]
	v_mfma_f32_16x16x32_bf16 v[58:61], v[162:165], v[190:193], v[58:61]
	v_mfma_f32_16x16x32_bf16 v[26:29], v[170:173], v[190:193], v[26:29]
	v_mfma_f32_16x16x32_bf16 v[46:49], v[162:165], v[198:201], v[46:49]
	v_mfma_f32_16x16x32_bf16 v[14:17], v[170:173], v[198:201], v[14:17]
	v_mfma_f32_16x16x32_bf16 v[42:45], v[162:165], v[206:209], v[42:45]
	v_mfma_f32_16x16x32_bf16 v[10:13], v[170:173], v[206:209], v[10:13]
	v_mfma_f32_16x16x32_bf16 v[34:37], v[162:165], v[214:217], v[34:37]
	v_mfma_f32_16x16x32_bf16 v[2:5], v[170:173], v[214:217], v[2:5]
	v_mfma_f32_16x16x32_bf16 v[58:61], v[166:169], v[194:197], v[58:61]
	v_mfma_f32_16x16x32_bf16 v[26:29], v[186:189], v[194:197], v[26:29]
	v_mfma_f32_16x16x32_bf16 v[46:49], v[166:169], v[202:205], v[46:49]
	v_mfma_f32_16x16x32_bf16 v[14:17], v[186:189], v[202:205], v[14:17]
	v_mfma_f32_16x16x32_bf16 v[42:45], v[166:169], v[210:213], v[42:45]
	v_mfma_f32_16x16x32_bf16 v[10:13], v[186:189], v[210:213], v[10:13]
	v_mfma_f32_16x16x32_bf16 v[34:37], v[166:169], v[218:221], v[34:37]
	v_mfma_f32_16x16x32_bf16 v[2:5], v[186:189], v[218:221], v[2:5]
	s_barrier
; #define PG8_STAGE(bufoff, gbase, voff) do { _Pragma("unroll") for (int _i = 0; _i < 2; ++_i) \
;         __builtin_amdgcn_global_load_lds((const unsigned*)((const char*)(gbase) + (voff)[_i]), (PG8_LAS unsigned*)(lds + (bufoff) + ldsw + _i * 8192), 16, 0, 0); } while (0)
; #define PG8_LDA(dst, b, h) do { _Pragma("unroll") for (int m = 0; m < 4; ++m) _Pragma("unroll") for (int k = 0; k < 2; ++k) dst[m][k] = *(const PG8_LAS bf16x8*)(lds + PG8_SA(b, h) + aoff + m * 2048 + k * 1024); } while (0)
; #define PG8_LDB(dst, b, h) do { _Pragma("unroll") for (int n = 0; n < 2; ++n) _Pragma("unroll") for (int k = 0; k < 2; ++k) dst[n][k] = *(const PG8_LAS bf16x8*)(lds + PG8_SB(b, h) + boff + n * 2048 + k * 1024); } while (0)
; #define PG8_MMA(ai, bj, At, Bt) do { __builtin_amdgcn_s_setprio(1); _Pragma("unroll") for (int m = 0; m < 4; ++m) _Pragma("unroll") for (int n = 0; n < 2; ++n) _Pragma("unroll") for (int k = 0; k < 2; ++k) \
;         acc[ai][bj][m][n] = __builtin_amdgcn_mfma_f32_16x16x32_bf16(Bt[n][k], At[m][k], acc[ai][bj][m][n], 0, 0, 0); __builtin_amdgcn_s_setprio(0); } while (0)
; #define PG8_WAIT_V(n) asm volatile("s_waitcnt vmcnt(" #n ")" ::: "memory")
; #define PG8_WAIT_L(n) asm volatile("s_waitcnt lgkmcnt(" #n ")" ::: "memory")
; #define PG8_BAR __builtin_amdgcn_s_barrier()
; #define PG8_SCHED __builtin_amdgcn_sched_barrier(0)
; template <class Epi, class Sched, bool ALIGN_EPI = false, bool SP2 = false>
; __device__ __forceinline__ void gemm_phase(PG8_LAS unsigned char* lds, const Gemm g, const Sched& S, const Epi& E) {
;     ...
;             PG8_LDB(B0, 1, 0); PG8_LDB(B1, 1, 1); PG8_SCHED; PG8_LDA(At, 1, 0); PG8_STAGE(PG8_SA(0, 1), a2 + hstepA, voffA);
;             PG8_WAIT_V(8); PG8_WAIT_L(0); PG8_BAR; PG8_MMA(0, 0, At, B0); PG8_MMA(0, 1, At, B1); PG8_BAR; PG8_SCHED;
;             PG8_LDA(At, 1, 1); PG8_STAGE(PG8_SB(1, 0), b3, voffB); PG8_STAGE(PG8_SB(1, 1), b3 + hstepB, voffB); PG8_STAGE(PG8_SA(1, 0), a3, voffA);
;             PG8_WAIT_V(8); PG8_WAIT_L(0); PG8_BAR; PG8_MMA(1, 0, At, B0); PG8_MMA(1, 1, At, B1); PG8_BAR; PG8_SCHED;
;     ...
;         if constexpr (ALIGN_EPI) { if (wr == 0) PG8_BAR; }
	s_add_i32 s70, 0, 0x18000
	s_add_i32 s71, 0, 0x1c000
	v_add_u32_e32 v158, s70, v176
	v_add_u32_e32 v185, s71, v176
	ds_read_b128 v[130:133], v158
	ds_read_b128 v[134:137], v158 offset:1024
	ds_read_b128 v[154:157], v158 offset:2048
	ds_read_b128 v[158:161], v158 offset:3072
	ds_read_b128 v[162:165], v185
	ds_read_b128 v[166:169], v185 offset:1024
	ds_read_b128 v[170:173], v185 offset:2048
	ds_read_b128 v[186:189], v185 offset:3072
	s_add_u32 s46, s46, 0x40000
	s_addc_u32 s47, s47, 0
	s_mov_b32 m0, s53
	ds_read_b128 v[190:193], v184 offset:32768
	ds_read_b128 v[194:197], v184 offset:33792
	ds_read_b128 v[198:201], v184 offset:34816
	ds_read_b128 v[202:205], v184 offset:35840
	ds_read_b128 v[206:209], v184 offset:36864
	ds_read_b128 v[210:213], v184 offset:37888
	ds_read_b128 v[214:217], v184 offset:38912
	ds_read_b128 v[218:221], v184 offset:39936
	global_load_lds_dwordx4 v138, s[46:47]
	s_mov_b32 m0, s54
	s_nop 0
	global_load_lds_dwordx4 v142, s[46:47]
	s_waitcnt vmcnt(8)
	s_waitcnt lgkmcnt(0)
	s_barrier
	v_mfma_f32_16x16x32_bf16 v[126:129], v[130:133], v[190:193], v[126:129]
	v_mfma_f32_16x16x32_bf16 v[94:97], v[154:157], v[190:193], v[94:97]
	v_mfma_f32_16x16x32_bf16 v[118:121], v[130:133], v[198:201], v[118:121]
	v_mfma_f32_16x16x32_bf16 v[86:89], v[154:157], v[198:201], v[86:89]
	v_mfma_f32_16x16x32_bf16 v[114:117], v[130:133], v[206:209], v[114:117]
	v_mfma_f32_16x16x32_bf16 v[82:85], v[154:157], v[206:209], v[82:85]
	v_mfma_f32_16x16x32_bf16 v[102:105], v[130:133], v[214:217], v[102:105]
	v_mfma_f32_16x16x32_bf16 v[70:73], v[154:157], v[214:217], v[70:73]
	v_mfma_f32_16x16x32_bf16 v[126:129], v[134:137], v[194:197], v[126:129]
	v_mfma_f32_16x16x32_bf16 v[94:97], v[158:161], v[194:197], v[94:97]
	v_mfma_f32_16x16x32_bf16 v[118:121], v[134:137], v[202:205], v[118:121]
	v_mfma_f32_16x16x32_bf16 v[86:89], v[158:161], v[202:205], v[86:89]
	v_mfma_f32_16x16x32_bf16 v[114:117], v[134:137], v[210:213], v[114:117]
	v_mfma_f32_16x16x32_bf16 v[82:85], v[158:161], v[210:213], v[82:85]
	v_mfma_f32_16x16x32_bf16 v[102:105], v[134:137], v[218:221], v[102:105]
	v_mfma_f32_16x16x32_bf16 v[70:73], v[158:161], v[218:221], v[70:73]
	v_mfma_f32_16x16x32_bf16 v[122:125], v[162:165], v[190:193], v[122:125]
	v_mfma_f32_16x16x32_bf16 v[90:93], v[170:173], v[190:193], v[90:93]
	v_mfma_f32_16x16x32_bf16 v[110:113], v[162:165], v[198:201], v[110:113]
	v_mfma_f32_16x16x32_bf16 v[78:81], v[170:173], v[198:201], v[78:81]
	v_mfma_f32_16x16x32_bf16 v[106:109], v[162:165], v[206:209], v[106:109]
	v_mfma_f32_16x16x32_bf16 v[74:77], v[170:173], v[206:209], v[74:77]
	v_mfma_f32_16x16x32_bf16 v[98:101], v[162:165], v[214:217], v[98:101]
	v_mfma_f32_16x16x32_bf16 v[66:69], v[170:173], v[214:217], v[66:69]
	v_mfma_f32_16x16x32_bf16 v[122:125], v[166:169], v[194:197], v[122:125]
	v_mfma_f32_16x16x32_bf16 v[90:93], v[186:189], v[194:197], v[90:93]
	v_mfma_f32_16x16x32_bf16 v[110:113], v[166:169], v[202:205], v[110:113]
	v_mfma_f32_16x16x32_bf16 v[78:81], v[186:189], v[202:205], v[78:81]
	v_mfma_f32_16x16x32_bf16 v[106:109], v[166:169], v[210:213], v[106:109]
	v_mfma_f32_16x16x32_bf16 v[74:77], v[186:189], v[210:213], v[74:77]
	v_mfma_f32_16x16x32_bf16 v[98:101], v[166:169], v[218:221], v[98:101]
	v_mfma_f32_16x16x32_bf16 v[66:69], v[186:189], v[218:221], v[66:69]
	s_barrier
	s_add_i32 s46, s70, s51
	s_mov_b32 m0, s46
	ds_read_b128 v[190:193], v184 offset:49152
	ds_read_b128 v[194:197], v184 offset:50176
	ds_read_b128 v[198:201], v184 offset:51200
	ds_read_b128 v[202:205], v184 offset:52224
	ds_read_b128 v[206:209], v184 offset:53248
	ds_read_b128 v[210:213], v184 offset:54272
	ds_read_b128 v[214:217], v184 offset:55296
	ds_read_b128 v[218:221], v184 offset:56320
	global_load_lds_dwordx4 v140, s[98:99]
	s_add_i32 m0, s46, 0x2000
	s_add_u32 s44, s44, 0x40080
	s_addc_u32 s45, s45, 0
	s_add_i32 s46, s71, s51
	global_load_lds_dwordx4 v144, s[98:99]
	s_mov_b32 m0, s46
	s_nop 0
	global_load_lds_dwordx4 v140, s[44:45]
	s_add_i32 m0, s46, 0x2000
	s_nop 0
	global_load_lds_dwordx4 v144, s[44:45]
	s_mov_b32 m0, s59
	s_nop 0
	global_load_lds_dwordx4 v138, s[100:101]
	v_lshl_add_u64 v[174:175], v[226:227], 0, s[24:25]
	s_mov_b32 m0, s60
	s_nop 0
	global_load_lds_dwordx4 v142, s[100:101]
	s_waitcnt vmcnt(8)
	s_waitcnt lgkmcnt(0)
	s_barrier
	v_mfma_f32_16x16x32_bf16 v[62:65], v[130:133], v[190:193], v[62:65]
	v_mfma_f32_16x16x32_bf16 v[30:33], v[154:157], v[190:193], v[30:33]
	v_mfma_f32_16x16x32_bf16 v[54:57], v[130:133], v[198:201], v[54:57]
	v_mfma_f32_16x16x32_bf16 v[22:25], v[154:157], v[198:201], v[22:25]
	v_mfma_f32_16x16x32_bf16 v[50:53], v[130:133], v[206:209], v[50:53]
	v_mfma_f32_16x16x32_bf16 v[18:21], v[154:157], v[206:209], v[18:21]
	v_mfma_f32_16x16x32_bf16 v[38:41], v[130:133], v[214:217], v[38:41]
	v_mfma_f32_16x16x32_bf16 v[6:9], v[154:157], v[214:217], v[6:9]
	v_mfma_f32_16x16x32_bf16 v[62:65], v[134:137], v[194:197], v[62:65]
	v_mfma_f32_16x16x32_bf16 v[30:33], v[158:161], v[194:197], v[30:33]
	v_mfma_f32_16x16x32_bf16 v[54:57], v[134:137], v[202:205], v[54:57]
	v_mfma_f32_16x16x32_bf16 v[22:25], v[158:161], v[202:205], v[22:25]
	v_mfma_f32_16x16x32_bf16 v[50:53], v[134:137], v[210:213], v[50:53]
	v_mfma_f32_16x16x32_bf16 v[18:21], v[158:161], v[210:213], v[18:21]
	v_mfma_f32_16x16x32_bf16 v[38:41], v[134:137], v[218:221], v[38:41]
	v_mfma_f32_16x16x32_bf16 v[6:9], v[158:161], v[218:221], v[6:9]
	v_mfma_f32_16x16x32_bf16 v[58:61], v[162:165], v[190:193], v[58:61]
	v_mfma_f32_16x16x32_bf16 v[26:29], v[170:173], v[190:193], v[26:29]
	v_mfma_f32_16x16x32_bf16 v[46:49], v[162:165], v[198:201], v[46:49]
	v_mfma_f32_16x16x32_bf16 v[14:17], v[170:173], v[198:201], v[14:17]
	v_mfma_f32_16x16x32_bf16 v[42:45], v[162:165], v[206:209], v[42:45]
	v_mfma_f32_16x16x32_bf16 v[10:13], v[170:173], v[206:209], v[10:13]
	v_mfma_f32_16x16x32_bf16 v[34:37], v[162:165], v[214:217], v[34:37]
	v_mfma_f32_16x16x32_bf16 v[2:5], v[170:173], v[214:217], v[2:5]
	v_mfma_f32_16x16x32_bf16 v[58:61], v[166:169], v[194:197], v[58:61]
	v_mfma_f32_16x16x32_bf16 v[26:29], v[186:189], v[194:197], v[26:29]
	v_mfma_f32_16x16x32_bf16 v[46:49], v[166:169], v[202:205], v[46:49]
	v_mfma_f32_16x16x32_bf16 v[14:17], v[186:189], v[202:205], v[14:17]
	v_mfma_f32_16x16x32_bf16 v[42:45], v[166:169], v[210:213], v[42:45]
	v_mfma_f32_16x16x32_bf16 v[10:13], v[186:189], v[210:213], v[10:13]
	v_mfma_f32_16x16x32_bf16 v[34:37], v[166:169], v[218:221], v[34:37]
	v_mfma_f32_16x16x32_bf16 v[2:5], v[186:189], v[218:221], v[2:5]
	s_barrier
	s_add_i32 s69, s69, 2
	s_add_u32 s42, s42, 0x100
	s_addc_u32 s43, s43, 0
	s_add_u32 s67, s67, 0x100
	s_addc_u32 s68, s68, 0
	s_cmp_gt_u32 s69, 13
	s_cbranch_scc0 .LBB0_1528
	s_and_b64 vcc, exec, s[26:27]
	s_cbranch_vccz .LBB0_1531
	s_barrier

; #define PG8_STAGE(bufoff, gbase, voff) do { _Pragma("unroll") for (int _i = 0; _i < 2; ++_i) \
;         __builtin_amdgcn_global_load_lds((const unsigned*)((const char*)(gbase) + (voff)[_i]), (PG8_LAS unsigned*)(lds + (bufoff) + ldsw + _i * 8192), 16, 0, 0); } while (0)
; #define PG8_LDA(dst, b, h) do { _Pragma("unroll") for (int m = 0; m < 4; ++m) _Pragma("unroll") for (int k = 0; k < 2; ++k) dst[m][k] = *(const PG8_LAS bf16x8*)(lds + PG8_SA(b, h) + aoff + m * 2048 + k * 1024); } while (0)
; #define PG8_LDB(dst, b, h) do { _Pragma("unroll") for (int n = 0; n < 2; ++n) _Pragma("unroll") for (int k = 0; k < 2; ++k) dst[n][k] = *(const PG8_LAS bf16x8*)(lds + PG8_SB(b, h) + boff + n * 2048 + k * 1024); } while (0)
; #define PG8_MMA(ai, bj, At, Bt) do { __builtin_amdgcn_s_setprio(1); _Pragma("unroll") for (int m = 0; m < 4; ++m) _Pragma("unroll") for (int n = 0; n < 2; ++n) _Pragma("unroll") for (int k = 0; k < 2; ++k) \
;         acc[ai][bj][m][n] = __builtin_amdgcn_mfma_f32_16x16x32_bf16(Bt[n][k], At[m][k], acc[ai][bj][m][n], 0, 0, 0); __builtin_amdgcn_s_setprio(0); } while (0)
; #define PG8_WAIT_V(n) asm volatile("s_waitcnt vmcnt(" #n ")" ::: "memory")
; #define PG8_WAIT_L(n) asm volatile("s_waitcnt lgkmcnt(" #n ")" ::: "memory")
; #define PG8_BAR __builtin_amdgcn_s_barrier()
; #define PG8_SCHED __builtin_amdgcn_sched_barrier(0)
; template <class Epi, class Sched, bool ALIGN_EPI = false, bool SP2 = false>
; __device__ __forceinline__ void gemm_phase(PG8_LAS unsigned char* lds, const Gemm g, const Sched& S, const Epi& E) {
;     ...
;             PG8_LDB(B0, 0, 0); PG8_LDB(B1, 0, 1); PG8_SCHED; PG8_LDA(At, 0, 0); PG8_STAGE(PG8_SA(1, 1), a1 + hstepA, voffA);
;             PG8_WAIT_V(8); PG8_WAIT_L(0); PG8_BAR; PG8_MMA(0, 0, At, B0); PG8_MMA(0, 1, At, B1); PG8_BAR; PG8_SCHED;
;             PG8_LDA(At, 0, 1); PG8_STAGE(PG8_SB(0, 0), b2, voffB); PG8_STAGE(PG8_SB(0, 1), b2 + hstepB, voffB); PG8_STAGE(PG8_SA(0, 0), a2, voffA);
;             PG8_WAIT_V(8); PG8_WAIT_L(0); PG8_BAR; PG8_MMA(1, 0, At, B0); PG8_MMA(1, 1, At, B1); PG8_BAR; PG8_SCHED;
.LBB0_1838:
	v_add_u32_e32 v24, s50, v22
	ds_read_b128 v[34:37], v24
	ds_read_b128 v[38:41], v24 offset:1024
	ds_read_b128 v[42:45], v24 offset:2048
	ds_read_b128 v[46:49], v24 offset:3072
	v_add_u32_e32 v24, s51, v22
	s_add_u32 s22, s14, s20
	ds_read_b128 v[50:53], v24
	ds_read_b128 v[54:57], v24 offset:1024
	ds_read_b128 v[66:69], v24 offset:2048
	ds_read_b128 v[70:73], v24 offset:3072
	s_addc_u32 s23, s15, s21
	s_add_u32 s22, s22, 0x100
	s_addc_u32 s23, s23, 0
	s_add_u32 s58, s55, s20
	s_addc_u32 s59, s56, s21
	s_cmpk_eq_i32 s20, 0x1500
	s_cselect_b32 s25, s19, s23
	s_cselect_b32 s24, s18, s22
	s_cselect_b32 s23, s1, s59
	s_cselect_b32 s22, s0, s58
	v_lshl_add_u64 v[24:25], v[18:19], 0, s[20:21]
	s_add_i32 m0, s42, 0xc000
	ds_read_b128 v[162:165], v23
	ds_read_b128 v[166:169], v23 offset:1024
	ds_read_b128 v[194:197], v23 offset:2048
	ds_read_b128 v[198:201], v23 offset:3072
	ds_read_b128 v[202:205], v23 offset:4096
	ds_read_b128 v[206:209], v23 offset:5120
	ds_read_b128 v[210:213], v23 offset:6144
	ds_read_b128 v[216:219], v23 offset:7168
	global_load_lds_dwordx4 v[24:25], off
	v_lshl_add_u64 v[24:25], v[20:21], 0, s[20:21]
	s_add_i32 m0, s42, 0xe000
	s_nop 0
	global_load_lds_dwordx4 v[24:25], off
	s_waitcnt vmcnt(8)
	s_waitcnt lgkmcnt(0)
	s_barrier
	v_mfma_f32_16x16x32_bf16 v[170:173], v[34:37], v[162:165], v[170:173]
	v_mfma_f32_16x16x32_bf16 v[174:177], v[42:45], v[162:165], v[174:177]
	v_mfma_f32_16x16x32_bf16 v[178:181], v[34:37], v[194:197], v[178:181]
	v_mfma_f32_16x16x32_bf16 v[182:185], v[42:45], v[194:197], v[182:185]
	v_mfma_f32_16x16x32_bf16 v[186:189], v[34:37], v[202:205], v[186:189]
	v_mfma_f32_16x16x32_bf16 v[190:193], v[42:45], v[202:205], v[190:193]
	v_mfma_f32_16x16x32_bf16 v[158:161], v[34:37], v[210:213], v[158:161]
	v_mfma_f32_16x16x32_bf16 v[154:157], v[42:45], v[210:213], v[154:157]
	v_mfma_f32_16x16x32_bf16 v[170:173], v[38:41], v[166:169], v[170:173]
	v_mfma_f32_16x16x32_bf16 v[174:177], v[46:49], v[166:169], v[174:177]
	v_mfma_f32_16x16x32_bf16 v[178:181], v[38:41], v[198:201], v[178:181]
	v_mfma_f32_16x16x32_bf16 v[182:185], v[46:49], v[198:201], v[182:185]
	v_mfma_f32_16x16x32_bf16 v[186:189], v[38:41], v[206:209], v[186:189]
	v_mfma_f32_16x16x32_bf16 v[190:193], v[46:49], v[206:209], v[190:193]
	v_mfma_f32_16x16x32_bf16 v[158:161], v[38:41], v[216:219], v[158:161]
	v_mfma_f32_16x16x32_bf16 v[154:157], v[46:49], v[216:219], v[154:157]
	v_mfma_f32_16x16x32_bf16 v[62:65], v[50:53], v[162:165], v[62:65]
	v_mfma_f32_16x16x32_bf16 v[58:61], v[66:69], v[162:165], v[58:61]
	v_mfma_f32_16x16x32_bf16 v[74:77], v[50:53], v[194:197], v[74:77]
	v_mfma_f32_16x16x32_bf16 v[78:81], v[66:69], v[194:197], v[78:81]
	v_mfma_f32_16x16x32_bf16 v[90:93], v[50:53], v[202:205], v[90:93]
	v_mfma_f32_16x16x32_bf16 v[94:97], v[66:69], v[202:205], v[94:97]
	v_mfma_f32_16x16x32_bf16 v[106:109], v[50:53], v[210:213], v[106:109]
	v_mfma_f32_16x16x32_bf16 v[110:113], v[66:69], v[210:213], v[110:113]
	v_mfma_f32_16x16x32_bf16 v[62:65], v[54:57], v[166:169], v[62:65]
	v_mfma_f32_16x16x32_bf16 v[58:61], v[70:73], v[166:169], v[58:61]
	v_mfma_f32_16x16x32_bf16 v[74:77], v[54:57], v[198:201], v[74:77]
	v_mfma_f32_16x16x32_bf16 v[78:81], v[70:73], v[198:201], v[78:81]
	v_mfma_f32_16x16x32_bf16 v[90:93], v[54:57], v[206:209], v[90:93]
	v_mfma_f32_16x16x32_bf16 v[94:97], v[70:73], v[206:209], v[94:97]
	v_mfma_f32_16x16x32_bf16 v[106:109], v[54:57], v[216:219], v[106:109]
	v_mfma_f32_16x16x32_bf16 v[110:113], v[70:73], v[216:219], v[110:113]
	s_barrier
	s_add_i32 s58, s50, s41
	s_add_u32 s98, s22, 0x80
	s_addc_u32 s99, s23, 0
	s_mov_b32 m0, s58
	ds_read_b128 v[162:165], v23 offset:16384
	ds_read_b128 v[166:169], v23 offset:17408
	ds_read_b128 v[194:197], v23 offset:18432
	ds_read_b128 v[198:201], v23 offset:19456
	ds_read_b128 v[202:205], v23 offset:20480
	ds_read_b128 v[206:209], v23 offset:21504
	ds_read_b128 v[210:213], v23 offset:22528
	ds_read_b128 v[216:219], v23 offset:23552
	global_load_lds_dwordx4 v4, s[22:23]
	s_add_i32 m0, s58, 0x2000
	s_add_u32 s58, s22, 0xb0000
	s_addc_u32 s59, s23, 0
	s_add_i32 s60, s51, s41
	global_load_lds_dwordx4 v8, s[22:23]
	s_mov_b32 m0, s60
	s_add_u32 s100, s24, 0x80
	s_addc_u32 s101, s25, 0
	global_load_lds_dwordx4 v4, s[58:59]
	s_add_i32 m0, s60, 0x2000
	s_nop 0
	global_load_lds_dwordx4 v8, s[58:59]
	s_mov_b32 m0, s42
	s_nop 0
	global_load_lds_dwordx4 v2, s[24:25]
	s_mov_b32 m0, s43
	s_nop 0
	global_load_lds_dwordx4 v6, s[24:25]
	s_waitcnt vmcnt(8)
	s_waitcnt lgkmcnt(0)
	s_barrier
	v_mfma_f32_16x16x32_bf16 v[150:153], v[34:37], v[162:165], v[150:153]
	v_mfma_f32_16x16x32_bf16 v[146:149], v[42:45], v[162:165], v[146:149]
	v_mfma_f32_16x16x32_bf16 v[142:145], v[34:37], v[194:197], v[142:145]
	v_mfma_f32_16x16x32_bf16 v[138:141], v[42:45], v[194:197], v[138:141]
	v_mfma_f32_16x16x32_bf16 v[134:137], v[34:37], v[202:205], v[134:137]
	v_mfma_f32_16x16x32_bf16 v[130:133], v[42:45], v[202:205], v[130:133]
	v_mfma_f32_16x16x32_bf16 v[34:37], v[34:37], v[210:213], v[98:101]
	v_mfma_f32_16x16x32_bf16 v[150:153], v[38:41], v[166:169], v[150:153]
	v_mfma_f32_16x16x32_bf16 v[146:149], v[46:49], v[166:169], v[146:149]
	v_mfma_f32_16x16x32_bf16 v[142:145], v[38:41], v[198:201], v[142:145]
	v_mfma_f32_16x16x32_bf16 v[138:141], v[46:49], v[198:201], v[138:141]
	v_mfma_f32_16x16x32_bf16 v[134:137], v[38:41], v[206:209], v[134:137]
	v_mfma_f32_16x16x32_bf16 v[130:133], v[46:49], v[206:209], v[130:133]
	v_mfma_f32_16x16x32_bf16 v[34:37], v[38:41], v[216:219], v[34:37]
	v_mfma_f32_16x16x32_bf16 v[38:41], v[42:45], v[210:213], v[82:85]
	v_mfma_f32_16x16x32_bf16 v[38:41], v[46:49], v[216:219], v[38:41]
	v_mfma_f32_16x16x32_bf16 v[82:85], v[50:53], v[194:197], v[122:125]
	v_mfma_f32_16x16x32_bf16 v[122:125], v[54:57], v[198:201], v[82:85]
	v_mfma_f32_16x16x32_bf16 v[82:85], v[66:69], v[194:197], v[126:129]
	v_mfma_f32_16x16x32_bf16 v[126:129], v[70:73], v[198:201], v[82:85]
	v_mfma_f32_16x16x32_bf16 v[82:85], v[50:53], v[202:205], v[102:105]
	v_mfma_f32_16x16x32_bf16 v[102:105], v[54:57], v[206:209], v[82:85]
	v_mfma_f32_16x16x32_bf16 v[82:85], v[66:69], v[202:205], v[86:89]
	v_mfma_f32_16x16x32_bf16 v[30:33], v[50:53], v[210:213], v[30:33]
	v_mfma_f32_16x16x32_bf16 v[24:27], v[66:69], v[210:213], v[26:29]
	v_mfma_f32_16x16x32_bf16 v[42:45], v[50:53], v[162:165], v[114:117]
	v_mfma_f32_16x16x32_bf16 v[46:49], v[66:69], v[162:165], v[118:121]
	v_mfma_f32_16x16x32_bf16 v[86:89], v[70:73], v[206:209], v[82:85]
	v_mfma_f32_16x16x32_bf16 v[30:33], v[54:57], v[216:219], v[30:33]
	v_mfma_f32_16x16x32_bf16 v[24:27], v[70:73], v[216:219], v[24:27]
	v_mfma_f32_16x16x32_bf16 v[42:45], v[54:57], v[166:169], v[42:45]
	v_mfma_f32_16x16x32_bf16 v[46:49], v[70:73], v[166:169], v[46:49]
	s_barrier
; #define PG8_STAGE(bufoff, gbase, voff) do { _Pragma("unroll") for (int _i = 0; _i < 2; ++_i) \
;         __builtin_amdgcn_global_load_lds((const unsigned*)((const char*)(gbase) + (voff)[_i]), (PG8_LAS unsigned*)(lds + (bufoff) + ldsw + _i * 8192), 16, 0, 0); } while (0)
; #define PG8_LDA(dst, b, h) do { _Pragma("unroll") for (int m = 0; m < 4; ++m) _Pragma("unroll") for (int k = 0; k < 2; ++k) dst[m][k] = *(const PG8_LAS bf16x8*)(lds + PG8_SA(b, h) + aoff + m * 2048 + k * 1024); } while (0)
; #define PG8_LDB(dst, b, h) do { _Pragma("unroll") for (int n = 0; n < 2; ++n) _Pragma("unroll") for (int k = 0; k < 2; ++k) dst[n][k] = *(const PG8_LAS bf16x8*)(lds + PG8_SB(b, h) + boff + n * 2048 + k * 1024); } while (0)
; #define PG8_MMA(ai, bj, At, Bt) do { __builtin_amdgcn_s_setprio(1); _Pragma("unroll") for (int m = 0; m < 4; ++m) _Pragma("unroll") for (int n = 0; n < 2; ++n) _Pragma("unroll") for (int k = 0; k < 2; ++k) \
;         acc[ai][bj][m][n] = __builtin_amdgcn_mfma_f32_16x16x32_bf16(Bt[n][k], At[m][k], acc[ai][bj][m][n], 0, 0, 0); __builtin_amdgcn_s_setprio(0); } while (0)
; #define PG8_WAIT_V(n) asm volatile("s_waitcnt vmcnt(" #n ")" ::: "memory")
; #define PG8_WAIT_L(n) asm volatile("s_waitcnt lgkmcnt(" #n ")" ::: "memory")
; #define PG8_BAR __builtin_amdgcn_s_barrier()
; #define PG8_SCHED __builtin_amdgcn_sched_barrier(0)
; template <class Epi, class Sched, bool ALIGN_EPI = false, bool SP2 = false>
; __device__ __forceinline__ void gemm_phase(PG8_LAS unsigned char* lds, const Gemm g, const Sched& S, const Epi& E) {
;     ...
;             PG8_LDB(B0, 1, 0); PG8_LDB(B1, 1, 1); PG8_SCHED; PG8_LDA(At, 1, 0); PG8_STAGE(PG8_SA(0, 1), a2 + hstepA, voffA);
;             PG8_WAIT_V(8); PG8_WAIT_L(0); PG8_BAR; PG8_MMA(0, 0, At, B0); PG8_MMA(0, 1, At, B1); PG8_BAR; PG8_SCHED;
;             PG8_LDA(At, 1, 1); PG8_STAGE(PG8_SB(1, 0), b3, voffB); PG8_STAGE(PG8_SB(1, 1), b3 + hstepB, voffB); PG8_STAGE(PG8_SA(1, 0), a3, voffA);
	s_add_i32 s58, 0, 0x18000
	v_add_u32_e32 v28, s58, v22
	s_add_i32 s59, 0, 0x1c000
	ds_read_b128 v[50:53], v28
	ds_read_b128 v[54:57], v28 offset:1024
	ds_read_b128 v[66:69], v28 offset:2048
	ds_read_b128 v[70:73], v28 offset:3072
	v_add_u32_e32 v28, s59, v22
	ds_read_b128 v[162:165], v28
	ds_read_b128 v[166:169], v28 offset:1024
	ds_read_b128 v[194:197], v28 offset:2048
	ds_read_b128 v[198:201], v28 offset:3072
	s_add_u32 s24, s24, 0xb0000
	s_addc_u32 s25, s25, 0
	s_mov_b32 m0, s45
	ds_read_b128 v[82:85], v23 offset:32768
	ds_read_b128 v[98:101], v23 offset:33792
	ds_read_b128 v[114:117], v23 offset:34816
	ds_read_b128 v[118:121], v23 offset:35840
	ds_read_b128 v[202:205], v23 offset:36864
	ds_read_b128 v[206:209], v23 offset:37888
	ds_read_b128 v[210:213], v23 offset:38912
	ds_read_b128 v[216:219], v23 offset:39936
	global_load_lds_dwordx4 v2, s[24:25]
	s_mov_b32 m0, s46
	s_nop 0
	global_load_lds_dwordx4 v6, s[24:25]
	s_waitcnt vmcnt(8)
	s_waitcnt lgkmcnt(0)
	s_barrier
	v_mfma_f32_16x16x32_bf16 v[170:173], v[50:53], v[82:85], v[170:173]
	v_mfma_f32_16x16x32_bf16 v[174:177], v[66:69], v[82:85], v[174:177]
	v_mfma_f32_16x16x32_bf16 v[178:181], v[50:53], v[114:117], v[178:181]
	v_mfma_f32_16x16x32_bf16 v[182:185], v[66:69], v[114:117], v[182:185]
	v_mfma_f32_16x16x32_bf16 v[186:189], v[50:53], v[202:205], v[186:189]
	v_mfma_f32_16x16x32_bf16 v[190:193], v[66:69], v[202:205], v[190:193]
	v_mfma_f32_16x16x32_bf16 v[158:161], v[50:53], v[210:213], v[158:161]
	v_mfma_f32_16x16x32_bf16 v[154:157], v[66:69], v[210:213], v[154:157]
	v_mfma_f32_16x16x32_bf16 v[170:173], v[54:57], v[98:101], v[170:173]
	v_mfma_f32_16x16x32_bf16 v[174:177], v[70:73], v[98:101], v[174:177]
	v_mfma_f32_16x16x32_bf16 v[178:181], v[54:57], v[118:121], v[178:181]
	v_mfma_f32_16x16x32_bf16 v[182:185], v[70:73], v[118:121], v[182:185]
	v_mfma_f32_16x16x32_bf16 v[186:189], v[54:57], v[206:209], v[186:189]
	v_mfma_f32_16x16x32_bf16 v[190:193], v[70:73], v[206:209], v[190:193]
	v_mfma_f32_16x16x32_bf16 v[158:161], v[54:57], v[216:219], v[158:161]
	v_mfma_f32_16x16x32_bf16 v[154:157], v[70:73], v[216:219], v[154:157]
	v_mfma_f32_16x16x32_bf16 v[62:65], v[162:165], v[82:85], v[62:65]
	v_mfma_f32_16x16x32_bf16 v[58:61], v[194:197], v[82:85], v[58:61]
	v_mfma_f32_16x16x32_bf16 v[82:85], v[162:165], v[202:205], v[90:93]
	v_mfma_f32_16x16x32_bf16 v[90:93], v[166:169], v[206:209], v[82:85]
	v_mfma_f32_16x16x32_bf16 v[82:85], v[194:197], v[202:205], v[94:97]
	v_mfma_f32_16x16x32_bf16 v[94:97], v[198:201], v[206:209], v[82:85]
	v_mfma_f32_16x16x32_bf16 v[82:85], v[162:165], v[210:213], v[106:109]
	v_mfma_f32_16x16x32_bf16 v[74:77], v[162:165], v[114:117], v[74:77]
	v_mfma_f32_16x16x32_bf16 v[78:81], v[194:197], v[114:117], v[78:81]
	v_mfma_f32_16x16x32_bf16 v[106:109], v[166:169], v[216:219], v[82:85]
	v_mfma_f32_16x16x32_bf16 v[82:85], v[194:197], v[210:213], v[110:113]
	v_mfma_f32_16x16x32_bf16 v[62:65], v[166:169], v[98:101], v[62:65]
	v_mfma_f32_16x16x32_bf16 v[58:61], v[198:201], v[98:101], v[58:61]
	v_mfma_f32_16x16x32_bf16 v[74:77], v[166:169], v[118:121], v[74:77]
	v_mfma_f32_16x16x32_bf16 v[78:81], v[198:201], v[118:121], v[78:81]
	v_mfma_f32_16x16x32_bf16 v[110:113], v[198:201], v[216:219], v[82:85]
	s_barrier
	s_add_i32 s24, s58, s41
	s_mov_b32 m0, s24
	ds_read_b128 v[118:121], v23 offset:49152
	ds_read_b128 v[202:205], v23 offset:50176
	ds_read_b128 v[206:209], v23 offset:51200
	ds_read_b128 v[210:213], v23 offset:52224
	ds_read_b128 v[216:219], v23 offset:53248
	ds_read_b128 v[220:223], v23 offset:54272
	ds_read_b128 v[224:227], v23 offset:55296
	ds_read_b128 v[228:231], v23 offset:56320
	global_load_lds_dwordx4 v4, s[98:99]
	s_add_i32 m0, s24, 0x2000
	s_add_u32 s22, s22, 0xb0080
	s_addc_u32 s23, s23, 0
	s_add_i32 s24, s59, s41
	global_load_lds_dwordx4 v8, s[98:99]
	s_mov_b32 m0, s24
	s_nop 0
	global_load_lds_dwordx4 v4, s[22:23]
	s_add_i32 m0, s24, 0x2000
	s_nop 0
	global_load_lds_dwordx4 v8, s[22:23]
	s_mov_b32 m0, s48
	s_nop 0
	global_load_lds_dwordx4 v2, s[100:101]
	s_mov_b32 m0, s49
	s_nop 0
	global_load_lds_dwordx4 v6, s[100:101]
	s_waitcnt vmcnt(8)
	s_waitcnt lgkmcnt(0)
	s_barrier
; #define PG8_STAGE(bufoff, gbase, voff) do { _Pragma("unroll") for (int _i = 0; _i < 2; ++_i) \
;         __builtin_amdgcn_global_load_lds((const unsigned*)((const char*)(gbase) + (voff)[_i]), (PG8_LAS unsigned*)(lds + (bufoff) + ldsw + _i * 8192), 16, 0, 0); } while (0)
; #define PG8_LDA(dst, b, h) do { _Pragma("unroll") for (int m = 0; m < 4; ++m) _Pragma("unroll") for (int k = 0; k < 2; ++k) dst[m][k] = *(const PG8_LAS bf16x8*)(lds + PG8_SA(b, h) + aoff + m * 2048 + k * 1024); } while (0)
; #define PG8_MMA(ai, bj, At, Bt) do { __builtin_amdgcn_s_setprio(1); _Pragma("unroll") for (int m = 0; m < 4; ++m) _Pragma("unroll") for (int n = 0; n < 2; ++n) _Pragma("unroll") for (int k = 0; k < 2; ++k) \
;         acc[ai][bj][m][n] = __builtin_amdgcn_mfma_f32_16x16x32_bf16(Bt[n][k], At[m][k], acc[ai][bj][m][n], 0, 0, 0); __builtin_amdgcn_s_setprio(0); } while (0)
; #define PG8_WAIT_V(n) asm volatile("s_waitcnt vmcnt(" #n ")" ::: "memory")
; #define PG8_WAIT_L(n) asm volatile("s_waitcnt lgkmcnt(" #n ")" ::: "memory")
; #define PG8_BAR __builtin_amdgcn_s_barrier()
; #define PG8_SCHED __builtin_amdgcn_sched_barrier(0)
; template <class Epi, class Sched, bool ALIGN_EPI = false, bool SP2 = false>
; __device__ __forceinline__ void gemm_phase(PG8_LAS unsigned char* lds, const Gemm g, const Sched& S, const Epi& E) {
;     ...
;             PG8_LDA(At, 1, 1); PG8_STAGE(PG8_SB(1, 0), b3, voffB); PG8_STAGE(PG8_SB(1, 1), b3 + hstepB, voffB); PG8_STAGE(PG8_SA(1, 0), a3, voffA);
;             PG8_WAIT_V(8); PG8_WAIT_L(0); PG8_BAR; PG8_MMA(1, 0, At, B0); PG8_MMA(1, 1, At, B1); PG8_BAR; PG8_SCHED;
;     ...
; #pragma unroll
;         for (int a = 0; a < 2; ++a)
; #pragma unroll
;             for (int b = 0; b < 2; ++b)
; #pragma unroll
;                 for (int m = 0; m < 4; ++m)
; #pragma unroll
;                     for (int n = 0; n < 2; ++n) acc[a][b][m][n] = (f32x4){0.f, 0.f, 0.f, 0.f};
	v_mfma_f32_16x16x32_bf16 v[82:85], v[50:53], v[118:121], v[150:153]
	v_mfma_f32_16x16x32_bf16 v[150:153], v[54:57], v[202:205], v[82:85]
	v_mfma_f32_16x16x32_bf16 v[82:85], v[66:69], v[118:121], v[146:149]
	v_mfma_f32_16x16x32_bf16 v[146:149], v[70:73], v[202:205], v[82:85]
	v_mfma_f32_16x16x32_bf16 v[82:85], v[50:53], v[206:209], v[142:145]
	v_mfma_f32_16x16x32_bf16 v[142:145], v[54:57], v[210:213], v[82:85]
	v_mfma_f32_16x16x32_bf16 v[82:85], v[66:69], v[206:209], v[138:141]
	v_mfma_f32_16x16x32_bf16 v[138:141], v[70:73], v[210:213], v[82:85]
	v_mfma_f32_16x16x32_bf16 v[82:85], v[50:53], v[216:219], v[134:137]
	v_mfma_f32_16x16x32_bf16 v[34:37], v[50:53], v[224:227], v[34:37]
	v_mfma_f32_16x16x32_bf16 v[134:137], v[54:57], v[220:223], v[82:85]
	v_mfma_f32_16x16x32_bf16 v[82:85], v[66:69], v[216:219], v[130:133]
	v_mfma_f32_16x16x32_bf16 v[98:101], v[54:57], v[228:231], v[34:37]
	v_mfma_f32_16x16x32_bf16 v[34:37], v[66:69], v[224:227], v[38:41]
	v_mfma_f32_16x16x32_bf16 v[130:133], v[70:73], v[220:223], v[82:85]
	v_mfma_f32_16x16x32_bf16 v[82:85], v[70:73], v[228:231], v[34:37]
	v_mfma_f32_16x16x32_bf16 v[34:37], v[162:165], v[118:121], v[42:45]
	v_mfma_f32_16x16x32_bf16 v[114:117], v[166:169], v[202:205], v[34:37]
	v_mfma_f32_16x16x32_bf16 v[34:37], v[194:197], v[118:121], v[46:49]
	v_mfma_f32_16x16x32_bf16 v[118:121], v[198:201], v[202:205], v[34:37]
	v_mfma_f32_16x16x32_bf16 v[34:37], v[162:165], v[206:209], v[122:125]
	v_mfma_f32_16x16x32_bf16 v[122:125], v[166:169], v[210:213], v[34:37]
	v_mfma_f32_16x16x32_bf16 v[34:37], v[194:197], v[206:209], v[126:129]
	v_mfma_f32_16x16x32_bf16 v[126:129], v[198:201], v[210:213], v[34:37]
	v_mfma_f32_16x16x32_bf16 v[34:37], v[162:165], v[216:219], v[102:105]
	v_mfma_f32_16x16x32_bf16 v[102:105], v[166:169], v[220:223], v[34:37]
	v_mfma_f32_16x16x32_bf16 v[34:37], v[194:197], v[216:219], v[86:89]
	v_mfma_f32_16x16x32_bf16 v[28:31], v[162:165], v[224:227], v[30:33]
	v_mfma_f32_16x16x32_bf16 v[24:27], v[194:197], v[224:227], v[24:27]
	v_mfma_f32_16x16x32_bf16 v[86:89], v[198:201], v[220:223], v[34:37]
	v_mfma_f32_16x16x32_bf16 v[30:33], v[166:169], v[228:231], v[28:31]
	v_mfma_f32_16x16x32_bf16 v[26:29], v[198:201], v[228:231], v[24:27]
	s_barrier
	s_add_i32 s57, s57, 2
	s_add_u32 s20, s20, 0x100
	s_addc_u32 s21, s21, 0
	s_cmp_gt_u32 s57, 41
	s_cbranch_scc0 .LBB0_1838
	s_add_u32 s20, s55, 0xffffff00
	s_addc_u32 s21, s56, -1
	s_and_b64 vcc, exec, s[4:5]
	s_cbranch_vccnz .LBB0_1825
	v_mov_b32_e32 v26, 0
	s_mov_b32 s12, s52
	s_mov_b32 s27, s53
	s_mov_b64 s[14:15], s[18:19]
	s_mov_b32 s47, s54
	v_mov_b32_e32 v27, v26
	v_mov_b32_e32 v28, v26
	v_mov_b32_e32 v29, v26
	v_mov_b32_e32 v30, v26
	v_mov_b32_e32 v31, v26
	v_mov_b32_e32 v32, v26
	v_mov_b32_e32 v33, v26
	v_mov_b32_e32 v86, v26
	v_mov_b32_e32 v87, v26
	v_mov_b32_e32 v88, v26
	v_mov_b32_e32 v89, v26
	v_mov_b32_e32 v102, v26
	v_mov_b32_e32 v103, v26
	v_mov_b32_e32 v104, v26
	v_mov_b32_e32 v105, v26
	v_mov_b32_e32 v126, v26
	v_mov_b32_e32 v127, v26
	v_mov_b32_e32 v128, v26
	v_mov_b32_e32 v129, v26
	v_mov_b32_e32 v122, v26
	v_mov_b32_e32 v123, v26
	v_mov_b32_e32 v124, v26
	v_mov_b32_e32 v125, v26
	v_mov_b32_e32 v118, v26
	v_mov_b32_e32 v119, v26
	v_mov_b32_e32 v120, v26
	v_mov_b32_e32 v121, v26
	v_mov_b32_e32 v114, v26
	v_mov_b32_e32 v115, v26
	v_mov_b32_e32 v116, v26
	v_mov_b32_e32 v117, v26
	v_mov_b32_e32 v82, v26
	v_mov_b32_e32 v83, v26
	v_mov_b32_e32 v84, v26
	v_mov_b32_e32 v85, v26
	v_mov_b32_e32 v98, v26
	v_mov_b32_e32 v99, v26
	v_mov_b32_e32 v100, v26
	v_mov_b32_e32 v101, v26
	v_mov_b32_e32 v130, v26
	v_mov_b32_e32 v131, v26
	v_mov_b32_e32 v132, v26
	v_mov_b32_e32 v133, v26
	v_mov_b32_e32 v134, v26
	v_mov_b32_e32 v135, v26
	v_mov_b32_e32 v136, v26
	v_mov_b32_e32 v137, v26
	v_mov_b32_e32 v138, v26
	v_mov_b32_e32 v139, v26
	v_mov_b32_e32 v140, v26
	v_mov_b32_e32 v141, v26
	v_mov_b32_e32 v142, v26
	v_mov_b32_e32 v143, v26
	v_mov_b32_e32 v144, v26
	v_mov_b32_e32 v145, v26
	v_mov_b32_e32 v146, v26
	v_mov_b32_e32 v147, v26
	v_mov_b32_e32 v148, v26
	v_mov_b32_e32 v149, v26
	v_mov_b32_e32 v150, v26
	v_mov_b32_e32 v151, v26
	v_mov_b32_e32 v152, v26
	v_mov_b32_e32 v153, v26
	v_mov_b32_e32 v110, v26
	v_mov_b32_e32 v111, v26
	v_mov_b32_e32 v112, v26
	v_mov_b32_e32 v113, v26
	v_mov_b32_e32 v106, v26
	v_mov_b32_e32 v107, v26
	v_mov_b32_e32 v108, v26
	v_mov_b32_e32 v109, v26
	v_mov_b32_e32 v94, v26
	v_mov_b32_e32 v95, v26
	v_mov_b32_e32 v96, v26
	v_mov_b32_e32 v97, v26
	v_mov_b32_e32 v90, v26
	v_mov_b32_e32 v91, v26
	v_mov_b32_e32 v92, v26
	v_mov_b32_e32 v93, v26
	v_mov_b32_e32 v78, v26
	v_mov_b32_e32 v79, v26
	v_mov_b32_e32 v80, v26
	v_mov_b32_e32 v81, v26
	v_mov_b32_e32 v74, v26
	v_mov_b32_e32 v75, v26
	v_mov_b32_e32 v76, v26
	v_mov_b32_e32 v77, v26
	v_mov_b32_e32 v58, v26
	v_mov_b32_e32 v59, v26
	v_mov_b32_e32 v60, v26
	v_mov_b32_e32 v61, v26
	v_mov_b32_e32 v62, v26
	v_mov_b32_e32 v63, v26
	v_mov_b32_e32 v64, v26
	v_mov_b32_e32 v65, v26
	v_mov_b32_e32 v154, v26
	v_mov_b32_e32 v155, v26
	v_mov_b32_e32 v156, v26
	v_mov_b32_e32 v157, v26
	v_mov_b32_e32 v158, v26
	v_mov_b32_e32 v159, v26
	v_mov_b32_e32 v160, v26
	v_mov_b32_e32 v161, v26
	v_mov_b32_e32 v190, v26
	v_mov_b32_e32 v191, v26
	v_mov_b32_e32 v192, v26
	v_mov_b32_e32 v193, v26
	v_mov_b32_e32 v186, v26
	v_mov_b32_e32 v187, v26
	v_mov_b32_e32 v188, v26
	v_mov_b32_e32 v189, v26
	v_mov_b32_e32 v182, v26
	v_mov_b32_e32 v183, v26
	v_mov_b32_e32 v184, v26
	v_mov_b32_e32 v185, v26
	v_mov_b32_e32 v178, v26
	v_mov_b32_e32 v179, v26
	v_mov_b32_e32 v180, v26
	v_mov_b32_e32 v181, v26
	v_mov_b32_e32 v174, v26
	v_mov_b32_e32 v175, v26
	v_mov_b32_e32 v176, v26
	v_mov_b32_e32 v177, v26
	v_mov_b32_e32 v170, v26
	v_mov_b32_e32 v171, v26
	v_mov_b32_e32 v172, v26
	v_mov_b32_e32 v173, v26
	s_andn2_b64 vcc, exec, s[2:3]
	s_cbranch_vccnz .LBB0_1826

; #define PG8_STAGE(bufoff, gbase, voff) do { _Pragma("unroll") for (int _i = 0; _i < 2; ++_i) \
;         __builtin_amdgcn_global_load_lds((const unsigned*)((const char*)(gbase) + (voff)[_i]), (PG8_LAS unsigned*)(lds + (bufoff) + ldsw + _i * 8192), 16, 0, 0); } while (0)
; #define PG8_LDA(dst, b, h) do { _Pragma("unroll") for (int m = 0; m < 4; ++m) _Pragma("unroll") for (int k = 0; k < 2; ++k) dst[m][k] = *(const PG8_LAS bf16x8*)(lds + PG8_SA(b, h) + aoff + m * 2048 + k * 1024); } while (0)
; #define PG8_LDB(dst, b, h) do { _Pragma("unroll") for (int n = 0; n < 2; ++n) _Pragma("unroll") for (int k = 0; k < 2; ++k) dst[n][k] = *(const PG8_LAS bf16x8*)(lds + PG8_SB(b, h) + boff + n * 2048 + k * 1024); } while (0)
; #define PG8_MMA(ai, bj, At, Bt) do { __builtin_amdgcn_s_setprio(1); _Pragma("unroll") for (int m = 0; m < 4; ++m) _Pragma("unroll") for (int n = 0; n < 2; ++n) _Pragma("unroll") for (int k = 0; k < 2; ++k) \
;         acc[ai][bj][m][n] = __builtin_amdgcn_mfma_f32_16x16x32_bf16(Bt[n][k], At[m][k], acc[ai][bj][m][n], 0, 0, 0); __builtin_amdgcn_s_setprio(0); } while (0)
; #define PG8_WAIT_V(n) asm volatile("s_waitcnt vmcnt(" #n ")" ::: "memory")
; #define PG8_WAIT_L(n) asm volatile("s_waitcnt lgkmcnt(" #n ")" ::: "memory")
; #define PG8_BAR __builtin_amdgcn_s_barrier()
; #define PG8_SCHED __builtin_amdgcn_sched_barrier(0)
; template <class Epi, class Sched, bool ALIGN_EPI = false, bool SP2 = false>
; __device__ __forceinline__ void gemm_phase(PG8_LAS unsigned char* lds, const Gemm g, const Sched& S, const Epi& E) {
;     ...
;             PG8_LDB(B0, 0, 0); PG8_LDB(B1, 0, 1); PG8_SCHED; PG8_LDA(At, 0, 0); PG8_STAGE(PG8_SA(1, 1), a1 + hstepA, voffA);
;             PG8_WAIT_V(8); PG8_WAIT_L(0); PG8_BAR; PG8_MMA(0, 0, At, B0); PG8_MMA(0, 1, At, B1); PG8_BAR; PG8_SCHED;
;             PG8_LDA(At, 0, 1); PG8_STAGE(PG8_SB(0, 0), b2, voffB); PG8_STAGE(PG8_SB(0, 1), b2 + hstepB, voffB); PG8_STAGE(PG8_SA(0, 0), a2, voffA);
;             PG8_WAIT_V(8); PG8_WAIT_L(0); PG8_BAR; PG8_MMA(1, 0, At, B0); PG8_MMA(1, 1, At, B1); PG8_BAR; PG8_SCHED;
.LBB0_1897:
	ds_read_b128 v[130:133], v162
	ds_read_b128 v[134:137], v162 offset:1024
	ds_read_b128 v[138:141], v162 offset:2048
	ds_read_b128 v[142:145], v162 offset:3072
	ds_read_b128 v[156:159], v163
	ds_read_b128 v[166:169], v163 offset:1024
	ds_read_b128 v[170:173], v163 offset:2048
	ds_read_b128 v[174:177], v163 offset:3072
	s_add_u32 s22, s20, 0x100
	s_addc_u32 s23, s21, 0
	s_cmp_eq_u32 s68, 4
	s_cselect_b32 s27, s17, s23
	s_cselect_b32 s26, s16, s22
	s_cselect_b32 s25, s19, s67
	s_cselect_b32 s24, s18, s66
	v_lshl_add_u64 v[210:211], s[20:21], 0, v[152:153]
	s_add_i32 m0, s42, 0xc000
	ds_read_b128 v[178:181], v164
	ds_read_b128 v[182:185], v164 offset:1024
	ds_read_b128 v[186:189], v164 offset:2048
	ds_read_b128 v[190:193], v164 offset:3072
	ds_read_b128 v[194:197], v164 offset:4096
	ds_read_b128 v[198:201], v164 offset:5120
	ds_read_b128 v[202:205], v164 offset:6144
	ds_read_b128 v[206:209], v164 offset:7168
	global_load_lds_dwordx4 v[210:211], off
	v_lshl_add_u64 v[210:211], s[20:21], 0, v[154:155]
	s_add_i32 m0, s42, 0xe000
	s_nop 0
	global_load_lds_dwordx4 v[210:211], off
	s_waitcnt vmcnt(8)
	s_waitcnt lgkmcnt(0)
	s_barrier
	v_mfma_f32_16x16x32_bf16 v[126:129], v[130:133], v[178:181], v[126:129]
	v_mfma_f32_16x16x32_bf16 v[122:125], v[138:141], v[178:181], v[122:125]
	v_mfma_f32_16x16x32_bf16 v[118:121], v[130:133], v[186:189], v[118:121]
	v_mfma_f32_16x16x32_bf16 v[114:117], v[138:141], v[186:189], v[114:117]
	v_mfma_f32_16x16x32_bf16 v[102:105], v[130:133], v[194:197], v[102:105]
	v_mfma_f32_16x16x32_bf16 v[90:93], v[138:141], v[194:197], v[90:93]
	v_mfma_f32_16x16x32_bf16 v[82:85], v[130:133], v[202:205], v[82:85]
	v_mfma_f32_16x16x32_bf16 v[74:77], v[138:141], v[202:205], v[74:77]
	v_mfma_f32_16x16x32_bf16 v[126:129], v[134:137], v[182:185], v[126:129]
	v_mfma_f32_16x16x32_bf16 v[122:125], v[142:145], v[182:185], v[122:125]
	v_mfma_f32_16x16x32_bf16 v[118:121], v[134:137], v[190:193], v[118:121]
	v_mfma_f32_16x16x32_bf16 v[114:117], v[142:145], v[190:193], v[114:117]
	v_mfma_f32_16x16x32_bf16 v[102:105], v[134:137], v[198:201], v[102:105]
	v_mfma_f32_16x16x32_bf16 v[90:93], v[142:145], v[198:201], v[90:93]
	v_mfma_f32_16x16x32_bf16 v[82:85], v[134:137], v[206:209], v[82:85]
	v_mfma_f32_16x16x32_bf16 v[74:77], v[142:145], v[206:209], v[74:77]
	v_mfma_f32_16x16x32_bf16 v[110:113], v[156:159], v[178:181], v[110:113]
	v_mfma_f32_16x16x32_bf16 v[106:109], v[170:173], v[178:181], v[106:109]
	v_mfma_f32_16x16x32_bf16 v[98:101], v[156:159], v[186:189], v[98:101]
	v_mfma_f32_16x16x32_bf16 v[94:97], v[170:173], v[186:189], v[94:97]
	v_mfma_f32_16x16x32_bf16 v[86:89], v[156:159], v[194:197], v[86:89]
	v_mfma_f32_16x16x32_bf16 v[78:81], v[170:173], v[194:197], v[78:81]
	v_mfma_f32_16x16x32_bf16 v[70:73], v[156:159], v[202:205], v[70:73]
	v_mfma_f32_16x16x32_bf16 v[66:69], v[170:173], v[202:205], v[66:69]
	v_mfma_f32_16x16x32_bf16 v[110:113], v[166:169], v[182:185], v[110:113]
	v_mfma_f32_16x16x32_bf16 v[106:109], v[174:177], v[182:185], v[106:109]
	v_mfma_f32_16x16x32_bf16 v[98:101], v[166:169], v[190:193], v[98:101]
	v_mfma_f32_16x16x32_bf16 v[94:97], v[174:177], v[190:193], v[94:97]
	v_mfma_f32_16x16x32_bf16 v[86:89], v[166:169], v[198:201], v[86:89]
	v_mfma_f32_16x16x32_bf16 v[78:81], v[174:177], v[198:201], v[78:81]
	v_mfma_f32_16x16x32_bf16 v[70:73], v[166:169], v[206:209], v[70:73]
	v_mfma_f32_16x16x32_bf16 v[66:69], v[174:177], v[206:209], v[66:69]
	s_barrier
	s_add_i32 s20, s54, s40
	s_add_u32 s98, s24, 0x80
	s_addc_u32 s99, s25, 0
	s_mov_b32 m0, s20
	ds_read_b128 v[178:181], v164 offset:16384
	ds_read_b128 v[182:185], v164 offset:17408
	ds_read_b128 v[186:189], v164 offset:18432
	ds_read_b128 v[190:193], v164 offset:19456
	ds_read_b128 v[194:197], v164 offset:20480
	ds_read_b128 v[198:201], v164 offset:21504
	ds_read_b128 v[202:205], v164 offset:22528
	ds_read_b128 v[206:209], v164 offset:23552
	global_load_lds_dwordx4 v148, s[24:25]
	s_add_i32 m0, s20, 0x2000
	s_add_u32 s20, s24, 0xb0000
	s_addc_u32 s21, s25, 0
	s_add_i32 s69, s55, s40
	global_load_lds_dwordx4 v146, s[24:25]
	s_mov_b32 m0, s69
	s_nop 0
	global_load_lds_dwordx4 v148, s[20:21]
	s_add_i32 m0, s69, 0x2000
	s_nop 0
	global_load_lds_dwordx4 v146, s[20:21]
	s_add_u32 s100, s26, 0x80
	s_addc_u32 s101, s27, 0
	s_mov_b32 m0, s42
	s_nop 0
	global_load_lds_dwordx4 v148, s[26:27]
	s_mov_b32 m0, s43
	s_nop 0
	global_load_lds_dwordx4 v146, s[26:27]
	s_waitcnt vmcnt(8)
	s_waitcnt lgkmcnt(0)
	s_barrier
	v_mfma_f32_16x16x32_bf16 v[62:65], v[130:133], v[178:181], v[62:65]
	v_mfma_f32_16x16x32_bf16 v[58:61], v[138:141], v[178:181], v[58:61]
	v_mfma_f32_16x16x32_bf16 v[54:57], v[130:133], v[186:189], v[54:57]
	v_mfma_f32_16x16x32_bf16 v[50:53], v[138:141], v[186:189], v[50:53]
	v_mfma_f32_16x16x32_bf16 v[46:49], v[130:133], v[194:197], v[46:49]
	v_mfma_f32_16x16x32_bf16 v[38:41], v[138:141], v[194:197], v[38:41]
	v_mfma_f32_16x16x32_bf16 v[18:21], v[130:133], v[202:205], v[18:21]
	v_mfma_f32_16x16x32_bf16 v[10:13], v[138:141], v[202:205], v[10:13]
	v_mfma_f32_16x16x32_bf16 v[62:65], v[134:137], v[182:185], v[62:65]
	v_mfma_f32_16x16x32_bf16 v[58:61], v[142:145], v[182:185], v[58:61]
	v_mfma_f32_16x16x32_bf16 v[54:57], v[134:137], v[190:193], v[54:57]
	v_mfma_f32_16x16x32_bf16 v[50:53], v[142:145], v[190:193], v[50:53]
	v_mfma_f32_16x16x32_bf16 v[46:49], v[134:137], v[198:201], v[46:49]
	v_mfma_f32_16x16x32_bf16 v[38:41], v[142:145], v[198:201], v[38:41]
	v_mfma_f32_16x16x32_bf16 v[18:21], v[134:137], v[206:209], v[18:21]
	v_mfma_f32_16x16x32_bf16 v[10:13], v[142:145], v[206:209], v[10:13]
	v_mfma_f32_16x16x32_bf16 v[42:45], v[156:159], v[178:181], v[42:45]
	v_mfma_f32_16x16x32_bf16 v[34:37], v[170:173], v[178:181], v[34:37]
	v_mfma_f32_16x16x32_bf16 v[30:33], v[156:159], v[186:189], v[30:33]
	v_mfma_f32_16x16x32_bf16 v[26:29], v[170:173], v[186:189], v[26:29]
	v_mfma_f32_16x16x32_bf16 v[22:25], v[156:159], v[194:197], v[22:25]
	v_mfma_f32_16x16x32_bf16 v[14:17], v[170:173], v[194:197], v[14:17]
	v_mfma_f32_16x16x32_bf16 v[6:9], v[156:159], v[202:205], v[6:9]
	v_mfma_f32_16x16x32_bf16 v[2:5], v[170:173], v[202:205], v[2:5]
	v_mfma_f32_16x16x32_bf16 v[42:45], v[166:169], v[182:185], v[42:45]
	v_mfma_f32_16x16x32_bf16 v[34:37], v[174:177], v[182:185], v[34:37]
	v_mfma_f32_16x16x32_bf16 v[30:33], v[166:169], v[190:193], v[30:33]
	v_mfma_f32_16x16x32_bf16 v[26:29], v[174:177], v[190:193], v[26:29]
	v_mfma_f32_16x16x32_bf16 v[22:25], v[166:169], v[198:201], v[22:25]
	v_mfma_f32_16x16x32_bf16 v[14:17], v[174:177], v[198:201], v[14:17]
	v_mfma_f32_16x16x32_bf16 v[6:9], v[166:169], v[206:209], v[6:9]
	v_mfma_f32_16x16x32_bf16 v[2:5], v[174:177], v[206:209], v[2:5]
	s_barrier
; #define PG8_STAGE(bufoff, gbase, voff) do { _Pragma("unroll") for (int _i = 0; _i < 2; ++_i) \
;         __builtin_amdgcn_global_load_lds((const unsigned*)((const char*)(gbase) + (voff)[_i]), (PG8_LAS unsigned*)(lds + (bufoff) + ldsw + _i * 8192), 16, 0, 0); } while (0)
; #define PG8_LDA(dst, b, h) do { _Pragma("unroll") for (int m = 0; m < 4; ++m) _Pragma("unroll") for (int k = 0; k < 2; ++k) dst[m][k] = *(const PG8_LAS bf16x8*)(lds + PG8_SA(b, h) + aoff + m * 2048 + k * 1024); } while (0)
; #define PG8_LDB(dst, b, h) do { _Pragma("unroll") for (int n = 0; n < 2; ++n) _Pragma("unroll") for (int k = 0; k < 2; ++k) dst[n][k] = *(const PG8_LAS bf16x8*)(lds + PG8_SB(b, h) + boff + n * 2048 + k * 1024); } while (0)
; #define PG8_MMA(ai, bj, At, Bt) do { __builtin_amdgcn_s_setprio(1); _Pragma("unroll") for (int m = 0; m < 4; ++m) _Pragma("unroll") for (int n = 0; n < 2; ++n) _Pragma("unroll") for (int k = 0; k < 2; ++k) \
;         acc[ai][bj][m][n] = __builtin_amdgcn_mfma_f32_16x16x32_bf16(Bt[n][k], At[m][k], acc[ai][bj][m][n], 0, 0, 0); __builtin_amdgcn_s_setprio(0); } while (0)
; #define PG8_WAIT_V(n) asm volatile("s_waitcnt vmcnt(" #n ")" ::: "memory")
; #define PG8_WAIT_L(n) asm volatile("s_waitcnt lgkmcnt(" #n ")" ::: "memory")
; #define PG8_BAR __builtin_amdgcn_s_barrier()
; #define PG8_SCHED __builtin_amdgcn_sched_barrier(0)
; template <class Epi, class Sched, bool ALIGN_EPI = false, bool SP2 = false>
; __device__ __forceinline__ void gemm_phase(PG8_LAS unsigned char* lds, const Gemm g, const Sched& S, const Epi& E) {
;     ...
;             PG8_LDB(B0, 1, 0); PG8_LDB(B1, 1, 1); PG8_SCHED; PG8_LDA(At, 1, 0); PG8_STAGE(PG8_SA(0, 1), a2 + hstepA, voffA);
;             PG8_WAIT_V(8); PG8_WAIT_L(0); PG8_BAR; PG8_MMA(0, 0, At, B0); PG8_MMA(0, 1, At, B1); PG8_BAR; PG8_SCHED;
;             PG8_LDA(At, 1, 1); PG8_STAGE(PG8_SB(1, 0), b3, voffB); PG8_STAGE(PG8_SB(1, 1), b3 + hstepB, voffB); PG8_STAGE(PG8_SA(1, 0), a3, voffA);
;             PG8_WAIT_V(8); PG8_WAIT_L(0); PG8_BAR; PG8_MMA(1, 0, At, B0); PG8_MMA(1, 1, At, B1); PG8_BAR; PG8_SCHED;
;     ...
;         if constexpr (ALIGN_EPI) { if (wr == 0) PG8_BAR; }
	s_add_i32 s69, 0, 0x18000
	s_add_i32 s70, 0, 0x1c000
	v_add_u32_e32 v142, s69, v1
	v_add_u32_e32 v174, s70, v1
	ds_read_b128 v[130:133], v142
	ds_read_b128 v[134:137], v142 offset:1024
	ds_read_b128 v[138:141], v142 offset:2048
	ds_read_b128 v[142:145], v142 offset:3072
	ds_read_b128 v[156:159], v174
	ds_read_b128 v[166:169], v174 offset:1024
	ds_read_b128 v[170:173], v174 offset:2048
	ds_read_b128 v[174:177], v174 offset:3072
	s_add_u32 s20, s26, 0xb0000
	s_addc_u32 s21, s27, 0
	s_mov_b32 m0, s44
	ds_read_b128 v[178:181], v164 offset:32768
	ds_read_b128 v[182:185], v164 offset:33792
	ds_read_b128 v[186:189], v164 offset:34816
	ds_read_b128 v[190:193], v164 offset:35840
	ds_read_b128 v[194:197], v164 offset:36864
	ds_read_b128 v[198:201], v164 offset:37888
	ds_read_b128 v[202:205], v164 offset:38912
	ds_read_b128 v[206:209], v164 offset:39936
	global_load_lds_dwordx4 v148, s[20:21]
	s_mov_b32 m0, s45
	s_nop 0
	global_load_lds_dwordx4 v146, s[20:21]
	s_waitcnt vmcnt(8)
	s_waitcnt lgkmcnt(0)
	s_barrier
	v_mfma_f32_16x16x32_bf16 v[126:129], v[130:133], v[178:181], v[126:129]
	v_mfma_f32_16x16x32_bf16 v[122:125], v[138:141], v[178:181], v[122:125]
	v_mfma_f32_16x16x32_bf16 v[118:121], v[130:133], v[186:189], v[118:121]
	v_mfma_f32_16x16x32_bf16 v[114:117], v[138:141], v[186:189], v[114:117]
	v_mfma_f32_16x16x32_bf16 v[102:105], v[130:133], v[194:197], v[102:105]
	v_mfma_f32_16x16x32_bf16 v[90:93], v[138:141], v[194:197], v[90:93]
	v_mfma_f32_16x16x32_bf16 v[82:85], v[130:133], v[202:205], v[82:85]
	v_mfma_f32_16x16x32_bf16 v[74:77], v[138:141], v[202:205], v[74:77]
	v_mfma_f32_16x16x32_bf16 v[126:129], v[134:137], v[182:185], v[126:129]
	v_mfma_f32_16x16x32_bf16 v[122:125], v[142:145], v[182:185], v[122:125]
	v_mfma_f32_16x16x32_bf16 v[118:121], v[134:137], v[190:193], v[118:121]
	v_mfma_f32_16x16x32_bf16 v[114:117], v[142:145], v[190:193], v[114:117]
	v_mfma_f32_16x16x32_bf16 v[102:105], v[134:137], v[198:201], v[102:105]
	v_mfma_f32_16x16x32_bf16 v[90:93], v[142:145], v[198:201], v[90:93]
	v_mfma_f32_16x16x32_bf16 v[82:85], v[134:137], v[206:209], v[82:85]
	v_mfma_f32_16x16x32_bf16 v[74:77], v[142:145], v[206:209], v[74:77]
	v_mfma_f32_16x16x32_bf16 v[110:113], v[156:159], v[178:181], v[110:113]
	v_mfma_f32_16x16x32_bf16 v[106:109], v[170:173], v[178:181], v[106:109]
	v_mfma_f32_16x16x32_bf16 v[98:101], v[156:159], v[186:189], v[98:101]
	v_mfma_f32_16x16x32_bf16 v[94:97], v[170:173], v[186:189], v[94:97]
	v_mfma_f32_16x16x32_bf16 v[86:89], v[156:159], v[194:197], v[86:89]
	v_mfma_f32_16x16x32_bf16 v[78:81], v[170:173], v[194:197], v[78:81]
	v_mfma_f32_16x16x32_bf16 v[70:73], v[156:159], v[202:205], v[70:73]
	v_mfma_f32_16x16x32_bf16 v[66:69], v[170:173], v[202:205], v[66:69]
	v_mfma_f32_16x16x32_bf16 v[110:113], v[166:169], v[182:185], v[110:113]
	v_mfma_f32_16x16x32_bf16 v[106:109], v[174:177], v[182:185], v[106:109]
	v_mfma_f32_16x16x32_bf16 v[98:101], v[166:169], v[190:193], v[98:101]
	v_mfma_f32_16x16x32_bf16 v[94:97], v[174:177], v[190:193], v[94:97]
	v_mfma_f32_16x16x32_bf16 v[86:89], v[166:169], v[198:201], v[86:89]
	v_mfma_f32_16x16x32_bf16 v[78:81], v[174:177], v[198:201], v[78:81]
	v_mfma_f32_16x16x32_bf16 v[70:73], v[166:169], v[206:209], v[70:73]
	v_mfma_f32_16x16x32_bf16 v[66:69], v[174:177], v[206:209], v[66:69]
	s_barrier
	s_add_i32 s20, s69, s40
	s_mov_b32 m0, s20
	ds_read_b128 v[178:181], v164 offset:49152
	ds_read_b128 v[182:185], v164 offset:50176
	ds_read_b128 v[186:189], v164 offset:51200
	ds_read_b128 v[190:193], v164 offset:52224
	ds_read_b128 v[194:197], v164 offset:53248
	ds_read_b128 v[198:201], v164 offset:54272
	ds_read_b128 v[202:205], v164 offset:55296
	ds_read_b128 v[206:209], v164 offset:56320
	global_load_lds_dwordx4 v148, s[98:99]
	s_add_i32 m0, s20, 0x2000
	s_add_u32 s20, s24, 0xb0080
	s_addc_u32 s21, s25, 0
	s_add_i32 s24, s70, s40
	global_load_lds_dwordx4 v146, s[98:99]
	s_mov_b32 m0, s24
	s_nop 0
	global_load_lds_dwordx4 v148, s[20:21]
	s_add_i32 m0, s24, 0x2000
	s_nop 0
	global_load_lds_dwordx4 v146, s[20:21]
	s_mov_b32 m0, s51
	s_nop 0
	global_load_lds_dwordx4 v148, s[100:101]
	s_mov_b32 m0, s52
	s_nop 0
	global_load_lds_dwordx4 v146, s[100:101]
	s_waitcnt vmcnt(8)
	s_waitcnt lgkmcnt(0)
	s_barrier
	v_mfma_f32_16x16x32_bf16 v[62:65], v[130:133], v[178:181], v[62:65]
	v_mfma_f32_16x16x32_bf16 v[58:61], v[138:141], v[178:181], v[58:61]
	v_mfma_f32_16x16x32_bf16 v[54:57], v[130:133], v[186:189], v[54:57]
	v_mfma_f32_16x16x32_bf16 v[50:53], v[138:141], v[186:189], v[50:53]
	v_mfma_f32_16x16x32_bf16 v[46:49], v[130:133], v[194:197], v[46:49]
	v_mfma_f32_16x16x32_bf16 v[38:41], v[138:141], v[194:197], v[38:41]
	v_mfma_f32_16x16x32_bf16 v[18:21], v[130:133], v[202:205], v[18:21]
	v_mfma_f32_16x16x32_bf16 v[10:13], v[138:141], v[202:205], v[10:13]
	v_mfma_f32_16x16x32_bf16 v[62:65], v[134:137], v[182:185], v[62:65]
	v_mfma_f32_16x16x32_bf16 v[58:61], v[142:145], v[182:185], v[58:61]
	v_mfma_f32_16x16x32_bf16 v[54:57], v[134:137], v[190:193], v[54:57]
	v_mfma_f32_16x16x32_bf16 v[50:53], v[142:145], v[190:193], v[50:53]
	v_mfma_f32_16x16x32_bf16 v[46:49], v[134:137], v[198:201], v[46:49]
	v_mfma_f32_16x16x32_bf16 v[38:41], v[142:145], v[198:201], v[38:41]
	v_mfma_f32_16x16x32_bf16 v[18:21], v[134:137], v[206:209], v[18:21]
	v_mfma_f32_16x16x32_bf16 v[10:13], v[142:145], v[206:209], v[10:13]
	v_mfma_f32_16x16x32_bf16 v[42:45], v[156:159], v[178:181], v[42:45]
	v_mfma_f32_16x16x32_bf16 v[34:37], v[170:173], v[178:181], v[34:37]
	v_mfma_f32_16x16x32_bf16 v[30:33], v[156:159], v[186:189], v[30:33]
	v_mfma_f32_16x16x32_bf16 v[26:29], v[170:173], v[186:189], v[26:29]
	v_mfma_f32_16x16x32_bf16 v[22:25], v[156:159], v[194:197], v[22:25]
	v_mfma_f32_16x16x32_bf16 v[14:17], v[170:173], v[194:197], v[14:17]
	v_mfma_f32_16x16x32_bf16 v[6:9], v[156:159], v[202:205], v[6:9]
	v_mfma_f32_16x16x32_bf16 v[2:5], v[170:173], v[202:205], v[2:5]
	v_mfma_f32_16x16x32_bf16 v[42:45], v[166:169], v[182:185], v[42:45]
	v_mfma_f32_16x16x32_bf16 v[34:37], v[174:177], v[182:185], v[34:37]
	v_mfma_f32_16x16x32_bf16 v[30:33], v[166:169], v[190:193], v[30:33]
	v_mfma_f32_16x16x32_bf16 v[26:29], v[174:177], v[190:193], v[26:29]
	v_mfma_f32_16x16x32_bf16 v[22:25], v[166:169], v[198:201], v[22:25]
	v_mfma_f32_16x16x32_bf16 v[14:17], v[174:177], v[198:201], v[14:17]
	v_mfma_f32_16x16x32_bf16 v[6:9], v[166:169], v[206:209], v[6:9]
	v_mfma_f32_16x16x32_bf16 v[2:5], v[174:177], v[206:209], v[2:5]
	s_barrier
	s_add_i32 s68, s68, 2
	s_add_u32 s66, s66, 0x100
	s_addc_u32 s67, s67, 0
	s_cmp_gt_u32 s68, 5
	s_mov_b64 s[20:21], s[22:23]
	s_cbranch_scc0 .LBB0_1897
	s_and_b64 vcc, exec, s[10:11]
	s_cbranch_vccz .LBB0_1900
	s_barrier

; #define PG8_STAGE(bufoff, gbase, voff) do { _Pragma("unroll") for (int _i = 0; _i < 2; ++_i) \
;         __builtin_amdgcn_global_load_lds((const unsigned*)((const char*)(gbase) + (voff)[_i]), (PG8_LAS unsigned*)(lds + (bufoff) + ldsw + _i * 8192), 16, 0, 0); } while (0)
; #define PG8_LDA(dst, b, h) do { _Pragma("unroll") for (int m = 0; m < 4; ++m) _Pragma("unroll") for (int k = 0; k < 2; ++k) dst[m][k] = *(const PG8_LAS bf16x8*)(lds + PG8_SA(b, h) + aoff + m * 2048 + k * 1024); } while (0)
; #define PG8_LDB(dst, b, h) do { _Pragma("unroll") for (int n = 0; n < 2; ++n) _Pragma("unroll") for (int k = 0; k < 2; ++k) dst[n][k] = *(const PG8_LAS bf16x8*)(lds + PG8_SB(b, h) + boff + n * 2048 + k * 1024); } while (0)
; #define PG8_MMA(ai, bj, At, Bt) do { __builtin_amdgcn_s_setprio(1); _Pragma("unroll") for (int m = 0; m < 4; ++m) _Pragma("unroll") for (int n = 0; n < 2; ++n) _Pragma("unroll") for (int k = 0; k < 2; ++k) \
;         acc[ai][bj][m][n] = __builtin_amdgcn_mfma_f32_16x16x32_bf16(Bt[n][k], At[m][k], acc[ai][bj][m][n], 0, 0, 0); __builtin_amdgcn_s_setprio(0); } while (0)
; #define PG8_WAIT_V(n) asm volatile("s_waitcnt vmcnt(" #n ")" ::: "memory")
; #define PG8_WAIT_L(n) asm volatile("s_waitcnt lgkmcnt(" #n ")" ::: "memory")
; #define PG8_BAR __builtin_amdgcn_s_barrier()
; #define PG8_SCHED __builtin_amdgcn_sched_barrier(0)
; template <class Epi, class Sched, bool ALIGN_EPI = false, bool SP2 = false>
; __device__ __forceinline__ void gemm_phase(PG8_LAS unsigned char* lds, const Gemm g, const Sched& S, const Epi& E) {
;     ...
;             PG8_LDB(B0, 0, 0); PG8_LDB(B1, 0, 1); PG8_SCHED; PG8_LDA(At, 0, 0); PG8_STAGE(PG8_SA(1, 1), a1 + hstepA, voffA);
;             PG8_WAIT_V(8); PG8_WAIT_L(0); PG8_BAR; PG8_MMA(0, 0, At, B0); PG8_MMA(0, 1, At, B1); PG8_BAR; PG8_SCHED;
;             PG8_LDA(At, 0, 1); PG8_STAGE(PG8_SB(0, 0), b2, voffB); PG8_STAGE(PG8_SB(0, 1), b2 + hstepB, voffB); PG8_STAGE(PG8_SA(0, 0), a2, voffA);
;             PG8_WAIT_V(8); PG8_WAIT_L(0); PG8_BAR; PG8_MMA(1, 0, At, B0); PG8_MMA(1, 1, At, B1); PG8_BAR; PG8_SCHED;
.LBB0_2153:
	ds_read_b128 v[148:151], v156
	ds_read_b128 v[160:163], v156 offset:1024
	ds_read_b128 v[164:167], v156 offset:2048
	ds_read_b128 v[168:171], v156 offset:3072
	ds_read_b128 v[172:175], v157
	ds_read_b128 v[176:179], v157 offset:1024
	ds_read_b128 v[180:183], v157 offset:2048
	ds_read_b128 v[184:187], v157 offset:3072
	s_add_u32 s36, s34, 0xfffc0080
	s_addc_u32 s37, s35, -1
	s_cmp_eq_u32 s59, 12
	s_cselect_b32 s39, s5, s37
	s_cselect_b32 s38, s25, s36
	s_cselect_b32 s37, s23, s58
	s_cselect_b32 s36, s31, s57
	s_add_i32 m0, s44, 0xc000
	ds_read_b128 v[188:191], v158
	ds_read_b128 v[192:195], v158 offset:1024
	ds_read_b128 v[196:199], v158 offset:2048
	ds_read_b128 v[200:203], v158 offset:3072
	ds_read_b128 v[204:207], v158 offset:4096
	ds_read_b128 v[208:211], v158 offset:5120
	ds_read_b128 v[212:215], v158 offset:6144
	ds_read_b128 v[216:219], v158 offset:7168
	global_load_lds_dwordx4 v140, s[34:35]
	s_add_i32 m0, s44, 0xe000
	s_nop 0
	global_load_lds_dwordx4 v142, s[34:35]
	s_waitcnt vmcnt(8)
	s_waitcnt lgkmcnt(0)
	s_barrier
	v_mfma_f32_16x16x32_bf16 v[126:129], v[148:151], v[188:191], v[126:129]
	v_mfma_f32_16x16x32_bf16 v[122:125], v[164:167], v[188:191], v[122:125]
	v_mfma_f32_16x16x32_bf16 v[110:113], v[148:151], v[196:199], v[110:113]
	v_mfma_f32_16x16x32_bf16 v[106:109], v[164:167], v[196:199], v[106:109]
	v_mfma_f32_16x16x32_bf16 v[94:97], v[148:151], v[204:207], v[94:97]
	v_mfma_f32_16x16x32_bf16 v[90:93], v[164:167], v[204:207], v[90:93]
	v_mfma_f32_16x16x32_bf16 v[78:81], v[148:151], v[212:215], v[78:81]
	v_mfma_f32_16x16x32_bf16 v[74:77], v[164:167], v[212:215], v[74:77]
	v_mfma_f32_16x16x32_bf16 v[126:129], v[160:163], v[192:195], v[126:129]
	v_mfma_f32_16x16x32_bf16 v[122:125], v[168:171], v[192:195], v[122:125]
	v_mfma_f32_16x16x32_bf16 v[110:113], v[160:163], v[200:203], v[110:113]
	v_mfma_f32_16x16x32_bf16 v[106:109], v[168:171], v[200:203], v[106:109]
	v_mfma_f32_16x16x32_bf16 v[94:97], v[160:163], v[208:211], v[94:97]
	v_mfma_f32_16x16x32_bf16 v[90:93], v[168:171], v[208:211], v[90:93]
	v_mfma_f32_16x16x32_bf16 v[78:81], v[160:163], v[216:219], v[78:81]
	v_mfma_f32_16x16x32_bf16 v[74:77], v[168:171], v[216:219], v[74:77]
	v_mfma_f32_16x16x32_bf16 v[118:121], v[172:175], v[188:191], v[118:121]
	v_mfma_f32_16x16x32_bf16 v[114:117], v[180:183], v[188:191], v[114:117]
	v_mfma_f32_16x16x32_bf16 v[102:105], v[172:175], v[196:199], v[102:105]
	v_mfma_f32_16x16x32_bf16 v[98:101], v[180:183], v[196:199], v[98:101]
	v_mfma_f32_16x16x32_bf16 v[86:89], v[172:175], v[204:207], v[86:89]
	v_mfma_f32_16x16x32_bf16 v[82:85], v[180:183], v[204:207], v[82:85]
	v_mfma_f32_16x16x32_bf16 v[70:73], v[172:175], v[212:215], v[70:73]
	v_mfma_f32_16x16x32_bf16 v[66:69], v[180:183], v[212:215], v[66:69]
	v_mfma_f32_16x16x32_bf16 v[118:121], v[176:179], v[192:195], v[118:121]
	v_mfma_f32_16x16x32_bf16 v[114:117], v[184:187], v[192:195], v[114:117]
	v_mfma_f32_16x16x32_bf16 v[102:105], v[176:179], v[200:203], v[102:105]
	v_mfma_f32_16x16x32_bf16 v[98:101], v[184:187], v[200:203], v[98:101]
	v_mfma_f32_16x16x32_bf16 v[86:89], v[176:179], v[208:211], v[86:89]
	v_mfma_f32_16x16x32_bf16 v[82:85], v[184:187], v[208:211], v[82:85]
	v_mfma_f32_16x16x32_bf16 v[70:73], v[176:179], v[216:219], v[70:73]
	v_mfma_f32_16x16x32_bf16 v[66:69], v[184:187], v[216:219], v[66:69]
	s_barrier
	s_add_i32 s60, s54, s43
	s_add_u32 s98, s36, 0x80
	s_addc_u32 s99, s37, 0
	s_mov_b32 m0, s60
	ds_read_b128 v[188:191], v158 offset:16384
	ds_read_b128 v[192:195], v158 offset:17408
	ds_read_b128 v[196:199], v158 offset:18432
	ds_read_b128 v[200:203], v158 offset:19456
	ds_read_b128 v[204:207], v158 offset:20480
	ds_read_b128 v[208:211], v158 offset:21504
	ds_read_b128 v[212:215], v158 offset:22528
	ds_read_b128 v[216:219], v158 offset:23552
	global_load_lds_dwordx4 v132, s[36:37]
	s_add_i32 m0, s60, 0x2000
	s_add_u32 s60, s36, 0x40000
	s_addc_u32 s61, s37, 0
	s_add_i32 s62, s55, s43
	global_load_lds_dwordx4 v136, s[36:37]
	s_mov_b32 m0, s62
	s_nop 0
	global_load_lds_dwordx4 v132, s[60:61]
	s_add_i32 m0, s62, 0x2000
	s_nop 0
	global_load_lds_dwordx4 v136, s[60:61]
	s_add_u32 s100, s38, 0x80
	s_addc_u32 s101, s39, 0
	s_mov_b32 m0, s44
	s_nop 0
	global_load_lds_dwordx4 v130, s[38:39]
	s_mov_b32 m0, s45
	s_nop 0
	global_load_lds_dwordx4 v134, s[38:39]
	s_waitcnt vmcnt(8)
	s_waitcnt lgkmcnt(0)
	s_barrier
	v_mfma_f32_16x16x32_bf16 v[62:65], v[148:151], v[188:191], v[62:65]
	v_mfma_f32_16x16x32_bf16 v[58:61], v[164:167], v[188:191], v[58:61]
	v_mfma_f32_16x16x32_bf16 v[46:49], v[148:151], v[196:199], v[46:49]
	v_mfma_f32_16x16x32_bf16 v[42:45], v[164:167], v[196:199], v[42:45]
	v_mfma_f32_16x16x32_bf16 v[30:33], v[148:151], v[204:207], v[30:33]
	v_mfma_f32_16x16x32_bf16 v[26:29], v[164:167], v[204:207], v[26:29]
	v_mfma_f32_16x16x32_bf16 v[14:17], v[148:151], v[212:215], v[14:17]
	v_mfma_f32_16x16x32_bf16 v[10:13], v[164:167], v[212:215], v[10:13]
	v_mfma_f32_16x16x32_bf16 v[62:65], v[160:163], v[192:195], v[62:65]
	v_mfma_f32_16x16x32_bf16 v[58:61], v[168:171], v[192:195], v[58:61]
	v_mfma_f32_16x16x32_bf16 v[46:49], v[160:163], v[200:203], v[46:49]
	v_mfma_f32_16x16x32_bf16 v[42:45], v[168:171], v[200:203], v[42:45]
	v_mfma_f32_16x16x32_bf16 v[30:33], v[160:163], v[208:211], v[30:33]
	v_mfma_f32_16x16x32_bf16 v[26:29], v[168:171], v[208:211], v[26:29]
	v_mfma_f32_16x16x32_bf16 v[14:17], v[160:163], v[216:219], v[14:17]
	v_mfma_f32_16x16x32_bf16 v[10:13], v[168:171], v[216:219], v[10:13]
	v_mfma_f32_16x16x32_bf16 v[54:57], v[172:175], v[188:191], v[54:57]
	v_mfma_f32_16x16x32_bf16 v[50:53], v[180:183], v[188:191], v[50:53]
	v_mfma_f32_16x16x32_bf16 v[38:41], v[172:175], v[196:199], v[38:41]
	v_mfma_f32_16x16x32_bf16 v[34:37], v[180:183], v[196:199], v[34:37]
	v_mfma_f32_16x16x32_bf16 v[22:25], v[172:175], v[204:207], v[22:25]
	v_mfma_f32_16x16x32_bf16 v[18:21], v[180:183], v[204:207], v[18:21]
	v_mfma_f32_16x16x32_bf16 v[6:9], v[172:175], v[212:215], v[6:9]
	v_mfma_f32_16x16x32_bf16 v[2:5], v[180:183], v[212:215], v[2:5]
	v_mfma_f32_16x16x32_bf16 v[54:57], v[176:179], v[192:195], v[54:57]
	v_mfma_f32_16x16x32_bf16 v[50:53], v[184:187], v[192:195], v[50:53]
	v_mfma_f32_16x16x32_bf16 v[38:41], v[176:179], v[200:203], v[38:41]
	v_mfma_f32_16x16x32_bf16 v[34:37], v[184:187], v[200:203], v[34:37]
	v_mfma_f32_16x16x32_bf16 v[22:25], v[176:179], v[208:211], v[22:25]
	v_mfma_f32_16x16x32_bf16 v[18:21], v[184:187], v[208:211], v[18:21]
	v_mfma_f32_16x16x32_bf16 v[6:9], v[176:179], v[216:219], v[6:9]
	v_mfma_f32_16x16x32_bf16 v[2:5], v[184:187], v[216:219], v[2:5]
	s_barrier
; #define PG8_STAGE(bufoff, gbase, voff) do { _Pragma("unroll") for (int _i = 0; _i < 2; ++_i) \
;         __builtin_amdgcn_global_load_lds((const unsigned*)((const char*)(gbase) + (voff)[_i]), (PG8_LAS unsigned*)(lds + (bufoff) + ldsw + _i * 8192), 16, 0, 0); } while (0)
; #define PG8_LDA(dst, b, h) do { _Pragma("unroll") for (int m = 0; m < 4; ++m) _Pragma("unroll") for (int k = 0; k < 2; ++k) dst[m][k] = *(const PG8_LAS bf16x8*)(lds + PG8_SA(b, h) + aoff + m * 2048 + k * 1024); } while (0)
; #define PG8_LDB(dst, b, h) do { _Pragma("unroll") for (int n = 0; n < 2; ++n) _Pragma("unroll") for (int k = 0; k < 2; ++k) dst[n][k] = *(const PG8_LAS bf16x8*)(lds + PG8_SB(b, h) + boff + n * 2048 + k * 1024); } while (0)
; #define PG8_MMA(ai, bj, At, Bt) do { __builtin_amdgcn_s_setprio(1); _Pragma("unroll") for (int m = 0; m < 4; ++m) _Pragma("unroll") for (int n = 0; n < 2; ++n) _Pragma("unroll") for (int k = 0; k < 2; ++k) \
;         acc[ai][bj][m][n] = __builtin_amdgcn_mfma_f32_16x16x32_bf16(Bt[n][k], At[m][k], acc[ai][bj][m][n], 0, 0, 0); __builtin_amdgcn_s_setprio(0); } while (0)
; #define PG8_WAIT_V(n) asm volatile("s_waitcnt vmcnt(" #n ")" ::: "memory")
; #define PG8_WAIT_L(n) asm volatile("s_waitcnt lgkmcnt(" #n ")" ::: "memory")
; #define PG8_BAR __builtin_amdgcn_s_barrier()
; #define PG8_SCHED __builtin_amdgcn_sched_barrier(0)
; template <class Epi, class Sched, bool ALIGN_EPI = false, bool SP2 = false>
; __device__ __forceinline__ void gemm_phase(PG8_LAS unsigned char* lds, const Gemm g, const Sched& S, const Epi& E) {
;     ...
;             PG8_LDB(B0, 1, 0); PG8_LDB(B1, 1, 1); PG8_SCHED; PG8_LDA(At, 1, 0); PG8_STAGE(PG8_SA(0, 1), a2 + hstepA, voffA);
;             PG8_WAIT_V(8); PG8_WAIT_L(0); PG8_BAR; PG8_MMA(0, 0, At, B0); PG8_MMA(0, 1, At, B1); PG8_BAR; PG8_SCHED;
;             PG8_LDA(At, 1, 1); PG8_STAGE(PG8_SB(1, 0), b3, voffB); PG8_STAGE(PG8_SB(1, 1), b3 + hstepB, voffB); PG8_STAGE(PG8_SA(1, 0), a3, voffA);
;             PG8_WAIT_V(8); PG8_WAIT_L(0); PG8_BAR; PG8_MMA(1, 0, At, B0); PG8_MMA(1, 1, At, B1); PG8_BAR; PG8_SCHED;
;     ...
;         if constexpr (ALIGN_EPI) { if (wr == 0) PG8_BAR; }
	s_add_i32 s60, 0, 0x18000
	v_add_u32_e32 v138, s60, v154
	s_add_i32 s61, 0, 0x1c000
	ds_read_b128 v[148:151], v138
	ds_read_b128 v[160:163], v138 offset:1024
	ds_read_b128 v[164:167], v138 offset:2048
	ds_read_b128 v[168:171], v138 offset:3072
	v_add_u32_e32 v138, s61, v154
	ds_read_b128 v[172:175], v138
	ds_read_b128 v[176:179], v138 offset:1024
	ds_read_b128 v[180:183], v138 offset:2048
	ds_read_b128 v[184:187], v138 offset:3072
	s_add_u32 s38, s38, 0x40000
	s_addc_u32 s39, s39, 0
	s_mov_b32 m0, s46
	ds_read_b128 v[188:191], v158 offset:32768
	ds_read_b128 v[192:195], v158 offset:33792
	ds_read_b128 v[196:199], v158 offset:34816
	ds_read_b128 v[200:203], v158 offset:35840
	ds_read_b128 v[204:207], v158 offset:36864
	ds_read_b128 v[208:211], v158 offset:37888
	ds_read_b128 v[212:215], v158 offset:38912
	ds_read_b128 v[216:219], v158 offset:39936
	global_load_lds_dwordx4 v130, s[38:39]
	s_mov_b32 m0, s47
	s_nop 0
	global_load_lds_dwordx4 v134, s[38:39]
	s_waitcnt vmcnt(8)
	s_waitcnt lgkmcnt(0)
	s_barrier
	v_mfma_f32_16x16x32_bf16 v[126:129], v[148:151], v[188:191], v[126:129]
	v_mfma_f32_16x16x32_bf16 v[122:125], v[164:167], v[188:191], v[122:125]
	v_mfma_f32_16x16x32_bf16 v[110:113], v[148:151], v[196:199], v[110:113]
	v_mfma_f32_16x16x32_bf16 v[106:109], v[164:167], v[196:199], v[106:109]
	v_mfma_f32_16x16x32_bf16 v[94:97], v[148:151], v[204:207], v[94:97]
	v_mfma_f32_16x16x32_bf16 v[90:93], v[164:167], v[204:207], v[90:93]
	v_mfma_f32_16x16x32_bf16 v[78:81], v[148:151], v[212:215], v[78:81]
	v_mfma_f32_16x16x32_bf16 v[74:77], v[164:167], v[212:215], v[74:77]
	v_mfma_f32_16x16x32_bf16 v[126:129], v[160:163], v[192:195], v[126:129]
	v_mfma_f32_16x16x32_bf16 v[122:125], v[168:171], v[192:195], v[122:125]
	v_mfma_f32_16x16x32_bf16 v[110:113], v[160:163], v[200:203], v[110:113]
	v_mfma_f32_16x16x32_bf16 v[106:109], v[168:171], v[200:203], v[106:109]
	v_mfma_f32_16x16x32_bf16 v[94:97], v[160:163], v[208:211], v[94:97]
	v_mfma_f32_16x16x32_bf16 v[90:93], v[168:171], v[208:211], v[90:93]
	v_mfma_f32_16x16x32_bf16 v[78:81], v[160:163], v[216:219], v[78:81]
	v_mfma_f32_16x16x32_bf16 v[74:77], v[168:171], v[216:219], v[74:77]
	v_mfma_f32_16x16x32_bf16 v[118:121], v[172:175], v[188:191], v[118:121]
	v_mfma_f32_16x16x32_bf16 v[114:117], v[180:183], v[188:191], v[114:117]
	v_mfma_f32_16x16x32_bf16 v[102:105], v[172:175], v[196:199], v[102:105]
	v_mfma_f32_16x16x32_bf16 v[98:101], v[180:183], v[196:199], v[98:101]
	v_mfma_f32_16x16x32_bf16 v[86:89], v[172:175], v[204:207], v[86:89]
	v_mfma_f32_16x16x32_bf16 v[82:85], v[180:183], v[204:207], v[82:85]
	v_mfma_f32_16x16x32_bf16 v[70:73], v[172:175], v[212:215], v[70:73]
	v_mfma_f32_16x16x32_bf16 v[66:69], v[180:183], v[212:215], v[66:69]
	v_mfma_f32_16x16x32_bf16 v[118:121], v[176:179], v[192:195], v[118:121]
	v_mfma_f32_16x16x32_bf16 v[114:117], v[184:187], v[192:195], v[114:117]
	v_mfma_f32_16x16x32_bf16 v[102:105], v[176:179], v[200:203], v[102:105]
	v_mfma_f32_16x16x32_bf16 v[98:101], v[184:187], v[200:203], v[98:101]
	v_mfma_f32_16x16x32_bf16 v[86:89], v[176:179], v[208:211], v[86:89]
	v_mfma_f32_16x16x32_bf16 v[82:85], v[184:187], v[208:211], v[82:85]
	v_mfma_f32_16x16x32_bf16 v[70:73], v[176:179], v[216:219], v[70:73]
	v_mfma_f32_16x16x32_bf16 v[66:69], v[184:187], v[216:219], v[66:69]
	s_barrier
	s_add_i32 s38, s60, s43
	s_mov_b32 m0, s38
	ds_read_b128 v[188:191], v158 offset:49152
	ds_read_b128 v[192:195], v158 offset:50176
	ds_read_b128 v[196:199], v158 offset:51200
	ds_read_b128 v[200:203], v158 offset:52224
	ds_read_b128 v[204:207], v158 offset:53248
	ds_read_b128 v[208:211], v158 offset:54272
	ds_read_b128 v[212:215], v158 offset:55296
	ds_read_b128 v[216:219], v158 offset:56320
	global_load_lds_dwordx4 v132, s[98:99]
	s_add_i32 m0, s38, 0x2000
	s_add_u32 s36, s36, 0x40080
	s_addc_u32 s37, s37, 0
	s_add_i32 s38, s61, s43
	global_load_lds_dwordx4 v136, s[98:99]
	s_mov_b32 m0, s38
	s_nop 0
	global_load_lds_dwordx4 v132, s[36:37]
	s_add_i32 m0, s38, 0x2000
	s_nop 0
	global_load_lds_dwordx4 v136, s[36:37]
	s_mov_b32 m0, s49
	s_nop 0
	global_load_lds_dwordx4 v130, s[100:101]
	s_mov_b32 m0, s50
	s_nop 0
	global_load_lds_dwordx4 v134, s[100:101]
	s_waitcnt vmcnt(8)
	s_waitcnt lgkmcnt(0)
	s_barrier
	v_mfma_f32_16x16x32_bf16 v[62:65], v[148:151], v[188:191], v[62:65]
	v_mfma_f32_16x16x32_bf16 v[58:61], v[164:167], v[188:191], v[58:61]
	v_mfma_f32_16x16x32_bf16 v[46:49], v[148:151], v[196:199], v[46:49]
	v_mfma_f32_16x16x32_bf16 v[42:45], v[164:167], v[196:199], v[42:45]
	v_mfma_f32_16x16x32_bf16 v[30:33], v[148:151], v[204:207], v[30:33]
	v_mfma_f32_16x16x32_bf16 v[26:29], v[164:167], v[204:207], v[26:29]
	v_mfma_f32_16x16x32_bf16 v[14:17], v[148:151], v[212:215], v[14:17]
	v_mfma_f32_16x16x32_bf16 v[10:13], v[164:167], v[212:215], v[10:13]
	v_mfma_f32_16x16x32_bf16 v[62:65], v[160:163], v[192:195], v[62:65]
	v_mfma_f32_16x16x32_bf16 v[58:61], v[168:171], v[192:195], v[58:61]
	v_mfma_f32_16x16x32_bf16 v[46:49], v[160:163], v[200:203], v[46:49]
	v_mfma_f32_16x16x32_bf16 v[42:45], v[168:171], v[200:203], v[42:45]
	v_mfma_f32_16x16x32_bf16 v[30:33], v[160:163], v[208:211], v[30:33]
	v_mfma_f32_16x16x32_bf16 v[26:29], v[168:171], v[208:211], v[26:29]
	v_mfma_f32_16x16x32_bf16 v[14:17], v[160:163], v[216:219], v[14:17]
	v_mfma_f32_16x16x32_bf16 v[10:13], v[168:171], v[216:219], v[10:13]
	v_mfma_f32_16x16x32_bf16 v[54:57], v[172:175], v[188:191], v[54:57]
	v_mfma_f32_16x16x32_bf16 v[50:53], v[180:183], v[188:191], v[50:53]
	v_mfma_f32_16x16x32_bf16 v[38:41], v[172:175], v[196:199], v[38:41]
	v_mfma_f32_16x16x32_bf16 v[34:37], v[180:183], v[196:199], v[34:37]
	v_mfma_f32_16x16x32_bf16 v[22:25], v[172:175], v[204:207], v[22:25]
	v_mfma_f32_16x16x32_bf16 v[18:21], v[180:183], v[204:207], v[18:21]
	v_mfma_f32_16x16x32_bf16 v[6:9], v[172:175], v[212:215], v[6:9]
	v_mfma_f32_16x16x32_bf16 v[2:5], v[180:183], v[212:215], v[2:5]
	v_mfma_f32_16x16x32_bf16 v[54:57], v[176:179], v[192:195], v[54:57]
	v_mfma_f32_16x16x32_bf16 v[50:53], v[184:187], v[192:195], v[50:53]
	v_mfma_f32_16x16x32_bf16 v[38:41], v[176:179], v[200:203], v[38:41]
	v_mfma_f32_16x16x32_bf16 v[34:37], v[184:187], v[200:203], v[34:37]
	v_mfma_f32_16x16x32_bf16 v[22:25], v[176:179], v[208:211], v[22:25]
	v_mfma_f32_16x16x32_bf16 v[18:21], v[184:187], v[208:211], v[18:21]
	v_mfma_f32_16x16x32_bf16 v[6:9], v[176:179], v[216:219], v[6:9]
	v_mfma_f32_16x16x32_bf16 v[2:5], v[184:187], v[216:219], v[2:5]
	s_barrier
	s_add_i32 s59, s59, 2
	s_add_u32 s34, s34, 0x100
	s_addc_u32 s35, s35, 0
	s_add_u32 s57, s57, 0x100
	s_addc_u32 s58, s58, 0
	s_cmp_gt_u32 s59, 13
	s_cbranch_scc0 .LBB0_2153
	s_and_b64 vcc, exec, s[14:15]
	s_cbranch_vccz .LBB0_2156
	s_barrier

; #define PG8_STAGE(bufoff, gbase, voff) do { _Pragma("unroll") for (int _i = 0; _i < 2; ++_i) \
;         __builtin_amdgcn_global_load_lds((const unsigned*)((const char*)(gbase) + (voff)[_i]), (PG8_LAS unsigned*)(lds + (bufoff) + ldsw + _i * 8192), 16, 0, 0); } while (0)
; #define PG8_LDA(dst, b, h) do { _Pragma("unroll") for (int m = 0; m < 4; ++m) _Pragma("unroll") for (int k = 0; k < 2; ++k) dst[m][k] = *(const PG8_LAS bf16x8*)(lds + PG8_SA(b, h) + aoff + m * 2048 + k * 1024); } while (0)
; #define PG8_LDB(dst, b, h) do { _Pragma("unroll") for (int n = 0; n < 2; ++n) _Pragma("unroll") for (int k = 0; k < 2; ++k) dst[n][k] = *(const PG8_LAS bf16x8*)(lds + PG8_SB(b, h) + boff + n * 2048 + k * 1024); } while (0)
; #define PG8_MMA(ai, bj, At, Bt) do { __builtin_amdgcn_s_setprio(1); _Pragma("unroll") for (int m = 0; m < 4; ++m) _Pragma("unroll") for (int n = 0; n < 2; ++n) _Pragma("unroll") for (int k = 0; k < 2; ++k) \
;         acc[ai][bj][m][n] = __builtin_amdgcn_mfma_f32_16x16x32_bf16(Bt[n][k], At[m][k], acc[ai][bj][m][n], 0, 0, 0); __builtin_amdgcn_s_setprio(0); } while (0)
; #define PG8_WAIT_V(n) asm volatile("s_waitcnt vmcnt(" #n ")" ::: "memory")
; #define PG8_WAIT_L(n) asm volatile("s_waitcnt lgkmcnt(" #n ")" ::: "memory")
; #define PG8_BAR __builtin_amdgcn_s_barrier()
; #define PG8_SCHED __builtin_amdgcn_sched_barrier(0)
; template <class Epi, class Sched, bool ALIGN_EPI = false, bool SP2 = false>
; __device__ __forceinline__ void gemm_phase(PG8_LAS unsigned char* lds, const Gemm g, const Sched& S, const Epi& E) {
;     ...
;             PG8_LDB(B0, 0, 0); PG8_LDB(B1, 0, 1); PG8_SCHED; PG8_LDA(At, 0, 0); PG8_STAGE(PG8_SA(1, 1), a1 + hstepA, voffA);
;             PG8_WAIT_V(8); PG8_WAIT_L(0); PG8_BAR; PG8_MMA(0, 0, At, B0); PG8_MMA(0, 1, At, B1); PG8_BAR; PG8_SCHED;
;             PG8_LDA(At, 0, 1); PG8_STAGE(PG8_SB(0, 0), b2, voffB); PG8_STAGE(PG8_SB(0, 1), b2 + hstepB, voffB); PG8_STAGE(PG8_SA(0, 0), a2, voffA);
;             PG8_WAIT_V(8); PG8_WAIT_L(0); PG8_BAR; PG8_MMA(1, 0, At, B0); PG8_MMA(1, 1, At, B1); PG8_BAR; PG8_SCHED;
.LBB0_2500:
	v_add_u32_e32 v24, s53, v22
	ds_read_b128 v[34:37], v24
	ds_read_b128 v[38:41], v24 offset:1024
	ds_read_b128 v[42:45], v24 offset:2048
	ds_read_b128 v[46:49], v24 offset:3072
	v_add_u32_e32 v24, s54, v22
	s_add_u32 s30, s0, s28
	ds_read_b128 v[50:53], v24
	ds_read_b128 v[54:57], v24 offset:1024
	ds_read_b128 v[66:69], v24 offset:2048
	ds_read_b128 v[70:73], v24 offset:3072
	s_addc_u32 s31, s1, s29
	s_add_u32 s30, s30, 0x100
	s_addc_u32 s31, s31, 0
	s_add_u32 s61, s56, s28
	s_addc_u32 s62, s57, s29
	s_cmpk_eq_i32 s28, 0x700
	s_cselect_b32 s35, s23, s31
	s_cselect_b32 s34, s58, s30
	s_cselect_b32 s31, s21, s62
	s_cselect_b32 s30, s59, s61
	v_lshl_add_u64 v[24:25], v[18:19], 0, s[28:29]
	s_add_i32 m0, s45, 0xc000
	ds_read_b128 v[162:165], v23
	ds_read_b128 v[166:169], v23 offset:1024
	ds_read_b128 v[194:197], v23 offset:2048
	ds_read_b128 v[198:201], v23 offset:3072
	ds_read_b128 v[202:205], v23 offset:4096
	ds_read_b128 v[206:209], v23 offset:5120
	ds_read_b128 v[210:213], v23 offset:6144
	ds_read_b128 v[216:219], v23 offset:7168
	global_load_lds_dwordx4 v[24:25], off
	v_lshl_add_u64 v[24:25], v[20:21], 0, s[28:29]
	s_add_i32 m0, s45, 0xe000
	s_nop 0
	global_load_lds_dwordx4 v[24:25], off
	s_waitcnt vmcnt(8)
	s_waitcnt lgkmcnt(0)
	s_barrier
	v_mfma_f32_16x16x32_bf16 v[170:173], v[34:37], v[162:165], v[170:173]
	v_mfma_f32_16x16x32_bf16 v[174:177], v[42:45], v[162:165], v[174:177]
	v_mfma_f32_16x16x32_bf16 v[178:181], v[34:37], v[194:197], v[178:181]
	v_mfma_f32_16x16x32_bf16 v[182:185], v[42:45], v[194:197], v[182:185]
	v_mfma_f32_16x16x32_bf16 v[186:189], v[34:37], v[202:205], v[186:189]
	v_mfma_f32_16x16x32_bf16 v[190:193], v[42:45], v[202:205], v[190:193]
	v_mfma_f32_16x16x32_bf16 v[158:161], v[34:37], v[210:213], v[158:161]
	v_mfma_f32_16x16x32_bf16 v[154:157], v[42:45], v[210:213], v[154:157]
	v_mfma_f32_16x16x32_bf16 v[170:173], v[38:41], v[166:169], v[170:173]
	v_mfma_f32_16x16x32_bf16 v[174:177], v[46:49], v[166:169], v[174:177]
	v_mfma_f32_16x16x32_bf16 v[178:181], v[38:41], v[198:201], v[178:181]
	v_mfma_f32_16x16x32_bf16 v[182:185], v[46:49], v[198:201], v[182:185]
	v_mfma_f32_16x16x32_bf16 v[186:189], v[38:41], v[206:209], v[186:189]
	v_mfma_f32_16x16x32_bf16 v[190:193], v[46:49], v[206:209], v[190:193]
	v_mfma_f32_16x16x32_bf16 v[158:161], v[38:41], v[216:219], v[158:161]
	v_mfma_f32_16x16x32_bf16 v[154:157], v[46:49], v[216:219], v[154:157]
	v_mfma_f32_16x16x32_bf16 v[62:65], v[50:53], v[162:165], v[62:65]
	v_mfma_f32_16x16x32_bf16 v[58:61], v[66:69], v[162:165], v[58:61]
	v_mfma_f32_16x16x32_bf16 v[74:77], v[50:53], v[194:197], v[74:77]
	v_mfma_f32_16x16x32_bf16 v[78:81], v[66:69], v[194:197], v[78:81]
	v_mfma_f32_16x16x32_bf16 v[94:97], v[50:53], v[202:205], v[94:97]
	v_mfma_f32_16x16x32_bf16 v[98:101], v[66:69], v[202:205], v[98:101]
	v_mfma_f32_16x16x32_bf16 v[106:109], v[50:53], v[210:213], v[106:109]
	v_mfma_f32_16x16x32_bf16 v[110:113], v[66:69], v[210:213], v[110:113]
	v_mfma_f32_16x16x32_bf16 v[62:65], v[54:57], v[166:169], v[62:65]
	v_mfma_f32_16x16x32_bf16 v[58:61], v[70:73], v[166:169], v[58:61]
	v_mfma_f32_16x16x32_bf16 v[74:77], v[54:57], v[198:201], v[74:77]
	v_mfma_f32_16x16x32_bf16 v[78:81], v[70:73], v[198:201], v[78:81]
	v_mfma_f32_16x16x32_bf16 v[94:97], v[54:57], v[206:209], v[94:97]
	v_mfma_f32_16x16x32_bf16 v[98:101], v[70:73], v[206:209], v[98:101]
	v_mfma_f32_16x16x32_bf16 v[106:109], v[54:57], v[216:219], v[106:109]
	v_mfma_f32_16x16x32_bf16 v[110:113], v[70:73], v[216:219], v[110:113]
	s_barrier
	s_add_i32 s61, s53, s44
	s_add_u32 s98, s30, 0x80
	s_addc_u32 s99, s31, 0
	s_mov_b32 m0, s61
	ds_read_b128 v[162:165], v23 offset:16384
	ds_read_b128 v[166:169], v23 offset:17408
	ds_read_b128 v[194:197], v23 offset:18432
	ds_read_b128 v[198:201], v23 offset:19456
	ds_read_b128 v[202:205], v23 offset:20480
	ds_read_b128 v[206:209], v23 offset:21504
	ds_read_b128 v[210:213], v23 offset:22528
	ds_read_b128 v[216:219], v23 offset:23552
	global_load_lds_dwordx4 v4, s[30:31]
	s_add_i32 m0, s61, 0x2000
	s_add_u32 s62, s30, 0x40000
	s_addc_u32 s63, s31, 0
	s_add_i32 s61, s54, s44
	global_load_lds_dwordx4 v8, s[30:31]
	s_mov_b32 m0, s61
	s_add_u32 s100, s34, 0x80
	s_addc_u32 s101, s35, 0
	global_load_lds_dwordx4 v4, s[62:63]
	s_add_i32 m0, s61, 0x2000
	s_nop 0
	global_load_lds_dwordx4 v8, s[62:63]
	s_mov_b32 m0, s45
	s_nop 0
	global_load_lds_dwordx4 v2, s[34:35]
	s_mov_b32 m0, s46
	s_nop 0
	global_load_lds_dwordx4 v6, s[34:35]
	s_waitcnt vmcnt(8)
	s_waitcnt lgkmcnt(0)
	s_barrier
	v_mfma_f32_16x16x32_bf16 v[150:153], v[34:37], v[162:165], v[150:153]
	v_mfma_f32_16x16x32_bf16 v[146:149], v[42:45], v[162:165], v[146:149]
	v_mfma_f32_16x16x32_bf16 v[142:145], v[34:37], v[194:197], v[142:145]
	v_mfma_f32_16x16x32_bf16 v[138:141], v[42:45], v[194:197], v[138:141]
	v_mfma_f32_16x16x32_bf16 v[134:137], v[34:37], v[202:205], v[134:137]
	v_mfma_f32_16x16x32_bf16 v[130:133], v[42:45], v[202:205], v[130:133]
	v_mfma_f32_16x16x32_bf16 v[34:37], v[34:37], v[210:213], v[90:93]
	v_mfma_f32_16x16x32_bf16 v[150:153], v[38:41], v[166:169], v[150:153]
	v_mfma_f32_16x16x32_bf16 v[146:149], v[46:49], v[166:169], v[146:149]
	v_mfma_f32_16x16x32_bf16 v[142:145], v[38:41], v[198:201], v[142:145]
	v_mfma_f32_16x16x32_bf16 v[138:141], v[46:49], v[198:201], v[138:141]
	v_mfma_f32_16x16x32_bf16 v[134:137], v[38:41], v[206:209], v[134:137]
	v_mfma_f32_16x16x32_bf16 v[130:133], v[46:49], v[206:209], v[130:133]
	v_mfma_f32_16x16x32_bf16 v[34:37], v[38:41], v[216:219], v[34:37]
	v_mfma_f32_16x16x32_bf16 v[38:41], v[42:45], v[210:213], v[82:85]
	v_mfma_f32_16x16x32_bf16 v[38:41], v[46:49], v[216:219], v[38:41]
	v_mfma_f32_16x16x32_bf16 v[82:85], v[50:53], v[194:197], v[122:125]
	v_mfma_f32_16x16x32_bf16 v[122:125], v[54:57], v[198:201], v[82:85]
	v_mfma_f32_16x16x32_bf16 v[82:85], v[66:69], v[194:197], v[126:129]
	v_mfma_f32_16x16x32_bf16 v[126:129], v[70:73], v[198:201], v[82:85]
	v_mfma_f32_16x16x32_bf16 v[82:85], v[50:53], v[202:205], v[102:105]
	v_mfma_f32_16x16x32_bf16 v[102:105], v[54:57], v[206:209], v[82:85]
	v_mfma_f32_16x16x32_bf16 v[82:85], v[66:69], v[202:205], v[86:89]
	v_mfma_f32_16x16x32_bf16 v[30:33], v[50:53], v[210:213], v[30:33]
	v_mfma_f32_16x16x32_bf16 v[24:27], v[66:69], v[210:213], v[26:29]
	v_mfma_f32_16x16x32_bf16 v[42:45], v[50:53], v[162:165], v[114:117]
	v_mfma_f32_16x16x32_bf16 v[46:49], v[66:69], v[162:165], v[118:121]
	v_mfma_f32_16x16x32_bf16 v[86:89], v[70:73], v[206:209], v[82:85]
	v_mfma_f32_16x16x32_bf16 v[30:33], v[54:57], v[216:219], v[30:33]
	v_mfma_f32_16x16x32_bf16 v[24:27], v[70:73], v[216:219], v[24:27]
	v_mfma_f32_16x16x32_bf16 v[42:45], v[54:57], v[166:169], v[42:45]
	v_mfma_f32_16x16x32_bf16 v[46:49], v[70:73], v[166:169], v[46:49]
	s_barrier
; #define PG8_STAGE(bufoff, gbase, voff) do { _Pragma("unroll") for (int _i = 0; _i < 2; ++_i) \
;         __builtin_amdgcn_global_load_lds((const unsigned*)((const char*)(gbase) + (voff)[_i]), (PG8_LAS unsigned*)(lds + (bufoff) + ldsw + _i * 8192), 16, 0, 0); } while (0)
; #define PG8_LDA(dst, b, h) do { _Pragma("unroll") for (int m = 0; m < 4; ++m) _Pragma("unroll") for (int k = 0; k < 2; ++k) dst[m][k] = *(const PG8_LAS bf16x8*)(lds + PG8_SA(b, h) + aoff + m * 2048 + k * 1024); } while (0)
; #define PG8_LDB(dst, b, h) do { _Pragma("unroll") for (int n = 0; n < 2; ++n) _Pragma("unroll") for (int k = 0; k < 2; ++k) dst[n][k] = *(const PG8_LAS bf16x8*)(lds + PG8_SB(b, h) + boff + n * 2048 + k * 1024); } while (0)
; #define PG8_MMA(ai, bj, At, Bt) do { __builtin_amdgcn_s_setprio(1); _Pragma("unroll") for (int m = 0; m < 4; ++m) _Pragma("unroll") for (int n = 0; n < 2; ++n) _Pragma("unroll") for (int k = 0; k < 2; ++k) \
;         acc[ai][bj][m][n] = __builtin_amdgcn_mfma_f32_16x16x32_bf16(Bt[n][k], At[m][k], acc[ai][bj][m][n], 0, 0, 0); __builtin_amdgcn_s_setprio(0); } while (0)
; #define PG8_WAIT_V(n) asm volatile("s_waitcnt vmcnt(" #n ")" ::: "memory")
; #define PG8_WAIT_L(n) asm volatile("s_waitcnt lgkmcnt(" #n ")" ::: "memory")
; #define PG8_BAR __builtin_amdgcn_s_barrier()
; #define PG8_SCHED __builtin_amdgcn_sched_barrier(0)
; template <class Epi, class Sched, bool ALIGN_EPI = false, bool SP2 = false>
; __device__ __forceinline__ void gemm_phase(PG8_LAS unsigned char* lds, const Gemm g, const Sched& S, const Epi& E) {
;     ...
;             PG8_LDB(B0, 1, 0); PG8_LDB(B1, 1, 1); PG8_SCHED; PG8_LDA(At, 1, 0); PG8_STAGE(PG8_SA(0, 1), a2 + hstepA, voffA);
;             PG8_WAIT_V(8); PG8_WAIT_L(0); PG8_BAR; PG8_MMA(0, 0, At, B0); PG8_MMA(0, 1, At, B1); PG8_BAR; PG8_SCHED;
;             PG8_LDA(At, 1, 1); PG8_STAGE(PG8_SB(1, 0), b3, voffB); PG8_STAGE(PG8_SB(1, 1), b3 + hstepB, voffB); PG8_STAGE(PG8_SA(1, 0), a3, voffA);
	s_add_i32 s61, 0, 0x18000
	v_add_u32_e32 v28, s61, v22
	s_add_i32 s62, 0, 0x1c000
	ds_read_b128 v[50:53], v28
	ds_read_b128 v[54:57], v28 offset:1024
	ds_read_b128 v[66:69], v28 offset:2048
	ds_read_b128 v[70:73], v28 offset:3072
	v_add_u32_e32 v28, s62, v22
	ds_read_b128 v[162:165], v28
	ds_read_b128 v[166:169], v28 offset:1024
	ds_read_b128 v[194:197], v28 offset:2048
	ds_read_b128 v[198:201], v28 offset:3072
	s_add_u32 s34, s34, 0x40000
	s_addc_u32 s35, s35, 0
	s_mov_b32 m0, s48
	ds_read_b128 v[82:85], v23 offset:32768
	ds_read_b128 v[90:93], v23 offset:33792
	ds_read_b128 v[114:117], v23 offset:34816
	ds_read_b128 v[118:121], v23 offset:35840
	ds_read_b128 v[202:205], v23 offset:36864
	ds_read_b128 v[206:209], v23 offset:37888
	ds_read_b128 v[210:213], v23 offset:38912
	ds_read_b128 v[216:219], v23 offset:39936
	global_load_lds_dwordx4 v2, s[34:35]
	s_mov_b32 m0, s49
	s_nop 0
	global_load_lds_dwordx4 v6, s[34:35]
	s_waitcnt vmcnt(8)
	s_waitcnt lgkmcnt(0)
	s_barrier
	v_mfma_f32_16x16x32_bf16 v[170:173], v[50:53], v[82:85], v[170:173]
	v_mfma_f32_16x16x32_bf16 v[174:177], v[66:69], v[82:85], v[174:177]
	v_mfma_f32_16x16x32_bf16 v[178:181], v[50:53], v[114:117], v[178:181]
	v_mfma_f32_16x16x32_bf16 v[182:185], v[66:69], v[114:117], v[182:185]
	v_mfma_f32_16x16x32_bf16 v[186:189], v[50:53], v[202:205], v[186:189]
	v_mfma_f32_16x16x32_bf16 v[190:193], v[66:69], v[202:205], v[190:193]
	v_mfma_f32_16x16x32_bf16 v[158:161], v[50:53], v[210:213], v[158:161]
	v_mfma_f32_16x16x32_bf16 v[154:157], v[66:69], v[210:213], v[154:157]
	v_mfma_f32_16x16x32_bf16 v[170:173], v[54:57], v[90:93], v[170:173]
	v_mfma_f32_16x16x32_bf16 v[174:177], v[70:73], v[90:93], v[174:177]
	v_mfma_f32_16x16x32_bf16 v[178:181], v[54:57], v[118:121], v[178:181]
	v_mfma_f32_16x16x32_bf16 v[182:185], v[70:73], v[118:121], v[182:185]
	v_mfma_f32_16x16x32_bf16 v[186:189], v[54:57], v[206:209], v[186:189]
	v_mfma_f32_16x16x32_bf16 v[190:193], v[70:73], v[206:209], v[190:193]
	v_mfma_f32_16x16x32_bf16 v[158:161], v[54:57], v[216:219], v[158:161]
	v_mfma_f32_16x16x32_bf16 v[154:157], v[70:73], v[216:219], v[154:157]
	v_mfma_f32_16x16x32_bf16 v[62:65], v[162:165], v[82:85], v[62:65]
	v_mfma_f32_16x16x32_bf16 v[58:61], v[194:197], v[82:85], v[58:61]
	v_mfma_f32_16x16x32_bf16 v[82:85], v[162:165], v[202:205], v[94:97]
	v_mfma_f32_16x16x32_bf16 v[94:97], v[166:169], v[206:209], v[82:85]
	v_mfma_f32_16x16x32_bf16 v[82:85], v[194:197], v[202:205], v[98:101]
	v_mfma_f32_16x16x32_bf16 v[98:101], v[198:201], v[206:209], v[82:85]
	v_mfma_f32_16x16x32_bf16 v[82:85], v[162:165], v[210:213], v[106:109]
	v_mfma_f32_16x16x32_bf16 v[74:77], v[162:165], v[114:117], v[74:77]
	v_mfma_f32_16x16x32_bf16 v[78:81], v[194:197], v[114:117], v[78:81]
	v_mfma_f32_16x16x32_bf16 v[106:109], v[166:169], v[216:219], v[82:85]
	v_mfma_f32_16x16x32_bf16 v[82:85], v[194:197], v[210:213], v[110:113]
	v_mfma_f32_16x16x32_bf16 v[62:65], v[166:169], v[90:93], v[62:65]
	v_mfma_f32_16x16x32_bf16 v[58:61], v[198:201], v[90:93], v[58:61]
	v_mfma_f32_16x16x32_bf16 v[74:77], v[166:169], v[118:121], v[74:77]
	v_mfma_f32_16x16x32_bf16 v[78:81], v[198:201], v[118:121], v[78:81]
	v_mfma_f32_16x16x32_bf16 v[110:113], v[198:201], v[216:219], v[82:85]
	s_barrier
	s_add_i32 s34, s61, s44
	s_mov_b32 m0, s34
	ds_read_b128 v[118:121], v23 offset:49152
	ds_read_b128 v[202:205], v23 offset:50176
	ds_read_b128 v[206:209], v23 offset:51200
	ds_read_b128 v[210:213], v23 offset:52224
	ds_read_b128 v[216:219], v23 offset:53248
	ds_read_b128 v[220:223], v23 offset:54272
	ds_read_b128 v[224:227], v23 offset:55296
	ds_read_b128 v[228:231], v23 offset:56320
	global_load_lds_dwordx4 v4, s[98:99]
	s_add_i32 m0, s34, 0x2000
	s_add_u32 s30, s30, 0x40080
	s_addc_u32 s31, s31, 0
	s_add_i32 s34, s62, s44
	global_load_lds_dwordx4 v8, s[98:99]
	s_mov_b32 m0, s34
	s_nop 0
	global_load_lds_dwordx4 v4, s[30:31]
	s_add_i32 m0, s34, 0x2000
	s_nop 0
	global_load_lds_dwordx4 v8, s[30:31]
	s_mov_b32 m0, s51
	s_nop 0
	global_load_lds_dwordx4 v2, s[100:101]
	s_mov_b32 m0, s52
	s_nop 0
	global_load_lds_dwordx4 v6, s[100:101]
	s_waitcnt vmcnt(8)
	s_waitcnt lgkmcnt(0)
	s_barrier
; #define PG8_STAGE(bufoff, gbase, voff) do { _Pragma("unroll") for (int _i = 0; _i < 2; ++_i) \
;         __builtin_amdgcn_global_load_lds((const unsigned*)((const char*)(gbase) + (voff)[_i]), (PG8_LAS unsigned*)(lds + (bufoff) + ldsw + _i * 8192), 16, 0, 0); } while (0)
; #define PG8_LDA(dst, b, h) do { _Pragma("unroll") for (int m = 0; m < 4; ++m) _Pragma("unroll") for (int k = 0; k < 2; ++k) dst[m][k] = *(const PG8_LAS bf16x8*)(lds + PG8_SA(b, h) + aoff + m * 2048 + k * 1024); } while (0)
; #define PG8_MMA(ai, bj, At, Bt) do { __builtin_amdgcn_s_setprio(1); _Pragma("unroll") for (int m = 0; m < 4; ++m) _Pragma("unroll") for (int n = 0; n < 2; ++n) _Pragma("unroll") for (int k = 0; k < 2; ++k) \
;         acc[ai][bj][m][n] = __builtin_amdgcn_mfma_f32_16x16x32_bf16(Bt[n][k], At[m][k], acc[ai][bj][m][n], 0, 0, 0); __builtin_amdgcn_s_setprio(0); } while (0)
; #define PG8_WAIT_V(n) asm volatile("s_waitcnt vmcnt(" #n ")" ::: "memory")
; #define PG8_WAIT_L(n) asm volatile("s_waitcnt lgkmcnt(" #n ")" ::: "memory")
; #define PG8_BAR __builtin_amdgcn_s_barrier()
; #define PG8_SCHED __builtin_amdgcn_sched_barrier(0)
; template <class Epi, class Sched, bool ALIGN_EPI = false, bool SP2 = false>
; __device__ __forceinline__ void gemm_phase(PG8_LAS unsigned char* lds, const Gemm g, const Sched& S, const Epi& E) {
;     ...
;             PG8_LDA(At, 1, 1); PG8_STAGE(PG8_SB(1, 0), b3, voffB); PG8_STAGE(PG8_SB(1, 1), b3 + hstepB, voffB); PG8_STAGE(PG8_SA(1, 0), a3, voffA);
;             PG8_WAIT_V(8); PG8_WAIT_L(0); PG8_BAR; PG8_MMA(1, 0, At, B0); PG8_MMA(1, 1, At, B1); PG8_BAR; PG8_SCHED;
;     ...
; #pragma unroll
;         for (int a = 0; a < 2; ++a)
; #pragma unroll
;             for (int b = 0; b < 2; ++b)
; #pragma unroll
;                 for (int m = 0; m < 4; ++m)
; #pragma unroll
;                     for (int n = 0; n < 2; ++n) acc[a][b][m][n] = (f32x4){0.f, 0.f, 0.f, 0.f};
	v_mfma_f32_16x16x32_bf16 v[82:85], v[50:53], v[118:121], v[150:153]
	v_mfma_f32_16x16x32_bf16 v[150:153], v[54:57], v[202:205], v[82:85]
	v_mfma_f32_16x16x32_bf16 v[82:85], v[66:69], v[118:121], v[146:149]
	v_mfma_f32_16x16x32_bf16 v[146:149], v[70:73], v[202:205], v[82:85]
	v_mfma_f32_16x16x32_bf16 v[82:85], v[50:53], v[206:209], v[142:145]
	v_mfma_f32_16x16x32_bf16 v[142:145], v[54:57], v[210:213], v[82:85]
	v_mfma_f32_16x16x32_bf16 v[82:85], v[66:69], v[206:209], v[138:141]
	v_mfma_f32_16x16x32_bf16 v[138:141], v[70:73], v[210:213], v[82:85]
	v_mfma_f32_16x16x32_bf16 v[82:85], v[50:53], v[216:219], v[134:137]
	v_mfma_f32_16x16x32_bf16 v[34:37], v[50:53], v[224:227], v[34:37]
	v_mfma_f32_16x16x32_bf16 v[134:137], v[54:57], v[220:223], v[82:85]
	v_mfma_f32_16x16x32_bf16 v[82:85], v[66:69], v[216:219], v[130:133]
	v_mfma_f32_16x16x32_bf16 v[90:93], v[54:57], v[228:231], v[34:37]
	v_mfma_f32_16x16x32_bf16 v[34:37], v[66:69], v[224:227], v[38:41]
	v_mfma_f32_16x16x32_bf16 v[130:133], v[70:73], v[220:223], v[82:85]
	v_mfma_f32_16x16x32_bf16 v[82:85], v[70:73], v[228:231], v[34:37]
	v_mfma_f32_16x16x32_bf16 v[34:37], v[162:165], v[118:121], v[42:45]
	v_mfma_f32_16x16x32_bf16 v[114:117], v[166:169], v[202:205], v[34:37]
	v_mfma_f32_16x16x32_bf16 v[34:37], v[194:197], v[118:121], v[46:49]
	v_mfma_f32_16x16x32_bf16 v[118:121], v[198:201], v[202:205], v[34:37]
	v_mfma_f32_16x16x32_bf16 v[34:37], v[162:165], v[206:209], v[122:125]
	v_mfma_f32_16x16x32_bf16 v[122:125], v[166:169], v[210:213], v[34:37]
	v_mfma_f32_16x16x32_bf16 v[34:37], v[194:197], v[206:209], v[126:129]
	v_mfma_f32_16x16x32_bf16 v[126:129], v[198:201], v[210:213], v[34:37]
	v_mfma_f32_16x16x32_bf16 v[34:37], v[162:165], v[216:219], v[102:105]
	v_mfma_f32_16x16x32_bf16 v[102:105], v[166:169], v[220:223], v[34:37]
	v_mfma_f32_16x16x32_bf16 v[34:37], v[194:197], v[216:219], v[86:89]
	v_mfma_f32_16x16x32_bf16 v[28:31], v[162:165], v[224:227], v[30:33]
	v_mfma_f32_16x16x32_bf16 v[24:27], v[194:197], v[224:227], v[24:27]
	v_mfma_f32_16x16x32_bf16 v[86:89], v[198:201], v[220:223], v[34:37]
	v_mfma_f32_16x16x32_bf16 v[30:33], v[166:169], v[228:231], v[28:31]
	v_mfma_f32_16x16x32_bf16 v[26:29], v[198:201], v[228:231], v[24:27]
	s_barrier
	s_add_i32 s60, s60, 2
	s_add_u32 s28, s28, 0x100
	s_addc_u32 s29, s29, 0
	s_cmp_gt_u32 s60, 13
	s_cbranch_scc0 .LBB0_2500
	s_add_u32 s28, s56, 0xffffff00
	s_addc_u32 s29, s57, -1
	s_andn2_b64 vcc, exec, s[4:5]
	s_cbranch_vccnz .LBB0_2491
	v_mov_b32_e32 v26, 0
	s_mov_b32 s16, s20
	s_mov_b32 s14, s22
	s_mov_b64 s[0:1], s[26:27]
	s_mov_b32 s50, s55
	v_mov_b32_e32 v27, v26
	v_mov_b32_e32 v28, v26
	v_mov_b32_e32 v29, v26
	v_mov_b32_e32 v30, v26
	v_mov_b32_e32 v31, v26
	v_mov_b32_e32 v32, v26
	v_mov_b32_e32 v33, v26
	v_mov_b32_e32 v86, v26
	v_mov_b32_e32 v87, v26
	v_mov_b32_e32 v88, v26
	v_mov_b32_e32 v89, v26
	v_mov_b32_e32 v102, v26
	v_mov_b32_e32 v103, v26
	v_mov_b32_e32 v104, v26
	v_mov_b32_e32 v105, v26
	v_mov_b32_e32 v126, v26
	v_mov_b32_e32 v127, v26
	v_mov_b32_e32 v128, v26
	v_mov_b32_e32 v129, v26
	v_mov_b32_e32 v122, v26
	v_mov_b32_e32 v123, v26
	v_mov_b32_e32 v124, v26
	v_mov_b32_e32 v125, v26
	v_mov_b32_e32 v118, v26
	v_mov_b32_e32 v119, v26
	v_mov_b32_e32 v120, v26
	v_mov_b32_e32 v121, v26
	v_mov_b32_e32 v114, v26
	v_mov_b32_e32 v115, v26
	v_mov_b32_e32 v116, v26
	v_mov_b32_e32 v117, v26
	v_mov_b32_e32 v82, v26
	v_mov_b32_e32 v83, v26
	v_mov_b32_e32 v84, v26
	v_mov_b32_e32 v85, v26
	v_mov_b32_e32 v90, v26
	v_mov_b32_e32 v91, v26
	v_mov_b32_e32 v92, v26
	v_mov_b32_e32 v93, v26
	v_mov_b32_e32 v130, v26
	v_mov_b32_e32 v131, v26
	v_mov_b32_e32 v132, v26
	v_mov_b32_e32 v133, v26
	v_mov_b32_e32 v134, v26
	v_mov_b32_e32 v135, v26
	v_mov_b32_e32 v136, v26
	v_mov_b32_e32 v137, v26
	v_mov_b32_e32 v138, v26
	v_mov_b32_e32 v139, v26
	v_mov_b32_e32 v140, v26
	v_mov_b32_e32 v141, v26
	v_mov_b32_e32 v142, v26
	v_mov_b32_e32 v143, v26
	v_mov_b32_e32 v144, v26
	v_mov_b32_e32 v145, v26
	v_mov_b32_e32 v146, v26
	v_mov_b32_e32 v147, v26
	v_mov_b32_e32 v148, v26
	v_mov_b32_e32 v149, v26
	v_mov_b32_e32 v150, v26
	v_mov_b32_e32 v151, v26
	v_mov_b32_e32 v152, v26
	v_mov_b32_e32 v153, v26
	v_mov_b32_e32 v110, v26
	v_mov_b32_e32 v111, v26
	v_mov_b32_e32 v112, v26
	v_mov_b32_e32 v113, v26
	v_mov_b32_e32 v106, v26
	v_mov_b32_e32 v107, v26
	v_mov_b32_e32 v108, v26
	v_mov_b32_e32 v109, v26
	v_mov_b32_e32 v98, v26
	v_mov_b32_e32 v99, v26
	v_mov_b32_e32 v100, v26
	v_mov_b32_e32 v101, v26
	v_mov_b32_e32 v94, v26
	v_mov_b32_e32 v95, v26
	v_mov_b32_e32 v96, v26
	v_mov_b32_e32 v97, v26
	v_mov_b32_e32 v78, v26
	v_mov_b32_e32 v79, v26
	v_mov_b32_e32 v80, v26
	v_mov_b32_e32 v81, v26
	v_mov_b32_e32 v74, v26
	v_mov_b32_e32 v75, v26
	v_mov_b32_e32 v76, v26
	v_mov_b32_e32 v77, v26
	v_mov_b32_e32 v58, v26
	v_mov_b32_e32 v59, v26
	v_mov_b32_e32 v60, v26
	v_mov_b32_e32 v61, v26
	v_mov_b32_e32 v62, v26
	v_mov_b32_e32 v63, v26
	v_mov_b32_e32 v64, v26
	v_mov_b32_e32 v65, v26
	v_mov_b32_e32 v154, v26
	v_mov_b32_e32 v155, v26
	v_mov_b32_e32 v156, v26
	v_mov_b32_e32 v157, v26
	v_mov_b32_e32 v158, v26
	v_mov_b32_e32 v159, v26
	v_mov_b32_e32 v160, v26
	v_mov_b32_e32 v161, v26
	v_mov_b32_e32 v190, v26
	v_mov_b32_e32 v191, v26
	v_mov_b32_e32 v192, v26
	v_mov_b32_e32 v193, v26
	v_mov_b32_e32 v186, v26
	v_mov_b32_e32 v187, v26
	v_mov_b32_e32 v188, v26
	v_mov_b32_e32 v189, v26
	v_mov_b32_e32 v182, v26
	v_mov_b32_e32 v183, v26
	v_mov_b32_e32 v184, v26
	v_mov_b32_e32 v185, v26
	v_mov_b32_e32 v178, v26
	v_mov_b32_e32 v179, v26
	v_mov_b32_e32 v180, v26
	v_mov_b32_e32 v181, v26
	v_mov_b32_e32 v174, v26
	v_mov_b32_e32 v175, v26
	v_mov_b32_e32 v176, v26
	v_mov_b32_e32 v177, v26
	v_mov_b32_e32 v170, v26
	v_mov_b32_e32 v171, v26
	v_mov_b32_e32 v172, v26
	v_mov_b32_e32 v173, v26
	s_andn2_b64 vcc, exec, s[2:3]
	s_cbranch_vccnz .LBB0_2492

; #define PG8_STAGE(bufoff, gbase, voff) do { _Pragma("unroll") for (int _i = 0; _i < 2; ++_i) \
;         __builtin_amdgcn_global_load_lds((const unsigned*)((const char*)(gbase) + (voff)[_i]), (PG8_LAS unsigned*)(lds + (bufoff) + ldsw + _i * 8192), 16, 0, 0); } while (0)
; #define PG8_LDA(dst, b, h) do { _Pragma("unroll") for (int m = 0; m < 4; ++m) _Pragma("unroll") for (int k = 0; k < 2; ++k) dst[m][k] = *(const PG8_LAS bf16x8*)(lds + PG8_SA(b, h) + aoff + m * 2048 + k * 1024); } while (0)
; #define PG8_LDB(dst, b, h) do { _Pragma("unroll") for (int n = 0; n < 2; ++n) _Pragma("unroll") for (int k = 0; k < 2; ++k) dst[n][k] = *(const PG8_LAS bf16x8*)(lds + PG8_SB(b, h) + boff + n * 2048 + k * 1024); } while (0)
; #define PG8_MMA(ai, bj, At, Bt) do { __builtin_amdgcn_s_setprio(1); _Pragma("unroll") for (int m = 0; m < 4; ++m) _Pragma("unroll") for (int n = 0; n < 2; ++n) _Pragma("unroll") for (int k = 0; k < 2; ++k) \
;         acc[ai][bj][m][n] = __builtin_amdgcn_mfma_f32_16x16x32_bf16(Bt[n][k], At[m][k], acc[ai][bj][m][n], 0, 0, 0); __builtin_amdgcn_s_setprio(0); } while (0)
; #define PG8_WAIT_V(n) asm volatile("s_waitcnt vmcnt(" #n ")" ::: "memory")
; #define PG8_WAIT_L(n) asm volatile("s_waitcnt lgkmcnt(" #n ")" ::: "memory")
; #define PG8_BAR __builtin_amdgcn_s_barrier()
; #define PG8_SCHED __builtin_amdgcn_sched_barrier(0)
; template <class Epi, class Sched, bool ALIGN_EPI = false, bool SP2 = false>
; __device__ __forceinline__ void gemm_phase(PG8_LAS unsigned char* lds, const Gemm g, const Sched& S, const Epi& E) {
;     ...
;             PG8_LDB(B0, 0, 0); PG8_LDB(B1, 0, 1); PG8_SCHED; PG8_LDA(At, 0, 0); PG8_STAGE(PG8_SA(1, 1), a1 + hstepA, voffA);
;             PG8_WAIT_V(8); PG8_WAIT_L(0); PG8_BAR; PG8_MMA(0, 0, At, B0); PG8_MMA(0, 1, At, B1); PG8_BAR; PG8_SCHED;
;             PG8_LDA(At, 0, 1); PG8_STAGE(PG8_SB(0, 0), b2, voffB); PG8_STAGE(PG8_SB(0, 1), b2 + hstepB, voffB); PG8_STAGE(PG8_SA(0, 0), a2, voffA);
;             PG8_WAIT_V(8); PG8_WAIT_L(0); PG8_BAR; PG8_MMA(1, 0, At, B0); PG8_MMA(1, 1, At, B1); PG8_BAR; PG8_SCHED;
.LBB0_2613:
	ds_read_b128 v[130:133], v182
	ds_read_b128 v[134:137], v182 offset:1024
	ds_read_b128 v[154:157], v182 offset:2048
	ds_read_b128 v[158:161], v182 offset:3072
	ds_read_b128 v[162:165], v183
	ds_read_b128 v[166:169], v183 offset:1024
	ds_read_b128 v[170:173], v183 offset:2048
	ds_read_b128 v[186:189], v183 offset:3072
	s_add_u32 s44, s42, 0xfffc0080
	s_addc_u32 s45, s43, -1
	s_cmp_eq_u32 s70, 12
	s_cselect_b32 s47, s31, s45
	s_cselect_b32 s46, s39, s44
	s_cselect_b32 s45, s29, s69
	s_cselect_b32 s44, s67, s68
	s_add_i32 m0, s41, 0xc000
	ds_read_b128 v[190:193], v184
	ds_read_b128 v[194:197], v184 offset:1024
	ds_read_b128 v[198:201], v184 offset:2048
	ds_read_b128 v[202:205], v184 offset:3072
	ds_read_b128 v[206:209], v184 offset:4096
	ds_read_b128 v[210:213], v184 offset:5120
	ds_read_b128 v[214:217], v184 offset:6144
	ds_read_b128 v[218:221], v184 offset:7168
	global_load_lds_dwordx4 v146, s[42:43]
	s_add_i32 m0, s41, 0xe000
	s_nop 0
	global_load_lds_dwordx4 v148, s[42:43]
	s_waitcnt vmcnt(8)
	s_waitcnt lgkmcnt(0)
	s_barrier
	v_mfma_f32_16x16x32_bf16 v[126:129], v[130:133], v[190:193], v[126:129]
	v_mfma_f32_16x16x32_bf16 v[94:97], v[154:157], v[190:193], v[94:97]
	v_mfma_f32_16x16x32_bf16 v[118:121], v[130:133], v[198:201], v[118:121]
	v_mfma_f32_16x16x32_bf16 v[86:89], v[154:157], v[198:201], v[86:89]
	v_mfma_f32_16x16x32_bf16 v[114:117], v[130:133], v[206:209], v[114:117]
	v_mfma_f32_16x16x32_bf16 v[82:85], v[154:157], v[206:209], v[82:85]
	v_mfma_f32_16x16x32_bf16 v[102:105], v[130:133], v[214:217], v[102:105]
	v_mfma_f32_16x16x32_bf16 v[70:73], v[154:157], v[214:217], v[70:73]
	v_mfma_f32_16x16x32_bf16 v[126:129], v[134:137], v[194:197], v[126:129]
	v_mfma_f32_16x16x32_bf16 v[94:97], v[158:161], v[194:197], v[94:97]
	v_mfma_f32_16x16x32_bf16 v[118:121], v[134:137], v[202:205], v[118:121]
	v_mfma_f32_16x16x32_bf16 v[86:89], v[158:161], v[202:205], v[86:89]
	v_mfma_f32_16x16x32_bf16 v[114:117], v[134:137], v[210:213], v[114:117]
	v_mfma_f32_16x16x32_bf16 v[82:85], v[158:161], v[210:213], v[82:85]
	v_mfma_f32_16x16x32_bf16 v[102:105], v[134:137], v[218:221], v[102:105]
	v_mfma_f32_16x16x32_bf16 v[70:73], v[158:161], v[218:221], v[70:73]
	v_mfma_f32_16x16x32_bf16 v[122:125], v[162:165], v[190:193], v[122:125]
	v_mfma_f32_16x16x32_bf16 v[90:93], v[170:173], v[190:193], v[90:93]
	v_mfma_f32_16x16x32_bf16 v[110:113], v[162:165], v[198:201], v[110:113]
	v_mfma_f32_16x16x32_bf16 v[78:81], v[170:173], v[198:201], v[78:81]
	v_mfma_f32_16x16x32_bf16 v[106:109], v[162:165], v[206:209], v[106:109]
	v_mfma_f32_16x16x32_bf16 v[74:77], v[170:173], v[206:209], v[74:77]
	v_mfma_f32_16x16x32_bf16 v[98:101], v[162:165], v[214:217], v[98:101]
	v_mfma_f32_16x16x32_bf16 v[66:69], v[170:173], v[214:217], v[66:69]
	v_mfma_f32_16x16x32_bf16 v[122:125], v[166:169], v[194:197], v[122:125]
	v_mfma_f32_16x16x32_bf16 v[90:93], v[186:189], v[194:197], v[90:93]
	v_mfma_f32_16x16x32_bf16 v[110:113], v[166:169], v[202:205], v[110:113]
	v_mfma_f32_16x16x32_bf16 v[78:81], v[186:189], v[202:205], v[78:81]
	v_mfma_f32_16x16x32_bf16 v[106:109], v[166:169], v[210:213], v[106:109]
	v_mfma_f32_16x16x32_bf16 v[74:77], v[186:189], v[210:213], v[74:77]
	v_mfma_f32_16x16x32_bf16 v[98:101], v[166:169], v[218:221], v[98:101]
	v_mfma_f32_16x16x32_bf16 v[66:69], v[186:189], v[218:221], v[66:69]
	s_barrier
	s_add_i32 s71, s64, s51
	s_add_u32 s98, s44, 0x80
	s_addc_u32 s99, s45, 0
	s_mov_b32 m0, s71
	ds_read_b128 v[190:193], v184 offset:16384
	ds_read_b128 v[194:197], v184 offset:17408
	ds_read_b128 v[198:201], v184 offset:18432
	ds_read_b128 v[202:205], v184 offset:19456
	ds_read_b128 v[206:209], v184 offset:20480
	ds_read_b128 v[210:213], v184 offset:21504
	ds_read_b128 v[214:217], v184 offset:22528
	ds_read_b128 v[218:221], v184 offset:23552
	global_load_lds_dwordx4 v140, s[44:45]
	s_add_i32 m0, s71, 0x2000
	s_add_u32 s72, s44, 0x40000
	s_addc_u32 s73, s45, 0
	s_add_i32 s71, s65, s51
	global_load_lds_dwordx4 v144, s[44:45]
	s_mov_b32 m0, s71
	v_lshl_add_u64 v[226:227], s[46:47], 0, v[142:143]
	global_load_lds_dwordx4 v140, s[72:73]
	s_add_i32 m0, s71, 0x2000
	s_nop 0
	global_load_lds_dwordx4 v144, s[72:73]
	s_add_u32 s100, s46, 0x80
	s_addc_u32 s101, s47, 0
	s_mov_b32 m0, s41
	s_nop 0
	global_load_lds_dwordx4 v138, s[46:47]
	s_mov_b32 m0, s52
	s_nop 0
	global_load_lds_dwordx4 v142, s[46:47]
	s_waitcnt vmcnt(8)
	s_waitcnt lgkmcnt(0)
	s_barrier
	v_mfma_f32_16x16x32_bf16 v[62:65], v[130:133], v[190:193], v[62:65]
	v_mfma_f32_16x16x32_bf16 v[30:33], v[154:157], v[190:193], v[30:33]
	v_mfma_f32_16x16x32_bf16 v[54:57], v[130:133], v[198:201], v[54:57]
	v_mfma_f32_16x16x32_bf16 v[22:25], v[154:157], v[198:201], v[22:25]
	v_mfma_f32_16x16x32_bf16 v[50:53], v[130:133], v[206:209], v[50:53]
	v_mfma_f32_16x16x32_bf16 v[18:21], v[154:157], v[206:209], v[18:21]
	v_mfma_f32_16x16x32_bf16 v[38:41], v[130:133], v[214:217], v[38:41]
	v_mfma_f32_16x16x32_bf16 v[6:9], v[154:157], v[214:217], v[6:9]
	v_mfma_f32_16x16x32_bf16 v[62:65], v[134:137], v[194:197], v[62:65]
	v_mfma_f32_16x16x32_bf16 v[30:33], v[158:161], v[194:197], v[30:33]
	v_mfma_f32_16x16x32_bf16 v[54:57], v[134:137], v[202:205], v[54:57]
	v_mfma_f32_16x16x32_bf16 v[22:25], v[158:161], v[202:205], v[22:25]
	v_mfma_f32_16x16x32_bf16 v[50:53], v[134:137], v[210:213], v[50:53]
	v_mfma_f32_16x16x32_bf16 v[18:21], v[158:161], v[210:213], v[18:21]
	v_mfma_f32_16x16x32_bf16 v[38:41], v[134:137], v[218:221], v[38:41]
	v_mfma_f32_16x16x32_bf16 v[6:9], v[158:161], v[218:221], v[6:9]
	v_mfma_f32_16x16x32_bf16 v[58:61], v[162:165], v[190:193], v[58:61]
	v_mfma_f32_16x16x32_bf16 v[26:29], v[170:173], v[190:193], v[26:29]
	v_mfma_f32_16x16x32_bf16 v[46:49], v[162:165], v[198:201], v[46:49]
	v_mfma_f32_16x16x32_bf16 v[14:17], v[170:173], v[198:201], v[14:17]
	v_mfma_f32_16x16x32_bf16 v[42:45], v[162:165], v[206:209], v[42:45]
	v_mfma_f32_16x16x32_bf16 v[10:13], v[170:173], v[206:209], v[10:13]
	v_mfma_f32_16x16x32_bf16 v[34:37], v[162:165], v[214:217], v[34:37]
	v_mfma_f32_16x16x32_bf16 v[2:5], v[170:173], v[214:217], v[2:5]
	v_mfma_f32_16x16x32_bf16 v[58:61], v[166:169], v[194:197], v[58:61]
	v_mfma_f32_16x16x32_bf16 v[26:29], v[186:189], v[194:197], v[26:29]
	v_mfma_f32_16x16x32_bf16 v[46:49], v[166:169], v[202:205], v[46:49]
	v_mfma_f32_16x16x32_bf16 v[14:17], v[186:189], v[202:205], v[14:17]
	v_mfma_f32_16x16x32_bf16 v[42:45], v[166:169], v[210:213], v[42:45]
	v_mfma_f32_16x16x32_bf16 v[10:13], v[186:189], v[210:213], v[10:13]
	v_mfma_f32_16x16x32_bf16 v[34:37], v[166:169], v[218:221], v[34:37]
	v_mfma_f32_16x16x32_bf16 v[2:5], v[186:189], v[218:221], v[2:5]
	s_barrier
; #define PG8_STAGE(bufoff, gbase, voff) do { _Pragma("unroll") for (int _i = 0; _i < 2; ++_i) \
;         __builtin_amdgcn_global_load_lds((const unsigned*)((const char*)(gbase) + (voff)[_i]), (PG8_LAS unsigned*)(lds + (bufoff) + ldsw + _i * 8192), 16, 0, 0); } while (0)
; #define PG8_LDA(dst, b, h) do { _Pragma("unroll") for (int m = 0; m < 4; ++m) _Pragma("unroll") for (int k = 0; k < 2; ++k) dst[m][k] = *(const PG8_LAS bf16x8*)(lds + PG8_SA(b, h) + aoff + m * 2048 + k * 1024); } while (0)
; #define PG8_LDB(dst, b, h) do { _Pragma("unroll") for (int n = 0; n < 2; ++n) _Pragma("unroll") for (int k = 0; k < 2; ++k) dst[n][k] = *(const PG8_LAS bf16x8*)(lds + PG8_SB(b, h) + boff + n * 2048 + k * 1024); } while (0)
; #define PG8_MMA(ai, bj, At, Bt) do { __builtin_amdgcn_s_setprio(1); _Pragma("unroll") for (int m = 0; m < 4; ++m) _Pragma("unroll") for (int n = 0; n < 2; ++n) _Pragma("unroll") for (int k = 0; k < 2; ++k) \
;         acc[ai][bj][m][n] = __builtin_amdgcn_mfma_f32_16x16x32_bf16(Bt[n][k], At[m][k], acc[ai][bj][m][n], 0, 0, 0); __builtin_amdgcn_s_setprio(0); } while (0)
; #define PG8_WAIT_V(n) asm volatile("s_waitcnt vmcnt(" #n ")" ::: "memory")
; #define PG8_WAIT_L(n) asm volatile("s_waitcnt lgkmcnt(" #n ")" ::: "memory")
; #define PG8_BAR __builtin_amdgcn_s_barrier()
; #define PG8_SCHED __builtin_amdgcn_sched_barrier(0)
; template <class Epi, class Sched, bool ALIGN_EPI = false, bool SP2 = false>
; __device__ __forceinline__ void gemm_phase(PG8_LAS unsigned char* lds, const Gemm g, const Sched& S, const Epi& E) {
;     ...
;             PG8_LDB(B0, 1, 0); PG8_LDB(B1, 1, 1); PG8_SCHED; PG8_LDA(At, 1, 0); PG8_STAGE(PG8_SA(0, 1), a2 + hstepA, voffA);
;             PG8_WAIT_V(8); PG8_WAIT_L(0); PG8_BAR; PG8_MMA(0, 0, At, B0); PG8_MMA(0, 1, At, B1); PG8_BAR; PG8_SCHED;
;             PG8_LDA(At, 1, 1); PG8_STAGE(PG8_SB(1, 0), b3, voffB); PG8_STAGE(PG8_SB(1, 1), b3 + hstepB, voffB); PG8_STAGE(PG8_SA(1, 0), a3, voffA);
;             PG8_WAIT_V(8); PG8_WAIT_L(0); PG8_BAR; PG8_MMA(1, 0, At, B0); PG8_MMA(1, 1, At, B1); PG8_BAR; PG8_SCHED;
;     ...
;         if constexpr (ALIGN_EPI) { if (wr == 0) PG8_BAR; }
	s_add_i32 s71, 0, 0x18000
	s_add_i32 s72, 0, 0x1c000
	v_add_u32_e32 v158, s71, v176
	v_add_u32_e32 v185, s72, v176
	ds_read_b128 v[130:133], v158
	ds_read_b128 v[134:137], v158 offset:1024
	ds_read_b128 v[154:157], v158 offset:2048
	ds_read_b128 v[158:161], v158 offset:3072
	ds_read_b128 v[162:165], v185
	ds_read_b128 v[166:169], v185 offset:1024
	ds_read_b128 v[170:173], v185 offset:2048
	ds_read_b128 v[186:189], v185 offset:3072
	s_add_u32 s46, s46, 0x40000
	s_addc_u32 s47, s47, 0
	s_mov_b32 m0, s53
	ds_read_b128 v[190:193], v184 offset:32768
	ds_read_b128 v[194:197], v184 offset:33792
	ds_read_b128 v[198:201], v184 offset:34816
	ds_read_b128 v[202:205], v184 offset:35840
	ds_read_b128 v[206:209], v184 offset:36864
	ds_read_b128 v[210:213], v184 offset:37888
	ds_read_b128 v[214:217], v184 offset:38912
	ds_read_b128 v[218:221], v184 offset:39936
	global_load_lds_dwordx4 v138, s[46:47]
	s_mov_b32 m0, s54
	s_nop 0
	global_load_lds_dwordx4 v142, s[46:47]
	s_waitcnt vmcnt(8)
	s_waitcnt lgkmcnt(0)
	s_barrier
	v_mfma_f32_16x16x32_bf16 v[126:129], v[130:133], v[190:193], v[126:129]
	v_mfma_f32_16x16x32_bf16 v[94:97], v[154:157], v[190:193], v[94:97]
	v_mfma_f32_16x16x32_bf16 v[118:121], v[130:133], v[198:201], v[118:121]
	v_mfma_f32_16x16x32_bf16 v[86:89], v[154:157], v[198:201], v[86:89]
	v_mfma_f32_16x16x32_bf16 v[114:117], v[130:133], v[206:209], v[114:117]
	v_mfma_f32_16x16x32_bf16 v[82:85], v[154:157], v[206:209], v[82:85]
	v_mfma_f32_16x16x32_bf16 v[102:105], v[130:133], v[214:217], v[102:105]
	v_mfma_f32_16x16x32_bf16 v[70:73], v[154:157], v[214:217], v[70:73]
	v_mfma_f32_16x16x32_bf16 v[126:129], v[134:137], v[194:197], v[126:129]
	v_mfma_f32_16x16x32_bf16 v[94:97], v[158:161], v[194:197], v[94:97]
	v_mfma_f32_16x16x32_bf16 v[118:121], v[134:137], v[202:205], v[118:121]
	v_mfma_f32_16x16x32_bf16 v[86:89], v[158:161], v[202:205], v[86:89]
	v_mfma_f32_16x16x32_bf16 v[114:117], v[134:137], v[210:213], v[114:117]
	v_mfma_f32_16x16x32_bf16 v[82:85], v[158:161], v[210:213], v[82:85]
	v_mfma_f32_16x16x32_bf16 v[102:105], v[134:137], v[218:221], v[102:105]
	v_mfma_f32_16x16x32_bf16 v[70:73], v[158:161], v[218:221], v[70:73]
	v_mfma_f32_16x16x32_bf16 v[122:125], v[162:165], v[190:193], v[122:125]
	v_mfma_f32_16x16x32_bf16 v[90:93], v[170:173], v[190:193], v[90:93]
	v_mfma_f32_16x16x32_bf16 v[110:113], v[162:165], v[198:201], v[110:113]
	v_mfma_f32_16x16x32_bf16 v[78:81], v[170:173], v[198:201], v[78:81]
	v_mfma_f32_16x16x32_bf16 v[106:109], v[162:165], v[206:209], v[106:109]
	v_mfma_f32_16x16x32_bf16 v[74:77], v[170:173], v[206:209], v[74:77]
	v_mfma_f32_16x16x32_bf16 v[98:101], v[162:165], v[214:217], v[98:101]
	v_mfma_f32_16x16x32_bf16 v[66:69], v[170:173], v[214:217], v[66:69]
	v_mfma_f32_16x16x32_bf16 v[122:125], v[166:169], v[194:197], v[122:125]
	v_mfma_f32_16x16x32_bf16 v[90:93], v[186:189], v[194:197], v[90:93]
	v_mfma_f32_16x16x32_bf16 v[110:113], v[166:169], v[202:205], v[110:113]
	v_mfma_f32_16x16x32_bf16 v[78:81], v[186:189], v[202:205], v[78:81]
	v_mfma_f32_16x16x32_bf16 v[106:109], v[166:169], v[210:213], v[106:109]
	v_mfma_f32_16x16x32_bf16 v[74:77], v[186:189], v[210:213], v[74:77]
	v_mfma_f32_16x16x32_bf16 v[98:101], v[166:169], v[218:221], v[98:101]
	v_mfma_f32_16x16x32_bf16 v[66:69], v[186:189], v[218:221], v[66:69]
	s_barrier
	s_add_i32 s46, s71, s51
	s_mov_b32 m0, s46
	ds_read_b128 v[190:193], v184 offset:49152
	ds_read_b128 v[194:197], v184 offset:50176
	ds_read_b128 v[198:201], v184 offset:51200
	ds_read_b128 v[202:205], v184 offset:52224
	ds_read_b128 v[206:209], v184 offset:53248
	ds_read_b128 v[210:213], v184 offset:54272
	ds_read_b128 v[214:217], v184 offset:55296
	ds_read_b128 v[218:221], v184 offset:56320
	global_load_lds_dwordx4 v140, s[98:99]
	s_add_i32 m0, s46, 0x2000
	s_add_u32 s44, s44, 0x40080
	s_addc_u32 s45, s45, 0
	s_add_i32 s46, s72, s51
	global_load_lds_dwordx4 v144, s[98:99]
	s_mov_b32 m0, s46
	s_nop 0
	global_load_lds_dwordx4 v140, s[44:45]
	s_add_i32 m0, s46, 0x2000
	s_nop 0
	global_load_lds_dwordx4 v144, s[44:45]
	s_mov_b32 m0, s59
	s_nop 0
	global_load_lds_dwordx4 v138, s[100:101]
	v_lshl_add_u64 v[174:175], v[226:227], 0, s[24:25]
	s_mov_b32 m0, s60
	s_nop 0
	global_load_lds_dwordx4 v142, s[100:101]
	s_waitcnt vmcnt(8)
	s_waitcnt lgkmcnt(0)
	s_barrier
	v_mfma_f32_16x16x32_bf16 v[62:65], v[130:133], v[190:193], v[62:65]
	v_mfma_f32_16x16x32_bf16 v[30:33], v[154:157], v[190:193], v[30:33]
	v_mfma_f32_16x16x32_bf16 v[54:57], v[130:133], v[198:201], v[54:57]
	v_mfma_f32_16x16x32_bf16 v[22:25], v[154:157], v[198:201], v[22:25]
	v_mfma_f32_16x16x32_bf16 v[50:53], v[130:133], v[206:209], v[50:53]
	v_mfma_f32_16x16x32_bf16 v[18:21], v[154:157], v[206:209], v[18:21]
	v_mfma_f32_16x16x32_bf16 v[38:41], v[130:133], v[214:217], v[38:41]
	v_mfma_f32_16x16x32_bf16 v[6:9], v[154:157], v[214:217], v[6:9]
	v_mfma_f32_16x16x32_bf16 v[62:65], v[134:137], v[194:197], v[62:65]
	v_mfma_f32_16x16x32_bf16 v[30:33], v[158:161], v[194:197], v[30:33]
	v_mfma_f32_16x16x32_bf16 v[54:57], v[134:137], v[202:205], v[54:57]
	v_mfma_f32_16x16x32_bf16 v[22:25], v[158:161], v[202:205], v[22:25]
	v_mfma_f32_16x16x32_bf16 v[50:53], v[134:137], v[210:213], v[50:53]
	v_mfma_f32_16x16x32_bf16 v[18:21], v[158:161], v[210:213], v[18:21]
	v_mfma_f32_16x16x32_bf16 v[38:41], v[134:137], v[218:221], v[38:41]
	v_mfma_f32_16x16x32_bf16 v[6:9], v[158:161], v[218:221], v[6:9]
	v_mfma_f32_16x16x32_bf16 v[58:61], v[162:165], v[190:193], v[58:61]
	v_mfma_f32_16x16x32_bf16 v[26:29], v[170:173], v[190:193], v[26:29]
	v_mfma_f32_16x16x32_bf16 v[46:49], v[162:165], v[198:201], v[46:49]
	v_mfma_f32_16x16x32_bf16 v[14:17], v[170:173], v[198:201], v[14:17]
	v_mfma_f32_16x16x32_bf16 v[42:45], v[162:165], v[206:209], v[42:45]
	v_mfma_f32_16x16x32_bf16 v[10:13], v[170:173], v[206:209], v[10:13]
	v_mfma_f32_16x16x32_bf16 v[34:37], v[162:165], v[214:217], v[34:37]
	v_mfma_f32_16x16x32_bf16 v[2:5], v[170:173], v[214:217], v[2:5]
	v_mfma_f32_16x16x32_bf16 v[58:61], v[166:169], v[194:197], v[58:61]
	v_mfma_f32_16x16x32_bf16 v[26:29], v[186:189], v[194:197], v[26:29]
	v_mfma_f32_16x16x32_bf16 v[46:49], v[166:169], v[202:205], v[46:49]
	v_mfma_f32_16x16x32_bf16 v[14:17], v[186:189], v[202:205], v[14:17]
	v_mfma_f32_16x16x32_bf16 v[42:45], v[166:169], v[210:213], v[42:45]
	v_mfma_f32_16x16x32_bf16 v[10:13], v[186:189], v[210:213], v[10:13]
	v_mfma_f32_16x16x32_bf16 v[34:37], v[166:169], v[218:221], v[34:37]
	v_mfma_f32_16x16x32_bf16 v[2:5], v[186:189], v[218:221], v[2:5]
	s_barrier
	s_add_i32 s70, s70, 2
	s_add_u32 s42, s42, 0x100
	s_addc_u32 s43, s43, 0
	s_add_u32 s68, s68, 0x100
	s_addc_u32 s69, s69, 0
	s_cmp_gt_u32 s70, 13
	s_cbranch_scc0 .LBB0_2613
	s_and_b64 vcc, exec, s[26:27]
	s_cbranch_vccz .LBB0_2616
	s_barrier

; #define PG8_STAGE(bufoff, gbase, voff) do { _Pragma("unroll") for (int _i = 0; _i < 2; ++_i) \
;         __builtin_amdgcn_global_load_lds((const unsigned*)((const char*)(gbase) + (voff)[_i]), (PG8_LAS unsigned*)(lds + (bufoff) + ldsw + _i * 8192), 16, 0, 0); } while (0)
; #define PG8_LDA(dst, b, h) do { _Pragma("unroll") for (int m = 0; m < 4; ++m) _Pragma("unroll") for (int k = 0; k < 2; ++k) dst[m][k] = *(const PG8_LAS bf16x8*)(lds + PG8_SA(b, h) + aoff + m * 2048 + k * 1024); } while (0)
; #define PG8_LDB(dst, b, h) do { _Pragma("unroll") for (int n = 0; n < 2; ++n) _Pragma("unroll") for (int k = 0; k < 2; ++k) dst[n][k] = *(const PG8_LAS bf16x8*)(lds + PG8_SB(b, h) + boff + n * 2048 + k * 1024); } while (0)
; #define PG8_MMA(ai, bj, At, Bt) do { __builtin_amdgcn_s_setprio(1); _Pragma("unroll") for (int m = 0; m < 4; ++m) _Pragma("unroll") for (int n = 0; n < 2; ++n) _Pragma("unroll") for (int k = 0; k < 2; ++k) \
;         acc[ai][bj][m][n] = __builtin_amdgcn_mfma_f32_16x16x32_bf16(Bt[n][k], At[m][k], acc[ai][bj][m][n], 0, 0, 0); __builtin_amdgcn_s_setprio(0); } while (0)
; #define PG8_WAIT_V(n) asm volatile("s_waitcnt vmcnt(" #n ")" ::: "memory")
; #define PG8_WAIT_L(n) asm volatile("s_waitcnt lgkmcnt(" #n ")" ::: "memory")
; #define PG8_BAR __builtin_amdgcn_s_barrier()
; #define PG8_SCHED __builtin_amdgcn_sched_barrier(0)
; template <class Epi, class Sched, bool ALIGN_EPI = false, bool SP2 = false>
; __device__ __forceinline__ void gemm_phase(PG8_LAS unsigned char* lds, const Gemm g, const Sched& S, const Epi& E) {
;     ...
;             PG8_LDB(B0, 0, 0); PG8_LDB(B1, 0, 1); PG8_SCHED; PG8_LDA(At, 0, 0); PG8_STAGE(PG8_SA(1, 1), a1 + hstepA, voffA);
;             PG8_WAIT_V(8); PG8_WAIT_L(0); PG8_BAR; PG8_MMA(0, 0, At, B0); PG8_MMA(0, 1, At, B1); PG8_BAR; PG8_SCHED;
;             PG8_LDA(At, 0, 1); PG8_STAGE(PG8_SB(0, 0), b2, voffB); PG8_STAGE(PG8_SB(0, 1), b2 + hstepB, voffB); PG8_STAGE(PG8_SA(0, 0), a2, voffA);
;             PG8_WAIT_V(8); PG8_WAIT_L(0); PG8_BAR; PG8_MMA(1, 0, At, B0); PG8_MMA(1, 1, At, B1); PG8_BAR; PG8_SCHED;
.LBB0_2807:
	v_add_u32_e32 v68, s49, v58
	ds_read_b128 v[60:63], v68
	ds_read_b128 v[64:67], v68 offset:1024
	ds_read_b128 v[162:165], v68 offset:2048
	ds_read_b128 v[166:169], v68 offset:3072
	v_add_u32_e32 v68, s50, v58
	s_add_u32 s22, s14, s20
	ds_read_b128 v[170:173], v68
	ds_read_b128 v[174:177], v68 offset:1024
	ds_read_b128 v[178:181], v68 offset:2048
	ds_read_b128 v[184:187], v68 offset:3072
	s_addc_u32 s23, s15, s21
	s_add_u32 s22, s22, 0x100
	s_addc_u32 s23, s23, 0
	s_add_u32 s57, s54, s20
	s_addc_u32 s58, s55, s21
	s_cmpk_eq_i32 s20, 0x1500
	s_cselect_b32 s25, s19, s23
	s_cselect_b32 s24, s18, s22
	s_cselect_b32 s23, s1, s58
	s_cselect_b32 s22, s0, s57
	v_lshl_add_u64 v[68:69], v[54:55], 0, s[20:21]
	s_add_i32 m0, s41, 0xc000
	ds_read_b128 v[188:191], v59
	ds_read_b128 v[192:195], v59 offset:1024
	ds_read_b128 v[196:199], v59 offset:2048
	ds_read_b128 v[200:203], v59 offset:3072
	ds_read_b128 v[204:207], v59 offset:4096
	ds_read_b128 v[208:211], v59 offset:5120
	ds_read_b128 v[212:215], v59 offset:6144
	ds_read_b128 v[216:219], v59 offset:7168
	global_load_lds_dwordx4 v[68:69], off
	v_lshl_add_u64 v[68:69], v[56:57], 0, s[20:21]
	s_add_i32 m0, s41, 0xe000
	s_nop 0
	global_load_lds_dwordx4 v[68:69], off
	s_waitcnt vmcnt(8)
	s_waitcnt lgkmcnt(0)
	s_barrier
	v_mfma_f32_16x16x32_bf16 v[158:161], v[60:63], v[188:191], v[158:161]
	v_mfma_f32_16x16x32_bf16 v[146:149], v[162:165], v[188:191], v[146:149]
	v_mfma_f32_16x16x32_bf16 v[150:153], v[60:63], v[196:199], v[150:153]
	v_mfma_f32_16x16x32_bf16 v[154:157], v[162:165], v[196:199], v[154:157]
	v_mfma_f32_16x16x32_bf16 v[142:145], v[60:63], v[204:207], v[142:145]
	v_mfma_f32_16x16x32_bf16 v[138:141], v[162:165], v[204:207], v[138:141]
	v_mfma_f32_16x16x32_bf16 v[134:137], v[60:63], v[212:215], v[134:137]
	v_mfma_f32_16x16x32_bf16 v[130:133], v[162:165], v[212:215], v[130:133]
	v_mfma_f32_16x16x32_bf16 v[158:161], v[64:67], v[192:195], v[158:161]
	v_mfma_f32_16x16x32_bf16 v[146:149], v[166:169], v[192:195], v[146:149]
	v_mfma_f32_16x16x32_bf16 v[150:153], v[64:67], v[200:203], v[150:153]
	v_mfma_f32_16x16x32_bf16 v[154:157], v[166:169], v[200:203], v[154:157]
	v_mfma_f32_16x16x32_bf16 v[142:145], v[64:67], v[208:211], v[142:145]
	v_mfma_f32_16x16x32_bf16 v[138:141], v[166:169], v[208:211], v[138:141]
	v_mfma_f32_16x16x32_bf16 v[134:137], v[64:67], v[216:219], v[134:137]
	v_mfma_f32_16x16x32_bf16 v[130:133], v[166:169], v[216:219], v[130:133]
	v_mfma_f32_16x16x32_bf16 v[78:81], v[170:173], v[188:191], v[78:81]
	v_mfma_f32_16x16x32_bf16 v[74:77], v[178:181], v[188:191], v[74:77]
	v_mfma_f32_16x16x32_bf16 v[86:89], v[170:173], v[196:199], v[86:89]
	v_mfma_f32_16x16x32_bf16 v[90:93], v[178:181], v[196:199], v[90:93]
	v_mfma_f32_16x16x32_bf16 v[118:121], v[170:173], v[204:207], v[118:121]
	v_mfma_f32_16x16x32_bf16 v[114:117], v[178:181], v[204:207], v[114:117]
	v_mfma_f32_16x16x32_bf16 v[122:125], v[170:173], v[212:215], v[122:125]
	v_mfma_f32_16x16x32_bf16 v[126:129], v[178:181], v[212:215], v[126:129]
	v_mfma_f32_16x16x32_bf16 v[78:81], v[174:177], v[192:195], v[78:81]
	v_mfma_f32_16x16x32_bf16 v[74:77], v[184:187], v[192:195], v[74:77]
	v_mfma_f32_16x16x32_bf16 v[86:89], v[174:177], v[200:203], v[86:89]
	v_mfma_f32_16x16x32_bf16 v[90:93], v[184:187], v[200:203], v[90:93]
	v_mfma_f32_16x16x32_bf16 v[118:121], v[174:177], v[208:211], v[118:121]
	v_mfma_f32_16x16x32_bf16 v[114:117], v[184:187], v[208:211], v[114:117]
	v_mfma_f32_16x16x32_bf16 v[122:125], v[174:177], v[216:219], v[122:125]
	v_mfma_f32_16x16x32_bf16 v[126:129], v[184:187], v[216:219], v[126:129]
	s_barrier
	s_add_i32 s57, s49, s40
	s_add_u32 s98, s22, 0x80
	s_addc_u32 s99, s23, 0
	s_mov_b32 m0, s57
	ds_read_b128 v[188:191], v59 offset:16384
	ds_read_b128 v[192:195], v59 offset:17408
	ds_read_b128 v[196:199], v59 offset:18432
	ds_read_b128 v[200:203], v59 offset:19456
	ds_read_b128 v[204:207], v59 offset:20480
	ds_read_b128 v[208:211], v59 offset:21504
	ds_read_b128 v[212:215], v59 offset:22528
	ds_read_b128 v[216:219], v59 offset:23552
	global_load_lds_dwordx4 v8, s[22:23]
	s_add_i32 m0, s57, 0x2000
	s_add_u32 s58, s22, 0xb0000
	s_addc_u32 s59, s23, 0
	s_add_i32 s57, s50, s40
	global_load_lds_dwordx4 v12, s[22:23]
	s_mov_b32 m0, s57
	s_add_u32 s100, s24, 0x80
	s_addc_u32 s101, s25, 0
	global_load_lds_dwordx4 v8, s[58:59]
	s_add_i32 m0, s57, 0x2000
	s_nop 0
	global_load_lds_dwordx4 v12, s[58:59]
	s_mov_b32 m0, s41
	s_nop 0
	global_load_lds_dwordx4 v6, s[24:25]
	s_mov_b32 m0, s42
	s_nop 0
	global_load_lds_dwordx4 v10, s[24:25]
	s_waitcnt vmcnt(8)
	s_waitcnt lgkmcnt(0)
	s_barrier
; #define PG8_STAGE(bufoff, gbase, voff) do { _Pragma("unroll") for (int _i = 0; _i < 2; ++_i) \
;         __builtin_amdgcn_global_load_lds((const unsigned*)((const char*)(gbase) + (voff)[_i]), (PG8_LAS unsigned*)(lds + (bufoff) + ldsw + _i * 8192), 16, 0, 0); } while (0)
; #define PG8_LDA(dst, b, h) do { _Pragma("unroll") for (int m = 0; m < 4; ++m) _Pragma("unroll") for (int k = 0; k < 2; ++k) dst[m][k] = *(const PG8_LAS bf16x8*)(lds + PG8_SA(b, h) + aoff + m * 2048 + k * 1024); } while (0)
; #define PG8_LDB(dst, b, h) do { _Pragma("unroll") for (int n = 0; n < 2; ++n) _Pragma("unroll") for (int k = 0; k < 2; ++k) dst[n][k] = *(const PG8_LAS bf16x8*)(lds + PG8_SB(b, h) + boff + n * 2048 + k * 1024); } while (0)
; #define PG8_MMA(ai, bj, At, Bt) do { __builtin_amdgcn_s_setprio(1); _Pragma("unroll") for (int m = 0; m < 4; ++m) _Pragma("unroll") for (int n = 0; n < 2; ++n) _Pragma("unroll") for (int k = 0; k < 2; ++k) \
;         acc[ai][bj][m][n] = __builtin_amdgcn_mfma_f32_16x16x32_bf16(Bt[n][k], At[m][k], acc[ai][bj][m][n], 0, 0, 0); __builtin_amdgcn_s_setprio(0); } while (0)
; #define PG8_WAIT_V(n) asm volatile("s_waitcnt vmcnt(" #n ")" ::: "memory")
; #define PG8_WAIT_L(n) asm volatile("s_waitcnt lgkmcnt(" #n ")" ::: "memory")
; #define PG8_BAR __builtin_amdgcn_s_barrier()
; #define PG8_SCHED __builtin_amdgcn_sched_barrier(0)
; template <class Epi, class Sched, bool ALIGN_EPI = false, bool SP2 = false>
; __device__ __forceinline__ void gemm_phase(PG8_LAS unsigned char* lds, const Gemm g, const Sched& S, const Epi& E) {
;     ...
;             PG8_WAIT_V(8); PG8_WAIT_L(0); PG8_BAR; PG8_MMA(1, 0, At, B0); PG8_MMA(1, 1, At, B1); PG8_BAR; PG8_SCHED;
;             PG8_LDB(B0, 1, 0); PG8_LDB(B1, 1, 1); PG8_SCHED; PG8_LDA(At, 1, 0); PG8_STAGE(PG8_SA(0, 1), a2 + hstepA, voffA);
;             PG8_WAIT_V(8); PG8_WAIT_L(0); PG8_BAR; PG8_MMA(0, 0, At, B0); PG8_MMA(0, 1, At, B1); PG8_BAR; PG8_SCHED;
	v_mfma_f32_16x16x32_bf16 v[110:113], v[60:63], v[188:191], v[110:113]
	v_mfma_f32_16x16x32_bf16 v[106:109], v[162:165], v[188:191], v[106:109]
	v_mfma_f32_16x16x32_bf16 v[102:105], v[60:63], v[196:199], v[102:105]
	v_mfma_f32_16x16x32_bf16 v[98:101], v[162:165], v[196:199], v[98:101]
	v_mfma_f32_16x16x32_bf16 v[46:49], v[60:63], v[204:207], v[46:49]
	v_mfma_f32_16x16x32_bf16 v[42:45], v[162:165], v[204:207], v[42:45]
	v_mfma_f32_16x16x32_bf16 v[38:41], v[60:63], v[212:215], v[38:41]
	v_mfma_f32_16x16x32_bf16 v[34:37], v[162:165], v[212:215], v[34:37]
	v_mfma_f32_16x16x32_bf16 v[110:113], v[64:67], v[192:195], v[110:113]
	v_mfma_f32_16x16x32_bf16 v[106:109], v[166:169], v[192:195], v[106:109]
	v_mfma_f32_16x16x32_bf16 v[102:105], v[64:67], v[200:203], v[102:105]
	v_mfma_f32_16x16x32_bf16 v[98:101], v[166:169], v[200:203], v[98:101]
	v_mfma_f32_16x16x32_bf16 v[46:49], v[64:67], v[208:211], v[46:49]
	v_mfma_f32_16x16x32_bf16 v[42:45], v[166:169], v[208:211], v[42:45]
	v_mfma_f32_16x16x32_bf16 v[38:41], v[64:67], v[216:219], v[38:41]
	v_mfma_f32_16x16x32_bf16 v[34:37], v[166:169], v[216:219], v[34:37]
	v_mfma_f32_16x16x32_bf16 v[68:71], v[170:173], v[196:199], v[70:73]
	v_mfma_f32_16x16x32_bf16 v[50:53], v[178:181], v[196:199], v[50:53]
	v_mfma_f32_16x16x32_bf16 v[30:33], v[170:173], v[204:207], v[30:33]
	v_mfma_f32_16x16x32_bf16 v[26:29], v[178:181], v[204:207], v[26:29]
	v_mfma_f32_16x16x32_bf16 v[22:25], v[170:173], v[212:215], v[22:25]
	v_mfma_f32_16x16x32_bf16 v[2:5], v[178:181], v[212:215], v[2:5]
	v_mfma_f32_16x16x32_bf16 v[60:63], v[170:173], v[188:191], v[94:97]
	v_mfma_f32_16x16x32_bf16 v[64:67], v[178:181], v[188:191], v[82:85]
	v_mfma_f32_16x16x32_bf16 v[68:71], v[174:177], v[200:203], v[68:71]
	v_mfma_f32_16x16x32_bf16 v[50:53], v[184:187], v[200:203], v[50:53]
	v_mfma_f32_16x16x32_bf16 v[30:33], v[174:177], v[208:211], v[30:33]
	v_mfma_f32_16x16x32_bf16 v[26:29], v[184:187], v[208:211], v[26:29]
	v_mfma_f32_16x16x32_bf16 v[22:25], v[174:177], v[216:219], v[22:25]
	v_mfma_f32_16x16x32_bf16 v[2:5], v[184:187], v[216:219], v[2:5]
	v_mfma_f32_16x16x32_bf16 v[60:63], v[174:177], v[192:195], v[60:63]
	v_mfma_f32_16x16x32_bf16 v[64:67], v[184:187], v[192:195], v[64:67]
	s_barrier
	s_add_i32 s57, 0, 0x18000
	v_add_u32_e32 v72, s57, v58
	s_add_i32 s58, 0, 0x1c000
	ds_read_b128 v[82:85], v72
	ds_read_b128 v[94:97], v72 offset:1024
	ds_read_b128 v[162:165], v72 offset:2048
	ds_read_b128 v[166:169], v72 offset:3072
	v_add_u32_e32 v72, s58, v58
	ds_read_b128 v[170:173], v72
	ds_read_b128 v[174:177], v72 offset:1024
	ds_read_b128 v[178:181], v72 offset:2048
	ds_read_b128 v[184:187], v72 offset:3072
	s_add_u32 s24, s24, 0xb0000
	s_addc_u32 s25, s25, 0
	s_mov_b32 m0, s44
	ds_read_b128 v[188:191], v59 offset:32768
	ds_read_b128 v[192:195], v59 offset:33792
	ds_read_b128 v[196:199], v59 offset:34816
	ds_read_b128 v[200:203], v59 offset:35840
	ds_read_b128 v[204:207], v59 offset:36864
	ds_read_b128 v[208:211], v59 offset:37888
	ds_read_b128 v[212:215], v59 offset:38912
	ds_read_b128 v[216:219], v59 offset:39936
	global_load_lds_dwordx4 v6, s[24:25]
	s_mov_b32 m0, s45
	s_nop 0
	global_load_lds_dwordx4 v10, s[24:25]
	s_waitcnt vmcnt(8)
	s_waitcnt lgkmcnt(0)
	s_barrier
	v_mfma_f32_16x16x32_bf16 v[158:161], v[82:85], v[188:191], v[158:161]
	v_mfma_f32_16x16x32_bf16 v[146:149], v[162:165], v[188:191], v[146:149]
	v_mfma_f32_16x16x32_bf16 v[150:153], v[82:85], v[196:199], v[150:153]
	v_mfma_f32_16x16x32_bf16 v[154:157], v[162:165], v[196:199], v[154:157]
	v_mfma_f32_16x16x32_bf16 v[142:145], v[82:85], v[204:207], v[142:145]
	v_mfma_f32_16x16x32_bf16 v[138:141], v[162:165], v[204:207], v[138:141]
	v_mfma_f32_16x16x32_bf16 v[134:137], v[82:85], v[212:215], v[134:137]
	v_mfma_f32_16x16x32_bf16 v[130:133], v[162:165], v[212:215], v[130:133]
	v_mfma_f32_16x16x32_bf16 v[158:161], v[94:97], v[192:195], v[158:161]
	v_mfma_f32_16x16x32_bf16 v[146:149], v[166:169], v[192:195], v[146:149]
	v_mfma_f32_16x16x32_bf16 v[150:153], v[94:97], v[200:203], v[150:153]
	v_mfma_f32_16x16x32_bf16 v[154:157], v[166:169], v[200:203], v[154:157]
	v_mfma_f32_16x16x32_bf16 v[142:145], v[94:97], v[208:211], v[142:145]
	v_mfma_f32_16x16x32_bf16 v[138:141], v[166:169], v[208:211], v[138:141]
	v_mfma_f32_16x16x32_bf16 v[134:137], v[94:97], v[216:219], v[134:137]
	v_mfma_f32_16x16x32_bf16 v[130:133], v[166:169], v[216:219], v[130:133]
	v_mfma_f32_16x16x32_bf16 v[78:81], v[170:173], v[188:191], v[78:81]
	v_mfma_f32_16x16x32_bf16 v[72:75], v[178:181], v[188:191], v[74:77]
	v_mfma_f32_16x16x32_bf16 v[86:89], v[170:173], v[196:199], v[86:89]
	v_mfma_f32_16x16x32_bf16 v[90:93], v[178:181], v[196:199], v[90:93]
	v_mfma_f32_16x16x32_bf16 v[118:121], v[170:173], v[204:207], v[118:121]
	v_mfma_f32_16x16x32_bf16 v[114:117], v[178:181], v[204:207], v[114:117]
	v_mfma_f32_16x16x32_bf16 v[122:125], v[170:173], v[212:215], v[122:125]
	v_mfma_f32_16x16x32_bf16 v[126:129], v[178:181], v[212:215], v[126:129]
	v_mfma_f32_16x16x32_bf16 v[78:81], v[174:177], v[192:195], v[78:81]
	v_mfma_f32_16x16x32_bf16 v[74:77], v[184:187], v[192:195], v[72:75]
	v_mfma_f32_16x16x32_bf16 v[86:89], v[174:177], v[200:203], v[86:89]
	v_mfma_f32_16x16x32_bf16 v[90:93], v[184:187], v[200:203], v[90:93]
	v_mfma_f32_16x16x32_bf16 v[118:121], v[174:177], v[208:211], v[118:121]
	v_mfma_f32_16x16x32_bf16 v[114:117], v[184:187], v[208:211], v[114:117]
	v_mfma_f32_16x16x32_bf16 v[122:125], v[174:177], v[216:219], v[122:125]
	v_mfma_f32_16x16x32_bf16 v[126:129], v[184:187], v[216:219], v[126:129]
	s_barrier
; #define PG8_STAGE(bufoff, gbase, voff) do { _Pragma("unroll") for (int _i = 0; _i < 2; ++_i) \
;         __builtin_amdgcn_global_load_lds((const unsigned*)((const char*)(gbase) + (voff)[_i]), (PG8_LAS unsigned*)(lds + (bufoff) + ldsw + _i * 8192), 16, 0, 0); } while (0)
; #define PG8_LDA(dst, b, h) do { _Pragma("unroll") for (int m = 0; m < 4; ++m) _Pragma("unroll") for (int k = 0; k < 2; ++k) dst[m][k] = *(const PG8_LAS bf16x8*)(lds + PG8_SA(b, h) + aoff + m * 2048 + k * 1024); } while (0)
; #define PG8_MMA(ai, bj, At, Bt) do { __builtin_amdgcn_s_setprio(1); _Pragma("unroll") for (int m = 0; m < 4; ++m) _Pragma("unroll") for (int n = 0; n < 2; ++n) _Pragma("unroll") for (int k = 0; k < 2; ++k) \
;         acc[ai][bj][m][n] = __builtin_amdgcn_mfma_f32_16x16x32_bf16(Bt[n][k], At[m][k], acc[ai][bj][m][n], 0, 0, 0); __builtin_amdgcn_s_setprio(0); } while (0)
; #define PG8_WAIT_V(n) asm volatile("s_waitcnt vmcnt(" #n ")" ::: "memory")
; #define PG8_WAIT_L(n) asm volatile("s_waitcnt lgkmcnt(" #n ")" ::: "memory")
; #define PG8_BAR __builtin_amdgcn_s_barrier()
; #define PG8_SCHED __builtin_amdgcn_sched_barrier(0)
; template <class Epi, class Sched, bool ALIGN_EPI = false, bool SP2 = false>
; __device__ __forceinline__ void gemm_phase(PG8_LAS unsigned char* lds, const Gemm g, const Sched& S, const Epi& E) {
;     ...
;             PG8_LDA(At, 1, 1); PG8_STAGE(PG8_SB(1, 0), b3, voffB); PG8_STAGE(PG8_SB(1, 1), b3 + hstepB, voffB); PG8_STAGE(PG8_SA(1, 0), a3, voffA);
;             PG8_WAIT_V(8); PG8_WAIT_L(0); PG8_BAR; PG8_MMA(1, 0, At, B0); PG8_MMA(1, 1, At, B1); PG8_BAR; PG8_SCHED;
;     ...
; #pragma unroll
;         for (int a = 0; a < 2; ++a)
; #pragma unroll
;             for (int b = 0; b < 2; ++b)
; #pragma unroll
;                 for (int m = 0; m < 4; ++m)
; #pragma unroll
;                     for (int n = 0; n < 2; ++n) acc[a][b][m][n] = (f32x4){0.f, 0.f, 0.f, 0.f};
	s_add_i32 s24, s57, s40
	s_mov_b32 m0, s24
	ds_read_b128 v[188:191], v59 offset:49152
	ds_read_b128 v[192:195], v59 offset:50176
	ds_read_b128 v[196:199], v59 offset:51200
	ds_read_b128 v[200:203], v59 offset:52224
	ds_read_b128 v[204:207], v59 offset:53248
	ds_read_b128 v[208:211], v59 offset:54272
	ds_read_b128 v[212:215], v59 offset:55296
	ds_read_b128 v[216:219], v59 offset:56320
	global_load_lds_dwordx4 v8, s[98:99]
	s_add_i32 m0, s24, 0x2000
	s_add_u32 s22, s22, 0xb0080
	s_addc_u32 s23, s23, 0
	s_add_i32 s24, s58, s40
	global_load_lds_dwordx4 v12, s[98:99]
	s_mov_b32 m0, s24
	s_nop 0
	global_load_lds_dwordx4 v8, s[22:23]
	s_add_i32 m0, s24, 0x2000
	s_nop 0
	global_load_lds_dwordx4 v12, s[22:23]
	s_mov_b32 m0, s47
	s_nop 0
	global_load_lds_dwordx4 v6, s[100:101]
	s_mov_b32 m0, s48
	s_nop 0
	global_load_lds_dwordx4 v10, s[100:101]
	s_waitcnt vmcnt(8)
	s_waitcnt lgkmcnt(0)
	s_barrier
	v_mfma_f32_16x16x32_bf16 v[110:113], v[82:85], v[188:191], v[110:113]
	v_mfma_f32_16x16x32_bf16 v[106:109], v[162:165], v[188:191], v[106:109]
	v_mfma_f32_16x16x32_bf16 v[102:105], v[82:85], v[196:199], v[102:105]
	v_mfma_f32_16x16x32_bf16 v[98:101], v[162:165], v[196:199], v[98:101]
	v_mfma_f32_16x16x32_bf16 v[46:49], v[82:85], v[204:207], v[46:49]
	v_mfma_f32_16x16x32_bf16 v[42:45], v[162:165], v[204:207], v[42:45]
	v_mfma_f32_16x16x32_bf16 v[38:41], v[82:85], v[212:215], v[38:41]
	v_mfma_f32_16x16x32_bf16 v[34:37], v[162:165], v[212:215], v[34:37]
	v_mfma_f32_16x16x32_bf16 v[110:113], v[94:97], v[192:195], v[110:113]
	v_mfma_f32_16x16x32_bf16 v[106:109], v[166:169], v[192:195], v[106:109]
	v_mfma_f32_16x16x32_bf16 v[102:105], v[94:97], v[200:203], v[102:105]
	v_mfma_f32_16x16x32_bf16 v[98:101], v[166:169], v[200:203], v[98:101]
	v_mfma_f32_16x16x32_bf16 v[46:49], v[94:97], v[208:211], v[46:49]
	v_mfma_f32_16x16x32_bf16 v[42:45], v[166:169], v[208:211], v[42:45]
	v_mfma_f32_16x16x32_bf16 v[38:41], v[94:97], v[216:219], v[38:41]
	v_mfma_f32_16x16x32_bf16 v[34:37], v[166:169], v[216:219], v[34:37]
	v_mfma_f32_16x16x32_bf16 v[60:63], v[170:173], v[188:191], v[60:63]
	v_mfma_f32_16x16x32_bf16 v[94:97], v[174:177], v[192:195], v[60:63]
	v_mfma_f32_16x16x32_bf16 v[60:63], v[178:181], v[188:191], v[64:67]
	v_mfma_f32_16x16x32_bf16 v[82:85], v[184:187], v[192:195], v[60:63]
	v_mfma_f32_16x16x32_bf16 v[60:63], v[170:173], v[196:199], v[68:71]
	v_mfma_f32_16x16x32_bf16 v[50:53], v[178:181], v[196:199], v[50:53]
	v_mfma_f32_16x16x32_bf16 v[30:33], v[170:173], v[204:207], v[30:33]
	v_mfma_f32_16x16x32_bf16 v[26:29], v[178:181], v[204:207], v[26:29]
	v_mfma_f32_16x16x32_bf16 v[22:25], v[170:173], v[212:215], v[22:25]
	v_mfma_f32_16x16x32_bf16 v[2:5], v[178:181], v[212:215], v[2:5]
	v_mfma_f32_16x16x32_bf16 v[70:73], v[174:177], v[200:203], v[60:63]
	v_mfma_f32_16x16x32_bf16 v[50:53], v[184:187], v[200:203], v[50:53]
	v_mfma_f32_16x16x32_bf16 v[30:33], v[174:177], v[208:211], v[30:33]
	v_mfma_f32_16x16x32_bf16 v[26:29], v[184:187], v[208:211], v[26:29]
	v_mfma_f32_16x16x32_bf16 v[22:25], v[174:177], v[216:219], v[22:25]
	v_mfma_f32_16x16x32_bf16 v[2:5], v[184:187], v[216:219], v[2:5]
	s_barrier
	s_add_i32 s56, s56, 2
	s_add_u32 s20, s20, 0x100
	s_addc_u32 s21, s21, 0
	s_cmp_gt_u32 s56, 41
	s_cbranch_scc0 .LBB0_2807
	s_add_u32 s20, s54, 0xffffff00
	s_addc_u32 s21, s55, -1
	s_and_b64 vcc, exec, s[4:5]
	s_cbranch_vccnz .LBB0_2794
	v_mov_b32_e32 v2, 0
	s_mov_b32 s12, s51
	s_mov_b32 s27, s52
	s_mov_b64 s[14:15], s[18:19]
	s_mov_b32 s46, s53
	v_mov_b32_e32 v3, v2
	v_mov_b32_e32 v4, v2
	v_mov_b32_e32 v5, v2
	v_mov_b32_e32 v22, v2
	v_mov_b32_e32 v23, v2
	v_mov_b32_e32 v24, v2
	v_mov_b32_e32 v25, v2
	v_mov_b32_e32 v26, v2
	v_mov_b32_e32 v27, v2
	v_mov_b32_e32 v28, v2
	v_mov_b32_e32 v29, v2
	v_mov_b32_e32 v30, v2
	v_mov_b32_e32 v31, v2
	v_mov_b32_e32 v32, v2
	v_mov_b32_e32 v33, v2
	v_mov_b32_e32 v50, v2
	v_mov_b32_e32 v51, v2
	v_mov_b32_e32 v52, v2
	v_mov_b32_e32 v53, v2
	v_mov_b32_e32 v70, v2
	v_mov_b32_e32 v71, v2
	v_mov_b32_e32 v72, v2
	v_mov_b32_e32 v73, v2
	v_mov_b32_e32 v82, v2
	v_mov_b32_e32 v83, v2
	v_mov_b32_e32 v84, v2
	v_mov_b32_e32 v85, v2
	v_mov_b32_e32 v94, v2
	v_mov_b32_e32 v95, v2
	v_mov_b32_e32 v96, v2
	v_mov_b32_e32 v97, v2
	v_mov_b32_e32 v34, v2
	v_mov_b32_e32 v35, v2
	v_mov_b32_e32 v36, v2
	v_mov_b32_e32 v37, v2
	v_mov_b32_e32 v38, v2
	v_mov_b32_e32 v39, v2
	v_mov_b32_e32 v40, v2
	v_mov_b32_e32 v41, v2
	v_mov_b32_e32 v42, v2
	v_mov_b32_e32 v43, v2
	v_mov_b32_e32 v44, v2
	v_mov_b32_e32 v45, v2
	v_mov_b32_e32 v46, v2
	v_mov_b32_e32 v47, v2
	v_mov_b32_e32 v48, v2
	v_mov_b32_e32 v49, v2
	v_mov_b32_e32 v98, v2
	v_mov_b32_e32 v99, v2
	v_mov_b32_e32 v100, v2
	v_mov_b32_e32 v101, v2
	v_mov_b32_e32 v102, v2
	v_mov_b32_e32 v103, v2
	v_mov_b32_e32 v104, v2
	v_mov_b32_e32 v105, v2
	v_mov_b32_e32 v106, v2
	v_mov_b32_e32 v107, v2
	v_mov_b32_e32 v108, v2
	v_mov_b32_e32 v109, v2
	v_mov_b32_e32 v110, v2
	v_mov_b32_e32 v111, v2
	v_mov_b32_e32 v112, v2
	v_mov_b32_e32 v113, v2
	v_mov_b32_e32 v126, v2
	v_mov_b32_e32 v127, v2
	v_mov_b32_e32 v128, v2
	v_mov_b32_e32 v129, v2
	v_mov_b32_e32 v122, v2
	v_mov_b32_e32 v123, v2
	v_mov_b32_e32 v124, v2
	v_mov_b32_e32 v125, v2
	v_mov_b32_e32 v114, v2
	v_mov_b32_e32 v115, v2
	v_mov_b32_e32 v116, v2
	v_mov_b32_e32 v117, v2
	v_mov_b32_e32 v118, v2
	v_mov_b32_e32 v119, v2
	v_mov_b32_e32 v120, v2
	v_mov_b32_e32 v121, v2
	v_mov_b32_e32 v90, v2
	v_mov_b32_e32 v91, v2
	v_mov_b32_e32 v92, v2
	v_mov_b32_e32 v93, v2
	v_mov_b32_e32 v86, v2
	v_mov_b32_e32 v87, v2
	v_mov_b32_e32 v88, v2
	v_mov_b32_e32 v89, v2
	v_mov_b32_e32 v74, v2
	v_mov_b32_e32 v75, v2
	v_mov_b32_e32 v76, v2
	v_mov_b32_e32 v77, v2
	v_mov_b32_e32 v78, v2
	v_mov_b32_e32 v79, v2
	v_mov_b32_e32 v80, v2
	v_mov_b32_e32 v81, v2
	v_mov_b32_e32 v130, v2
	v_mov_b32_e32 v131, v2
	v_mov_b32_e32 v132, v2
	v_mov_b32_e32 v133, v2
	v_mov_b32_e32 v134, v2
	v_mov_b32_e32 v135, v2
	v_mov_b32_e32 v136, v2
	v_mov_b32_e32 v137, v2
	v_mov_b32_e32 v138, v2
	v_mov_b32_e32 v139, v2
	v_mov_b32_e32 v140, v2
	v_mov_b32_e32 v141, v2
	v_mov_b32_e32 v142, v2
	v_mov_b32_e32 v143, v2
	v_mov_b32_e32 v144, v2
	v_mov_b32_e32 v145, v2
	v_mov_b32_e32 v154, v2
	v_mov_b32_e32 v155, v2
	v_mov_b32_e32 v156, v2
	v_mov_b32_e32 v157, v2
	v_mov_b32_e32 v150, v2
	v_mov_b32_e32 v151, v2
	v_mov_b32_e32 v152, v2
	v_mov_b32_e32 v153, v2
	v_mov_b32_e32 v146, v2
	v_mov_b32_e32 v147, v2
	v_mov_b32_e32 v148, v2
	v_mov_b32_e32 v149, v2
	v_mov_b32_e32 v158, v2
	v_mov_b32_e32 v159, v2
	v_mov_b32_e32 v160, v2
	v_mov_b32_e32 v161, v2
	s_andn2_b64 vcc, exec, s[2:3]
	s_cbranch_vccnz .LBB0_2795
